# hand-written FFN-in epilogue (conv3+gelu*val): weights kept in VGPRs, DPP halo moves instead of cndmask chains, no packed-f32 shuffles; skip final grid barrier
# speedup vs baseline: 1.0643x; 1.0353x over previous
.LBB0_993:
	v_mov_b32_e32 v134, v192
	v_mov_b32_e32 v135, v192
	s_lshl_b32 s6, s30, 7
	v_bfe_i32 v128, v135, 7, 1
	v_and_b32_e32 v128, 0xb00, v128
	v_add_u32_e32 v128, s6, v128
	s_movk_i32 s7, 0x7f
	v_and_or_b32 v128, v135, s7, v128
	v_ashrrev_i32_e32 v129, 31, v128
	v_lshl_add_u64 v[130:131], v[128:129], 2, s[20:21]
	v_ashrrev_i32_e32 v129, 8, v135
	v_mad_i32_i24 v132, v129, s79, v128
	v_ashrrev_i32_e32 v133, 31, v132
	v_lshl_add_u64 v[132:133], v[132:133], 2, s[18:19]
	v_cmp_gt_i32_e32 vcc, 3, v129
	v_add_u32_e32 v129, 0x200, v135
	v_lshl_add_u32 v135, v135, 2, 0
	v_cndmask_b32_e32 v133, v131, v133, vcc
	v_cndmask_b32_e32 v132, v130, v132, vcc
	global_load_dword v132, v[132:133], off
	v_ashrrev_i32_e32 v133, 8, v129
	v_mad_i32_i24 v128, v133, s79, v128
	v_ashrrev_i32_e32 v129, 31, v128
	v_lshl_add_u64 v[128:129], v[128:129], 2, s[18:19]
	v_cmp_gt_i32_e32 vcc, 3, v133
	s_mulk_i32 s0, 0xfc
	v_lshrrev_b32_e32 v136, 1, v134
	v_cndmask_b32_e32 v129, v131, v129, vcc
	v_cndmask_b32_e32 v128, v130, v128, vcc
	global_load_dword v133, v[128:129], off
	v_add_u32_e32 v135, 0x20000, v135
	s_add_i32 s0, s66, s0
	v_and_b32_e32 v219, 15, v134
	v_and_or_b32 v134, v136, 24, s62
	v_add_u32_e32 v218, s0, v219
	v_or_b32_e32 v136, 0x80, v134
	v_or_b32_e32 v137, 4, v134
	v_or_b32_e32 v138, 0x84, v134
	v_cmp_lt_u32_e32 vcc, 1, v219
	v_or_b32_e32 v188, s6, v134
	v_cmp_gt_i32_e64 s[6:7], s58, v218
	v_lshlrev_b32_e32 v172, 2, v134
	v_lshlrev_b32_e32 v210, 2, v137
	v_lshlrev_b32_e32 v206, 2, v136
	v_lshlrev_b32_e32 v212, 2, v138
	v_ashrrev_i32_e32 v189, 31, v188
	s_and_b64 s[6:7], vcc, s[6:7]
	s_waitcnt vmcnt(0)
	ds_write2st64_b32 v135, v132, v133 offset1:8
	s_waitcnt lgkmcnt(0)
	s_barrier
	v_add_u32_e32 v203, 0x20000, v172
	ds_read_b128 v[128:131], v203 offset:0
	ds_read_b128 v[132:135], v203 offset:512
	ds_read_b128 v[136:139], v203 offset:16
	ds_read_b128 v[140:143], v203 offset:528
	ds_read_b128 v[144:147], v203 offset:1024
	ds_read_b128 v[148:151], v203 offset:1536
	ds_read_b128 v[152:155], v203 offset:1040
	ds_read_b128 v[156:159], v203 offset:1552
	s_waitcnt lgkmcnt(0)
	ds_read_b128 v[160:163], v203 offset:2048
	ds_read_b128 v[164:167], v203 offset:2560
	ds_read_b128 v[168:171], v203 offset:2064
	ds_read_b128 v[204:207], v203 offset:2576
	ds_read_b128 v[208:211], v203 offset:3072
	ds_read_b128 v[212:215], v203 offset:3584
	ds_read_b128 v[220:223], v203 offset:3088
	ds_read_b128 v[224:227], v203 offset:3600
	v_lshl_add_u64 v[190:191], v[188:189], 1, s[16:17]
	s_waitcnt lgkmcnt(0)
	s_add_i32 s6, s0, 2079
	s_mul_hi_u32 s7, s6, s59
	s_lshr_b32 s7, s7, 7
	s_mulk_i32 s7, 0x810
	s_sub_i32 s6, s6, s7
	s_cmp_lt_u32 s6, 17
	s_cbranch_scc1 .Lffn1e_slow0
	v_mov_b32_dpp v228, v124 row_shr:1 row_mask:0xf bank_mask:0xf bound_ctrl:1
	v_mov_b32_dpp v229, v124 row_shr:2 row_mask:0xf bank_mask:0xf bound_ctrl:1
	v_mov_b32_dpp v230, v125 row_shr:1 row_mask:0xf bank_mask:0xf bound_ctrl:1
	v_mov_b32_dpp v231, v125 row_shr:2 row_mask:0xf bank_mask:0xf bound_ctrl:1
	v_mov_b32_dpp v232, v126 row_shr:1 row_mask:0xf bank_mask:0xf bound_ctrl:1
	v_mov_b32_dpp v233, v126 row_shr:2 row_mask:0xf bank_mask:0xf bound_ctrl:1
	v_mov_b32_dpp v234, v127 row_shr:1 row_mask:0xf bank_mask:0xf bound_ctrl:1
	v_mov_b32_dpp v235, v127 row_shr:2 row_mask:0xf bank_mask:0xf bound_ctrl:1
	v_fma_f32 v236, v229, v128, v208
	v_fma_f32 v237, v231, v129, v209
	v_fma_f32 v238, v233, v130, v210
	v_fma_f32 v239, v235, v131, v211
	v_fmac_f32_e32 v236, v228, v144
	v_fmac_f32_e32 v237, v230, v145
	v_fmac_f32_e32 v238, v232, v146
	v_fmac_f32_e32 v239, v234, v147
	v_fmac_f32_e32 v236, v124, v160
	v_fmac_f32_e32 v237, v125, v161
	v_fmac_f32_e32 v238, v126, v162
	v_fmac_f32_e32 v239, v127, v163
	v_mov_b32_dpp v228, v116 row_shr:1 row_mask:0xf bank_mask:0xf bound_ctrl:1
	v_mov_b32_dpp v229, v116 row_shr:2 row_mask:0xf bank_mask:0xf bound_ctrl:1
	v_mov_b32_dpp v230, v117 row_shr:1 row_mask:0xf bank_mask:0xf bound_ctrl:1
	v_mov_b32_dpp v231, v117 row_shr:2 row_mask:0xf bank_mask:0xf bound_ctrl:1
	v_mov_b32_dpp v232, v118 row_shr:1 row_mask:0xf bank_mask:0xf bound_ctrl:1
	v_mov_b32_dpp v233, v118 row_shr:2 row_mask:0xf bank_mask:0xf bound_ctrl:1
	v_mov_b32_dpp v234, v119 row_shr:1 row_mask:0xf bank_mask:0xf bound_ctrl:1
	v_mov_b32_dpp v235, v119 row_shr:2 row_mask:0xf bank_mask:0xf bound_ctrl:1
	v_fma_f32 v240, v229, v132, v212
	v_fma_f32 v241, v231, v133, v213
	v_fma_f32 v242, v233, v134, v214
	v_fma_f32 v243, v235, v135, v215
	v_fmac_f32_e32 v240, v228, v148
	v_fmac_f32_e32 v241, v230, v149
	v_fmac_f32_e32 v242, v232, v150
	v_fmac_f32_e32 v243, v234, v151
	v_fmac_f32_e32 v240, v116, v164
	v_fmac_f32_e32 v241, v117, v165
	v_fmac_f32_e32 v242, v118, v166
	v_fmac_f32_e32 v243, v119, v167
	v_mul_f32_e32 v244, 0x3d372713, v236
	v_mul_f32_e32 v245, 0x3d372713, v237
	v_mul_f32_e32 v246, 0x3d372713, v238
	v_mul_f32_e32 v247, 0x3d372713, v239
	v_mul_f32_e32 v244, v236, v244
	v_mul_f32_e32 v245, v237, v245
	v_mul_f32_e32 v246, v238, v246
	v_mul_f32_e32 v247, v239, v247
	v_fma_f32 v244, v236, v244, v236
	v_fma_f32 v245, v237, v245, v237
	v_fma_f32 v246, v238, v246, v238
	v_fma_f32 v247, v239, v247, v239
	v_mul_f32_e32 v244, 0x3f4c422a, v244
	v_mul_f32_e32 v245, 0x3f4c422a, v245
	v_mul_f32_e32 v246, 0x3f4c422a, v246
	v_mul_f32_e32 v247, 0x3f4c422a, v247
	v_mul_f32_e32 v244, 0xc038aa3b, v244
	v_mul_f32_e32 v245, 0xc038aa3b, v245
	v_mul_f32_e32 v246, 0xc038aa3b, v246
	v_mul_f32_e32 v247, 0xc038aa3b, v247
	v_exp_f32_e32 v244, v244
	v_exp_f32_e32 v245, v245
	v_exp_f32_e32 v246, v246
	v_exp_f32_e32 v247, v247
	v_add_f32_e32 v244, 1.0, v244
	v_add_f32_e32 v245, 1.0, v245
	v_add_f32_e32 v246, 1.0, v246
	v_add_f32_e32 v247, 1.0, v247
	v_rcp_f32_e32 v244, v244
	v_rcp_f32_e32 v245, v245
	v_rcp_f32_e32 v246, v246
	v_rcp_f32_e32 v247, v247
	v_mul_f32_e32 v244, v236, v244
	v_mul_f32_e32 v245, v237, v245
	v_mul_f32_e32 v246, v238, v246
	v_mul_f32_e32 v247, v239, v247
	v_mul_f32_e32 v248, v240, v244
	v_mul_f32_e32 v249, v241, v245
	v_mul_f32_e32 v250, v242, v246
	v_mul_f32_e32 v251, v243, v247
	v_mov_b32_dpp v228, v120 row_shr:1 row_mask:0xf bank_mask:0xf bound_ctrl:1
	v_mov_b32_dpp v229, v120 row_shr:2 row_mask:0xf bank_mask:0xf bound_ctrl:1
	v_mov_b32_dpp v230, v121 row_shr:1 row_mask:0xf bank_mask:0xf bound_ctrl:1
	v_mov_b32_dpp v231, v121 row_shr:2 row_mask:0xf bank_mask:0xf bound_ctrl:1
	v_mov_b32_dpp v232, v122 row_shr:1 row_mask:0xf bank_mask:0xf bound_ctrl:1
	v_mov_b32_dpp v233, v122 row_shr:2 row_mask:0xf bank_mask:0xf bound_ctrl:1
	v_mov_b32_dpp v234, v123 row_shr:1 row_mask:0xf bank_mask:0xf bound_ctrl:1
	v_mov_b32_dpp v235, v123 row_shr:2 row_mask:0xf bank_mask:0xf bound_ctrl:1
	v_fma_f32 v236, v229, v136, v220
	v_fma_f32 v237, v231, v137, v221
	v_fma_f32 v238, v233, v138, v222
	v_fma_f32 v239, v235, v139, v223
	v_fmac_f32_e32 v236, v228, v152
	v_fmac_f32_e32 v237, v230, v153
	v_fmac_f32_e32 v238, v232, v154
	v_fmac_f32_e32 v239, v234, v155
	v_fmac_f32_e32 v236, v120, v168
	v_fmac_f32_e32 v237, v121, v169
	v_fmac_f32_e32 v238, v122, v170
	v_fmac_f32_e32 v239, v123, v171
	v_mov_b32_dpp v228, v112 row_shr:1 row_mask:0xf bank_mask:0xf bound_ctrl:1
	v_mov_b32_dpp v229, v112 row_shr:2 row_mask:0xf bank_mask:0xf bound_ctrl:1
	v_mov_b32_dpp v230, v113 row_shr:1 row_mask:0xf bank_mask:0xf bound_ctrl:1
	v_mov_b32_dpp v231, v113 row_shr:2 row_mask:0xf bank_mask:0xf bound_ctrl:1
	v_mov_b32_dpp v232, v114 row_shr:1 row_mask:0xf bank_mask:0xf bound_ctrl:1
	v_mov_b32_dpp v233, v114 row_shr:2 row_mask:0xf bank_mask:0xf bound_ctrl:1
	v_mov_b32_dpp v234, v115 row_shr:1 row_mask:0xf bank_mask:0xf bound_ctrl:1
	v_mov_b32_dpp v235, v115 row_shr:2 row_mask:0xf bank_mask:0xf bound_ctrl:1
	v_fma_f32 v240, v229, v140, v224
	v_fma_f32 v241, v231, v141, v225
	v_fma_f32 v242, v233, v142, v226
	v_fma_f32 v243, v235, v143, v227
	v_fmac_f32_e32 v240, v228, v156
	v_fmac_f32_e32 v241, v230, v157
	v_fmac_f32_e32 v242, v232, v158
	v_fmac_f32_e32 v243, v234, v159
	v_fmac_f32_e32 v240, v112, v204
	v_fmac_f32_e32 v241, v113, v205
	v_fmac_f32_e32 v242, v114, v206
	v_fmac_f32_e32 v243, v115, v207
	v_mul_f32_e32 v244, 0x3d372713, v236
	v_mul_f32_e32 v245, 0x3d372713, v237
	v_mul_f32_e32 v246, 0x3d372713, v238
	v_mul_f32_e32 v247, 0x3d372713, v239
	v_mul_f32_e32 v244, v236, v244
	v_mul_f32_e32 v245, v237, v245
	v_mul_f32_e32 v246, v238, v246
	v_mul_f32_e32 v247, v239, v247
	v_fma_f32 v244, v236, v244, v236
	v_fma_f32 v245, v237, v245, v237
	v_fma_f32 v246, v238, v246, v238
	v_fma_f32 v247, v239, v247, v239
	v_mul_f32_e32 v244, 0x3f4c422a, v244
	v_mul_f32_e32 v245, 0x3f4c422a, v245
	v_mul_f32_e32 v246, 0x3f4c422a, v246
	v_mul_f32_e32 v247, 0x3f4c422a, v247
	v_mul_f32_e32 v244, 0xc038aa3b, v244
	v_mul_f32_e32 v245, 0xc038aa3b, v245
	v_mul_f32_e32 v246, 0xc038aa3b, v246
	v_mul_f32_e32 v247, 0xc038aa3b, v247
	v_exp_f32_e32 v244, v244
	v_exp_f32_e32 v245, v245
	v_exp_f32_e32 v246, v246
	v_exp_f32_e32 v247, v247
	v_add_f32_e32 v244, 1.0, v244
	v_add_f32_e32 v245, 1.0, v245
	v_add_f32_e32 v246, 1.0, v246
	v_add_f32_e32 v247, 1.0, v247
	v_rcp_f32_e32 v244, v244
	v_rcp_f32_e32 v245, v245
	v_rcp_f32_e32 v246, v246
	v_rcp_f32_e32 v247, v247
	v_mul_f32_e32 v244, v236, v244
	v_mul_f32_e32 v245, v237, v245
	v_mul_f32_e32 v246, v238, v246
	v_mul_f32_e32 v247, v239, v247
	v_mul_f32_e32 v174, v240, v244
	v_mul_f32_e32 v175, v241, v245
	v_mul_f32_e32 v176, v242, v246
	v_mul_f32_e32 v177, v243, v247
	v_cvt_pk_bf16_f32 v180, v248, v249
	v_cvt_pk_bf16_f32 v181, v250, v251
	v_cvt_pk_bf16_f32 v182, v174, v175
	v_cvt_pk_bf16_f32 v183, v176, v177
.Lffn1e_store0:
	v_mad_i64_i32 v[216:217], vcc, v218, s79, v[190:191]
	v_cmp_lt_u32_e64 s[8:9], 1, v219
	v_cmp_gt_i32_e32 vcc, s58, v218
	s_nop 1
	s_and_b64 vcc, vcc, s[8:9]
	s_and_saveexec_b64 s[10:11], vcc
	global_store_dwordx4 v[216:217], v[180:183], off sc1
	s_mov_b64 exec, s[10:11]
	s_add_i32 s6, s0, 2095
	s_mul_hi_u32 s7, s6, s59
	s_lshr_b32 s7, s7, 7
	s_mulk_i32 s7, 0x810
	s_sub_i32 s6, s6, s7
	s_cmp_lt_u32 s6, 17
	s_cbranch_scc1 .Lffn1e_slow1
	v_mov_b32_dpp v228, v124 row_ror:1 row_mask:0xf bank_mask:0xf
	v_mov_b32_dpp v229, v124 row_ror:2 row_mask:0xf bank_mask:0xf
	v_mov_b32_dpp v230, v125 row_ror:1 row_mask:0xf bank_mask:0xf
	v_mov_b32_dpp v231, v125 row_ror:2 row_mask:0xf bank_mask:0xf
	v_mov_b32_dpp v232, v126 row_ror:1 row_mask:0xf bank_mask:0xf
	v_mov_b32_dpp v233, v126 row_ror:2 row_mask:0xf bank_mask:0xf
	v_mov_b32_dpp v234, v127 row_ror:1 row_mask:0xf bank_mask:0xf
	v_mov_b32_dpp v235, v127 row_ror:2 row_mask:0xf bank_mask:0xf
	v_mov_b32_dpp v228, v108 row_shr:1 row_mask:0xf bank_mask:0xf
	v_mov_b32_dpp v229, v108 row_shr:2 row_mask:0xf bank_mask:0xf
	v_mov_b32_dpp v230, v109 row_shr:1 row_mask:0xf bank_mask:0xf
	v_mov_b32_dpp v231, v109 row_shr:2 row_mask:0xf bank_mask:0xf
	v_mov_b32_dpp v232, v110 row_shr:1 row_mask:0xf bank_mask:0xf
	v_mov_b32_dpp v233, v110 row_shr:2 row_mask:0xf bank_mask:0xf
	v_mov_b32_dpp v234, v111 row_shr:1 row_mask:0xf bank_mask:0xf
	v_mov_b32_dpp v235, v111 row_shr:2 row_mask:0xf bank_mask:0xf
	v_fma_f32 v236, v229, v128, v208
	v_fma_f32 v237, v231, v129, v209
	v_fma_f32 v238, v233, v130, v210
	v_fma_f32 v239, v235, v131, v211
	v_fmac_f32_e32 v236, v228, v144
	v_fmac_f32_e32 v237, v230, v145
	v_fmac_f32_e32 v238, v232, v146
	v_fmac_f32_e32 v239, v234, v147
	v_fmac_f32_e32 v236, v108, v160
	v_fmac_f32_e32 v237, v109, v161
	v_fmac_f32_e32 v238, v110, v162
	v_fmac_f32_e32 v239, v111, v163
	v_mov_b32_dpp v228, v116 row_ror:1 row_mask:0xf bank_mask:0xf
	v_mov_b32_dpp v229, v116 row_ror:2 row_mask:0xf bank_mask:0xf
	v_mov_b32_dpp v230, v117 row_ror:1 row_mask:0xf bank_mask:0xf
	v_mov_b32_dpp v231, v117 row_ror:2 row_mask:0xf bank_mask:0xf
	v_mov_b32_dpp v232, v118 row_ror:1 row_mask:0xf bank_mask:0xf
	v_mov_b32_dpp v233, v118 row_ror:2 row_mask:0xf bank_mask:0xf
	v_mov_b32_dpp v234, v119 row_ror:1 row_mask:0xf bank_mask:0xf
	v_mov_b32_dpp v235, v119 row_ror:2 row_mask:0xf bank_mask:0xf
	v_mov_b32_dpp v228, v100 row_shr:1 row_mask:0xf bank_mask:0xf
	v_mov_b32_dpp v229, v100 row_shr:2 row_mask:0xf bank_mask:0xf
	v_mov_b32_dpp v230, v101 row_shr:1 row_mask:0xf bank_mask:0xf
	v_mov_b32_dpp v231, v101 row_shr:2 row_mask:0xf bank_mask:0xf
	v_mov_b32_dpp v232, v102 row_shr:1 row_mask:0xf bank_mask:0xf
	v_mov_b32_dpp v233, v102 row_shr:2 row_mask:0xf bank_mask:0xf
	v_mov_b32_dpp v234, v103 row_shr:1 row_mask:0xf bank_mask:0xf
	v_mov_b32_dpp v235, v103 row_shr:2 row_mask:0xf bank_mask:0xf
	v_fma_f32 v240, v229, v132, v212
	v_fma_f32 v241, v231, v133, v213
	v_fma_f32 v242, v233, v134, v214
	v_fma_f32 v243, v235, v135, v215
	v_fmac_f32_e32 v240, v228, v148
	v_fmac_f32_e32 v241, v230, v149
	v_fmac_f32_e32 v242, v232, v150
	v_fmac_f32_e32 v243, v234, v151
	v_fmac_f32_e32 v240, v100, v164
	v_fmac_f32_e32 v241, v101, v165
	v_fmac_f32_e32 v242, v102, v166
	v_fmac_f32_e32 v243, v103, v167
	v_mul_f32_e32 v244, 0x3d372713, v236
	v_mul_f32_e32 v245, 0x3d372713, v237
	v_mul_f32_e32 v246, 0x3d372713, v238
	v_mul_f32_e32 v247, 0x3d372713, v239
	v_mul_f32_e32 v244, v236, v244
	v_mul_f32_e32 v245, v237, v245
	v_mul_f32_e32 v246, v238, v246
	v_mul_f32_e32 v247, v239, v247
	v_fma_f32 v244, v236, v244, v236
	v_fma_f32 v245, v237, v245, v237
	v_fma_f32 v246, v238, v246, v238
	v_fma_f32 v247, v239, v247, v239
	v_mul_f32_e32 v244, 0x3f4c422a, v244
	v_mul_f32_e32 v245, 0x3f4c422a, v245
	v_mul_f32_e32 v246, 0x3f4c422a, v246
	v_mul_f32_e32 v247, 0x3f4c422a, v247
	v_mul_f32_e32 v244, 0xc038aa3b, v244
	v_mul_f32_e32 v245, 0xc038aa3b, v245
	v_mul_f32_e32 v246, 0xc038aa3b, v246
	v_mul_f32_e32 v247, 0xc038aa3b, v247
	v_exp_f32_e32 v244, v244
	v_exp_f32_e32 v245, v245
	v_exp_f32_e32 v246, v246
	v_exp_f32_e32 v247, v247
	v_add_f32_e32 v244, 1.0, v244
	v_add_f32_e32 v245, 1.0, v245
	v_add_f32_e32 v246, 1.0, v246
	v_add_f32_e32 v247, 1.0, v247
	v_rcp_f32_e32 v244, v244
	v_rcp_f32_e32 v245, v245
	v_rcp_f32_e32 v246, v246
	v_rcp_f32_e32 v247, v247
	v_mul_f32_e32 v244, v236, v244
	v_mul_f32_e32 v245, v237, v245
	v_mul_f32_e32 v246, v238, v246
	v_mul_f32_e32 v247, v239, v247
	v_mul_f32_e32 v248, v240, v244
	v_mul_f32_e32 v249, v241, v245
	v_mul_f32_e32 v250, v242, v246
	v_mul_f32_e32 v251, v243, v247
	v_mov_b32_dpp v228, v120 row_ror:1 row_mask:0xf bank_mask:0xf
	v_mov_b32_dpp v229, v120 row_ror:2 row_mask:0xf bank_mask:0xf
	v_mov_b32_dpp v230, v121 row_ror:1 row_mask:0xf bank_mask:0xf
	v_mov_b32_dpp v231, v121 row_ror:2 row_mask:0xf bank_mask:0xf
	v_mov_b32_dpp v232, v122 row_ror:1 row_mask:0xf bank_mask:0xf
	v_mov_b32_dpp v233, v122 row_ror:2 row_mask:0xf bank_mask:0xf
	v_mov_b32_dpp v234, v123 row_ror:1 row_mask:0xf bank_mask:0xf
	v_mov_b32_dpp v235, v123 row_ror:2 row_mask:0xf bank_mask:0xf
	v_mov_b32_dpp v228, v104 row_shr:1 row_mask:0xf bank_mask:0xf
	v_mov_b32_dpp v229, v104 row_shr:2 row_mask:0xf bank_mask:0xf
	v_mov_b32_dpp v230, v105 row_shr:1 row_mask:0xf bank_mask:0xf
	v_mov_b32_dpp v231, v105 row_shr:2 row_mask:0xf bank_mask:0xf
	v_mov_b32_dpp v232, v106 row_shr:1 row_mask:0xf bank_mask:0xf
	v_mov_b32_dpp v233, v106 row_shr:2 row_mask:0xf bank_mask:0xf
	v_mov_b32_dpp v234, v107 row_shr:1 row_mask:0xf bank_mask:0xf
	v_mov_b32_dpp v235, v107 row_shr:2 row_mask:0xf bank_mask:0xf
	v_fma_f32 v236, v229, v136, v220
	v_fma_f32 v237, v231, v137, v221
	v_fma_f32 v238, v233, v138, v222
	v_fma_f32 v239, v235, v139, v223
	v_fmac_f32_e32 v236, v228, v152
	v_fmac_f32_e32 v237, v230, v153
	v_fmac_f32_e32 v238, v232, v154
	v_fmac_f32_e32 v239, v234, v155
	v_fmac_f32_e32 v236, v104, v168
	v_fmac_f32_e32 v237, v105, v169
	v_fmac_f32_e32 v238, v106, v170
	v_fmac_f32_e32 v239, v107, v171
	v_mov_b32_dpp v228, v112 row_ror:1 row_mask:0xf bank_mask:0xf
	v_mov_b32_dpp v229, v112 row_ror:2 row_mask:0xf bank_mask:0xf
	v_mov_b32_dpp v230, v113 row_ror:1 row_mask:0xf bank_mask:0xf
	v_mov_b32_dpp v231, v113 row_ror:2 row_mask:0xf bank_mask:0xf
	v_mov_b32_dpp v232, v114 row_ror:1 row_mask:0xf bank_mask:0xf
	v_mov_b32_dpp v233, v114 row_ror:2 row_mask:0xf bank_mask:0xf
	v_mov_b32_dpp v234, v115 row_ror:1 row_mask:0xf bank_mask:0xf
	v_mov_b32_dpp v235, v115 row_ror:2 row_mask:0xf bank_mask:0xf
	v_mov_b32_dpp v228, v96 row_shr:1 row_mask:0xf bank_mask:0xf
	v_mov_b32_dpp v229, v96 row_shr:2 row_mask:0xf bank_mask:0xf
	v_mov_b32_dpp v230, v97 row_shr:1 row_mask:0xf bank_mask:0xf
	v_mov_b32_dpp v231, v97 row_shr:2 row_mask:0xf bank_mask:0xf
	v_mov_b32_dpp v232, v98 row_shr:1 row_mask:0xf bank_mask:0xf
	v_mov_b32_dpp v233, v98 row_shr:2 row_mask:0xf bank_mask:0xf
	v_mov_b32_dpp v234, v99 row_shr:1 row_mask:0xf bank_mask:0xf
	v_mov_b32_dpp v235, v99 row_shr:2 row_mask:0xf bank_mask:0xf
	v_fma_f32 v240, v229, v140, v224
	v_fma_f32 v241, v231, v141, v225
	v_fma_f32 v242, v233, v142, v226
	v_fma_f32 v243, v235, v143, v227
	v_fmac_f32_e32 v240, v228, v156
	v_fmac_f32_e32 v241, v230, v157
	v_fmac_f32_e32 v242, v232, v158
	v_fmac_f32_e32 v243, v234, v159
	v_fmac_f32_e32 v240, v96, v204
	v_fmac_f32_e32 v241, v97, v205
	v_fmac_f32_e32 v242, v98, v206
	v_fmac_f32_e32 v243, v99, v207
	v_mul_f32_e32 v244, 0x3d372713, v236
	v_mul_f32_e32 v245, 0x3d372713, v237
	v_mul_f32_e32 v246, 0x3d372713, v238
	v_mul_f32_e32 v247, 0x3d372713, v239
	v_mul_f32_e32 v244, v236, v244
	v_mul_f32_e32 v245, v237, v245
	v_mul_f32_e32 v246, v238, v246
	v_mul_f32_e32 v247, v239, v247
	v_fma_f32 v244, v236, v244, v236
	v_fma_f32 v245, v237, v245, v237
	v_fma_f32 v246, v238, v246, v238
	v_fma_f32 v247, v239, v247, v239
	v_mul_f32_e32 v244, 0x3f4c422a, v244
	v_mul_f32_e32 v245, 0x3f4c422a, v245
	v_mul_f32_e32 v246, 0x3f4c422a, v246
	v_mul_f32_e32 v247, 0x3f4c422a, v247
	v_mul_f32_e32 v244, 0xc038aa3b, v244
	v_mul_f32_e32 v245, 0xc038aa3b, v245
	v_mul_f32_e32 v246, 0xc038aa3b, v246
	v_mul_f32_e32 v247, 0xc038aa3b, v247
	v_exp_f32_e32 v244, v244
	v_exp_f32_e32 v245, v245
	v_exp_f32_e32 v246, v246
	v_exp_f32_e32 v247, v247
	v_add_f32_e32 v244, 1.0, v244
	v_add_f32_e32 v245, 1.0, v245
	v_add_f32_e32 v246, 1.0, v246
	v_add_f32_e32 v247, 1.0, v247
	v_rcp_f32_e32 v244, v244
	v_rcp_f32_e32 v245, v245
	v_rcp_f32_e32 v246, v246
	v_rcp_f32_e32 v247, v247
	v_mul_f32_e32 v244, v236, v244
	v_mul_f32_e32 v245, v237, v245
	v_mul_f32_e32 v246, v238, v246
	v_mul_f32_e32 v247, v239, v247
	v_mul_f32_e32 v174, v240, v244
	v_mul_f32_e32 v175, v241, v245
	v_mul_f32_e32 v176, v242, v246
	v_mul_f32_e32 v177, v243, v247
	v_cvt_pk_bf16_f32 v180, v248, v249
	v_cvt_pk_bf16_f32 v181, v250, v251
	v_cvt_pk_bf16_f32 v182, v174, v175
	v_cvt_pk_bf16_f32 v183, v176, v177
.Lffn1e_store1:
	v_add_u32_e32 v252, 16, v218
	v_mad_i64_i32 v[216:217], vcc, v252, s79, v[190:191]
	v_cmp_gt_i32_e32 vcc, s58, v252
	s_nop 1
	s_and_saveexec_b64 s[10:11], vcc
	global_store_dwordx4 v[216:217], v[180:183], off sc1
	s_mov_b64 exec, s[10:11]
	s_add_i32 s6, s0, 2111
	s_mul_hi_u32 s7, s6, s59
	s_lshr_b32 s7, s7, 7
	s_mulk_i32 s7, 0x810
	s_sub_i32 s6, s6, s7
	s_cmp_lt_u32 s6, 17
	s_cbranch_scc1 .Lffn1e_slow2
	v_mov_b32_dpp v228, v108 row_ror:1 row_mask:0xf bank_mask:0xf
	v_mov_b32_dpp v229, v108 row_ror:2 row_mask:0xf bank_mask:0xf
	v_mov_b32_dpp v230, v109 row_ror:1 row_mask:0xf bank_mask:0xf
	v_mov_b32_dpp v231, v109 row_ror:2 row_mask:0xf bank_mask:0xf
	v_mov_b32_dpp v232, v110 row_ror:1 row_mask:0xf bank_mask:0xf
	v_mov_b32_dpp v233, v110 row_ror:2 row_mask:0xf bank_mask:0xf
	v_mov_b32_dpp v234, v111 row_ror:1 row_mask:0xf bank_mask:0xf
	v_mov_b32_dpp v235, v111 row_ror:2 row_mask:0xf bank_mask:0xf
	v_mov_b32_dpp v228, v92 row_shr:1 row_mask:0xf bank_mask:0xf
	v_mov_b32_dpp v229, v92 row_shr:2 row_mask:0xf bank_mask:0xf
	v_mov_b32_dpp v230, v93 row_shr:1 row_mask:0xf bank_mask:0xf
	v_mov_b32_dpp v231, v93 row_shr:2 row_mask:0xf bank_mask:0xf
	v_mov_b32_dpp v232, v94 row_shr:1 row_mask:0xf bank_mask:0xf
	v_mov_b32_dpp v233, v94 row_shr:2 row_mask:0xf bank_mask:0xf
	v_mov_b32_dpp v234, v95 row_shr:1 row_mask:0xf bank_mask:0xf
	v_mov_b32_dpp v235, v95 row_shr:2 row_mask:0xf bank_mask:0xf
	v_fma_f32 v236, v229, v128, v208
	v_fma_f32 v237, v231, v129, v209
	v_fma_f32 v238, v233, v130, v210
	v_fma_f32 v239, v235, v131, v211
	v_fmac_f32_e32 v236, v228, v144
	v_fmac_f32_e32 v237, v230, v145
	v_fmac_f32_e32 v238, v232, v146
	v_fmac_f32_e32 v239, v234, v147
	v_fmac_f32_e32 v236, v92, v160
	v_fmac_f32_e32 v237, v93, v161
	v_fmac_f32_e32 v238, v94, v162
	v_fmac_f32_e32 v239, v95, v163
	v_mov_b32_dpp v228, v100 row_ror:1 row_mask:0xf bank_mask:0xf
	v_mov_b32_dpp v229, v100 row_ror:2 row_mask:0xf bank_mask:0xf
	v_mov_b32_dpp v230, v101 row_ror:1 row_mask:0xf bank_mask:0xf
	v_mov_b32_dpp v231, v101 row_ror:2 row_mask:0xf bank_mask:0xf
	v_mov_b32_dpp v232, v102 row_ror:1 row_mask:0xf bank_mask:0xf
	v_mov_b32_dpp v233, v102 row_ror:2 row_mask:0xf bank_mask:0xf
	v_mov_b32_dpp v234, v103 row_ror:1 row_mask:0xf bank_mask:0xf
	v_mov_b32_dpp v235, v103 row_ror:2 row_mask:0xf bank_mask:0xf
	v_mov_b32_dpp v228, v84 row_shr:1 row_mask:0xf bank_mask:0xf
	v_mov_b32_dpp v229, v84 row_shr:2 row_mask:0xf bank_mask:0xf
	v_mov_b32_dpp v230, v85 row_shr:1 row_mask:0xf bank_mask:0xf
	v_mov_b32_dpp v231, v85 row_shr:2 row_mask:0xf bank_mask:0xf
	v_mov_b32_dpp v232, v86 row_shr:1 row_mask:0xf bank_mask:0xf
	v_mov_b32_dpp v233, v86 row_shr:2 row_mask:0xf bank_mask:0xf
	v_mov_b32_dpp v234, v87 row_shr:1 row_mask:0xf bank_mask:0xf
	v_mov_b32_dpp v235, v87 row_shr:2 row_mask:0xf bank_mask:0xf
	v_fma_f32 v240, v229, v132, v212
	v_fma_f32 v241, v231, v133, v213
	v_fma_f32 v242, v233, v134, v214
	v_fma_f32 v243, v235, v135, v215
	v_fmac_f32_e32 v240, v228, v148
	v_fmac_f32_e32 v241, v230, v149
	v_fmac_f32_e32 v242, v232, v150
	v_fmac_f32_e32 v243, v234, v151
	v_fmac_f32_e32 v240, v84, v164
	v_fmac_f32_e32 v241, v85, v165
	v_fmac_f32_e32 v242, v86, v166
	v_fmac_f32_e32 v243, v87, v167
	v_mul_f32_e32 v244, 0x3d372713, v236
	v_mul_f32_e32 v245, 0x3d372713, v237
	v_mul_f32_e32 v246, 0x3d372713, v238
	v_mul_f32_e32 v247, 0x3d372713, v239
	v_mul_f32_e32 v244, v236, v244
	v_mul_f32_e32 v245, v237, v245
	v_mul_f32_e32 v246, v238, v246
	v_mul_f32_e32 v247, v239, v247
	v_fma_f32 v244, v236, v244, v236
	v_fma_f32 v245, v237, v245, v237
	v_fma_f32 v246, v238, v246, v238
	v_fma_f32 v247, v239, v247, v239
	v_mul_f32_e32 v244, 0x3f4c422a, v244
	v_mul_f32_e32 v245, 0x3f4c422a, v245
	v_mul_f32_e32 v246, 0x3f4c422a, v246
	v_mul_f32_e32 v247, 0x3f4c422a, v247
	v_mul_f32_e32 v244, 0xc038aa3b, v244
	v_mul_f32_e32 v245, 0xc038aa3b, v245
	v_mul_f32_e32 v246, 0xc038aa3b, v246
	v_mul_f32_e32 v247, 0xc038aa3b, v247
	v_exp_f32_e32 v244, v244
	v_exp_f32_e32 v245, v245
	v_exp_f32_e32 v246, v246
	v_exp_f32_e32 v247, v247
	v_add_f32_e32 v244, 1.0, v244
	v_add_f32_e32 v245, 1.0, v245
	v_add_f32_e32 v246, 1.0, v246
	v_add_f32_e32 v247, 1.0, v247
	v_rcp_f32_e32 v244, v244
	v_rcp_f32_e32 v245, v245
	v_rcp_f32_e32 v246, v246
	v_rcp_f32_e32 v247, v247
	v_mul_f32_e32 v244, v236, v244
	v_mul_f32_e32 v245, v237, v245
	v_mul_f32_e32 v246, v238, v246
	v_mul_f32_e32 v247, v239, v247
	v_mul_f32_e32 v248, v240, v244
	v_mul_f32_e32 v249, v241, v245
	v_mul_f32_e32 v250, v242, v246
	v_mul_f32_e32 v251, v243, v247
	v_mov_b32_dpp v228, v104 row_ror:1 row_mask:0xf bank_mask:0xf
	v_mov_b32_dpp v229, v104 row_ror:2 row_mask:0xf bank_mask:0xf
	v_mov_b32_dpp v230, v105 row_ror:1 row_mask:0xf bank_mask:0xf
	v_mov_b32_dpp v231, v105 row_ror:2 row_mask:0xf bank_mask:0xf
	v_mov_b32_dpp v232, v106 row_ror:1 row_mask:0xf bank_mask:0xf
	v_mov_b32_dpp v233, v106 row_ror:2 row_mask:0xf bank_mask:0xf
	v_mov_b32_dpp v234, v107 row_ror:1 row_mask:0xf bank_mask:0xf
	v_mov_b32_dpp v235, v107 row_ror:2 row_mask:0xf bank_mask:0xf
	v_mov_b32_dpp v228, v88 row_shr:1 row_mask:0xf bank_mask:0xf
	v_mov_b32_dpp v229, v88 row_shr:2 row_mask:0xf bank_mask:0xf
	v_mov_b32_dpp v230, v89 row_shr:1 row_mask:0xf bank_mask:0xf
	v_mov_b32_dpp v231, v89 row_shr:2 row_mask:0xf bank_mask:0xf
	v_mov_b32_dpp v232, v90 row_shr:1 row_mask:0xf bank_mask:0xf
	v_mov_b32_dpp v233, v90 row_shr:2 row_mask:0xf bank_mask:0xf
	v_mov_b32_dpp v234, v91 row_shr:1 row_mask:0xf bank_mask:0xf
	v_mov_b32_dpp v235, v91 row_shr:2 row_mask:0xf bank_mask:0xf
	v_fma_f32 v236, v229, v136, v220
	v_fma_f32 v237, v231, v137, v221
	v_fma_f32 v238, v233, v138, v222
	v_fma_f32 v239, v235, v139, v223
	v_fmac_f32_e32 v236, v228, v152
	v_fmac_f32_e32 v237, v230, v153
	v_fmac_f32_e32 v238, v232, v154
	v_fmac_f32_e32 v239, v234, v155
	v_fmac_f32_e32 v236, v88, v168
	v_fmac_f32_e32 v237, v89, v169
	v_fmac_f32_e32 v238, v90, v170
	v_fmac_f32_e32 v239, v91, v171
	v_mov_b32_dpp v228, v96 row_ror:1 row_mask:0xf bank_mask:0xf
	v_mov_b32_dpp v229, v96 row_ror:2 row_mask:0xf bank_mask:0xf
	v_mov_b32_dpp v230, v97 row_ror:1 row_mask:0xf bank_mask:0xf
	v_mov_b32_dpp v231, v97 row_ror:2 row_mask:0xf bank_mask:0xf
	v_mov_b32_dpp v232, v98 row_ror:1 row_mask:0xf bank_mask:0xf
	v_mov_b32_dpp v233, v98 row_ror:2 row_mask:0xf bank_mask:0xf
	v_mov_b32_dpp v234, v99 row_ror:1 row_mask:0xf bank_mask:0xf
	v_mov_b32_dpp v235, v99 row_ror:2 row_mask:0xf bank_mask:0xf
	v_mov_b32_dpp v228, v80 row_shr:1 row_mask:0xf bank_mask:0xf
	v_mov_b32_dpp v229, v80 row_shr:2 row_mask:0xf bank_mask:0xf
	v_mov_b32_dpp v230, v81 row_shr:1 row_mask:0xf bank_mask:0xf
	v_mov_b32_dpp v231, v81 row_shr:2 row_mask:0xf bank_mask:0xf
	v_mov_b32_dpp v232, v82 row_shr:1 row_mask:0xf bank_mask:0xf
	v_mov_b32_dpp v233, v82 row_shr:2 row_mask:0xf bank_mask:0xf
	v_mov_b32_dpp v234, v83 row_shr:1 row_mask:0xf bank_mask:0xf
	v_mov_b32_dpp v235, v83 row_shr:2 row_mask:0xf bank_mask:0xf
	v_fma_f32 v240, v229, v140, v224
	v_fma_f32 v241, v231, v141, v225
	v_fma_f32 v242, v233, v142, v226
	v_fma_f32 v243, v235, v143, v227
	v_fmac_f32_e32 v240, v228, v156
	v_fmac_f32_e32 v241, v230, v157
	v_fmac_f32_e32 v242, v232, v158
	v_fmac_f32_e32 v243, v234, v159
	v_fmac_f32_e32 v240, v80, v204
	v_fmac_f32_e32 v241, v81, v205
	v_fmac_f32_e32 v242, v82, v206
	v_fmac_f32_e32 v243, v83, v207
	v_mul_f32_e32 v244, 0x3d372713, v236
	v_mul_f32_e32 v245, 0x3d372713, v237
	v_mul_f32_e32 v246, 0x3d372713, v238
	v_mul_f32_e32 v247, 0x3d372713, v239
	v_mul_f32_e32 v244, v236, v244
	v_mul_f32_e32 v245, v237, v245
	v_mul_f32_e32 v246, v238, v246
	v_mul_f32_e32 v247, v239, v247
	v_fma_f32 v244, v236, v244, v236
	v_fma_f32 v245, v237, v245, v237
	v_fma_f32 v246, v238, v246, v238
	v_fma_f32 v247, v239, v247, v239
	v_mul_f32_e32 v244, 0x3f4c422a, v244
	v_mul_f32_e32 v245, 0x3f4c422a, v245
	v_mul_f32_e32 v246, 0x3f4c422a, v246
	v_mul_f32_e32 v247, 0x3f4c422a, v247
	v_mul_f32_e32 v244, 0xc038aa3b, v244
	v_mul_f32_e32 v245, 0xc038aa3b, v245
	v_mul_f32_e32 v246, 0xc038aa3b, v246
	v_mul_f32_e32 v247, 0xc038aa3b, v247
	v_exp_f32_e32 v244, v244
	v_exp_f32_e32 v245, v245
	v_exp_f32_e32 v246, v246
	v_exp_f32_e32 v247, v247
	v_add_f32_e32 v244, 1.0, v244
	v_add_f32_e32 v245, 1.0, v245
	v_add_f32_e32 v246, 1.0, v246
	v_add_f32_e32 v247, 1.0, v247
	v_rcp_f32_e32 v244, v244
	v_rcp_f32_e32 v245, v245
	v_rcp_f32_e32 v246, v246
	v_rcp_f32_e32 v247, v247
	v_mul_f32_e32 v244, v236, v244
	v_mul_f32_e32 v245, v237, v245
	v_mul_f32_e32 v246, v238, v246
	v_mul_f32_e32 v247, v239, v247
	v_mul_f32_e32 v174, v240, v244
	v_mul_f32_e32 v175, v241, v245
	v_mul_f32_e32 v176, v242, v246
	v_mul_f32_e32 v177, v243, v247
	v_cvt_pk_bf16_f32 v180, v248, v249
	v_cvt_pk_bf16_f32 v181, v250, v251
	v_cvt_pk_bf16_f32 v182, v174, v175
	v_cvt_pk_bf16_f32 v183, v176, v177
.Lffn1e_store2:
	v_add_u32_e32 v252, 32, v218
	v_mad_i64_i32 v[216:217], vcc, v252, s79, v[190:191]
	v_cmp_gt_i32_e32 vcc, s58, v252
	s_nop 1
	s_and_saveexec_b64 s[10:11], vcc
	global_store_dwordx4 v[216:217], v[180:183], off sc1
	s_mov_b64 exec, s[10:11]
	s_add_i32 s6, s0, 2127
	s_mul_hi_u32 s7, s6, s59
	s_lshr_b32 s7, s7, 7
	s_mulk_i32 s7, 0x810
	s_sub_i32 s6, s6, s7
	s_cmp_lt_u32 s6, 17
	s_cbranch_scc1 .Lffn1e_slow3
	v_mov_b32_dpp v228, v92 row_ror:1 row_mask:0xf bank_mask:0xf
	v_mov_b32_dpp v229, v92 row_ror:2 row_mask:0xf bank_mask:0xf
	v_mov_b32_dpp v230, v93 row_ror:1 row_mask:0xf bank_mask:0xf
	v_mov_b32_dpp v231, v93 row_ror:2 row_mask:0xf bank_mask:0xf
	v_mov_b32_dpp v232, v94 row_ror:1 row_mask:0xf bank_mask:0xf
	v_mov_b32_dpp v233, v94 row_ror:2 row_mask:0xf bank_mask:0xf
	v_mov_b32_dpp v234, v95 row_ror:1 row_mask:0xf bank_mask:0xf
	v_mov_b32_dpp v235, v95 row_ror:2 row_mask:0xf bank_mask:0xf
	v_mov_b32_dpp v228, v76 row_shr:1 row_mask:0xf bank_mask:0xf
	v_mov_b32_dpp v229, v76 row_shr:2 row_mask:0xf bank_mask:0xf
	v_mov_b32_dpp v230, v77 row_shr:1 row_mask:0xf bank_mask:0xf
	v_mov_b32_dpp v231, v77 row_shr:2 row_mask:0xf bank_mask:0xf
	v_mov_b32_dpp v232, v78 row_shr:1 row_mask:0xf bank_mask:0xf
	v_mov_b32_dpp v233, v78 row_shr:2 row_mask:0xf bank_mask:0xf
	v_mov_b32_dpp v234, v79 row_shr:1 row_mask:0xf bank_mask:0xf
	v_mov_b32_dpp v235, v79 row_shr:2 row_mask:0xf bank_mask:0xf
	v_fma_f32 v236, v229, v128, v208
	v_fma_f32 v237, v231, v129, v209
	v_fma_f32 v238, v233, v130, v210
	v_fma_f32 v239, v235, v131, v211
	v_fmac_f32_e32 v236, v228, v144
	v_fmac_f32_e32 v237, v230, v145
	v_fmac_f32_e32 v238, v232, v146
	v_fmac_f32_e32 v239, v234, v147
	v_fmac_f32_e32 v236, v76, v160
	v_fmac_f32_e32 v237, v77, v161
	v_fmac_f32_e32 v238, v78, v162
	v_fmac_f32_e32 v239, v79, v163
	v_mov_b32_dpp v228, v84 row_ror:1 row_mask:0xf bank_mask:0xf
	v_mov_b32_dpp v229, v84 row_ror:2 row_mask:0xf bank_mask:0xf
	v_mov_b32_dpp v230, v85 row_ror:1 row_mask:0xf bank_mask:0xf
	v_mov_b32_dpp v231, v85 row_ror:2 row_mask:0xf bank_mask:0xf
	v_mov_b32_dpp v232, v86 row_ror:1 row_mask:0xf bank_mask:0xf
	v_mov_b32_dpp v233, v86 row_ror:2 row_mask:0xf bank_mask:0xf
	v_mov_b32_dpp v234, v87 row_ror:1 row_mask:0xf bank_mask:0xf
	v_mov_b32_dpp v235, v87 row_ror:2 row_mask:0xf bank_mask:0xf
	v_mov_b32_dpp v228, v68 row_shr:1 row_mask:0xf bank_mask:0xf
	v_mov_b32_dpp v229, v68 row_shr:2 row_mask:0xf bank_mask:0xf
	v_mov_b32_dpp v230, v69 row_shr:1 row_mask:0xf bank_mask:0xf
	v_mov_b32_dpp v231, v69 row_shr:2 row_mask:0xf bank_mask:0xf
	v_mov_b32_dpp v232, v70 row_shr:1 row_mask:0xf bank_mask:0xf
	v_mov_b32_dpp v233, v70 row_shr:2 row_mask:0xf bank_mask:0xf
	v_mov_b32_dpp v234, v71 row_shr:1 row_mask:0xf bank_mask:0xf
	v_mov_b32_dpp v235, v71 row_shr:2 row_mask:0xf bank_mask:0xf
	v_fma_f32 v240, v229, v132, v212
	v_fma_f32 v241, v231, v133, v213
	v_fma_f32 v242, v233, v134, v214
	v_fma_f32 v243, v235, v135, v215
	v_fmac_f32_e32 v240, v228, v148
	v_fmac_f32_e32 v241, v230, v149
	v_fmac_f32_e32 v242, v232, v150
	v_fmac_f32_e32 v243, v234, v151
	v_fmac_f32_e32 v240, v68, v164
	v_fmac_f32_e32 v241, v69, v165
	v_fmac_f32_e32 v242, v70, v166
	v_fmac_f32_e32 v243, v71, v167
	v_mul_f32_e32 v244, 0x3d372713, v236
	v_mul_f32_e32 v245, 0x3d372713, v237
	v_mul_f32_e32 v246, 0x3d372713, v238
	v_mul_f32_e32 v247, 0x3d372713, v239
	v_mul_f32_e32 v244, v236, v244
	v_mul_f32_e32 v245, v237, v245
	v_mul_f32_e32 v246, v238, v246
	v_mul_f32_e32 v247, v239, v247
	v_fma_f32 v244, v236, v244, v236
	v_fma_f32 v245, v237, v245, v237
	v_fma_f32 v246, v238, v246, v238
	v_fma_f32 v247, v239, v247, v239
	v_mul_f32_e32 v244, 0x3f4c422a, v244
	v_mul_f32_e32 v245, 0x3f4c422a, v245
	v_mul_f32_e32 v246, 0x3f4c422a, v246
	v_mul_f32_e32 v247, 0x3f4c422a, v247
	v_mul_f32_e32 v244, 0xc038aa3b, v244
	v_mul_f32_e32 v245, 0xc038aa3b, v245
	v_mul_f32_e32 v246, 0xc038aa3b, v246
	v_mul_f32_e32 v247, 0xc038aa3b, v247
	v_exp_f32_e32 v244, v244
	v_exp_f32_e32 v245, v245
	v_exp_f32_e32 v246, v246
	v_exp_f32_e32 v247, v247
	v_add_f32_e32 v244, 1.0, v244
	v_add_f32_e32 v245, 1.0, v245
	v_add_f32_e32 v246, 1.0, v246
	v_add_f32_e32 v247, 1.0, v247
	v_rcp_f32_e32 v244, v244
	v_rcp_f32_e32 v245, v245
	v_rcp_f32_e32 v246, v246
	v_rcp_f32_e32 v247, v247
	v_mul_f32_e32 v244, v236, v244
	v_mul_f32_e32 v245, v237, v245
	v_mul_f32_e32 v246, v238, v246
	v_mul_f32_e32 v247, v239, v247
	v_mul_f32_e32 v248, v240, v244
	v_mul_f32_e32 v249, v241, v245
	v_mul_f32_e32 v250, v242, v246
	v_mul_f32_e32 v251, v243, v247
	v_mov_b32_dpp v228, v88 row_ror:1 row_mask:0xf bank_mask:0xf
	v_mov_b32_dpp v229, v88 row_ror:2 row_mask:0xf bank_mask:0xf
	v_mov_b32_dpp v230, v89 row_ror:1 row_mask:0xf bank_mask:0xf
	v_mov_b32_dpp v231, v89 row_ror:2 row_mask:0xf bank_mask:0xf
	v_mov_b32_dpp v232, v90 row_ror:1 row_mask:0xf bank_mask:0xf
	v_mov_b32_dpp v233, v90 row_ror:2 row_mask:0xf bank_mask:0xf
	v_mov_b32_dpp v234, v91 row_ror:1 row_mask:0xf bank_mask:0xf
	v_mov_b32_dpp v235, v91 row_ror:2 row_mask:0xf bank_mask:0xf
	v_mov_b32_dpp v228, v72 row_shr:1 row_mask:0xf bank_mask:0xf
	v_mov_b32_dpp v229, v72 row_shr:2 row_mask:0xf bank_mask:0xf
	v_mov_b32_dpp v230, v73 row_shr:1 row_mask:0xf bank_mask:0xf
	v_mov_b32_dpp v231, v73 row_shr:2 row_mask:0xf bank_mask:0xf
	v_mov_b32_dpp v232, v74 row_shr:1 row_mask:0xf bank_mask:0xf
	v_mov_b32_dpp v233, v74 row_shr:2 row_mask:0xf bank_mask:0xf
	v_mov_b32_dpp v234, v75 row_shr:1 row_mask:0xf bank_mask:0xf
	v_mov_b32_dpp v235, v75 row_shr:2 row_mask:0xf bank_mask:0xf
	v_fma_f32 v236, v229, v136, v220
	v_fma_f32 v237, v231, v137, v221
	v_fma_f32 v238, v233, v138, v222
	v_fma_f32 v239, v235, v139, v223
	v_fmac_f32_e32 v236, v228, v152
	v_fmac_f32_e32 v237, v230, v153
	v_fmac_f32_e32 v238, v232, v154
	v_fmac_f32_e32 v239, v234, v155
	v_fmac_f32_e32 v236, v72, v168
	v_fmac_f32_e32 v237, v73, v169
	v_fmac_f32_e32 v238, v74, v170
	v_fmac_f32_e32 v239, v75, v171
	v_mov_b32_dpp v228, v80 row_ror:1 row_mask:0xf bank_mask:0xf
	v_mov_b32_dpp v229, v80 row_ror:2 row_mask:0xf bank_mask:0xf
	v_mov_b32_dpp v230, v81 row_ror:1 row_mask:0xf bank_mask:0xf
	v_mov_b32_dpp v231, v81 row_ror:2 row_mask:0xf bank_mask:0xf
	v_mov_b32_dpp v232, v82 row_ror:1 row_mask:0xf bank_mask:0xf
	v_mov_b32_dpp v233, v82 row_ror:2 row_mask:0xf bank_mask:0xf
	v_mov_b32_dpp v234, v83 row_ror:1 row_mask:0xf bank_mask:0xf
	v_mov_b32_dpp v235, v83 row_ror:2 row_mask:0xf bank_mask:0xf
	v_mov_b32_dpp v228, v64 row_shr:1 row_mask:0xf bank_mask:0xf
	v_mov_b32_dpp v229, v64 row_shr:2 row_mask:0xf bank_mask:0xf
	v_mov_b32_dpp v230, v65 row_shr:1 row_mask:0xf bank_mask:0xf
	v_mov_b32_dpp v231, v65 row_shr:2 row_mask:0xf bank_mask:0xf
	v_mov_b32_dpp v232, v66 row_shr:1 row_mask:0xf bank_mask:0xf
	v_mov_b32_dpp v233, v66 row_shr:2 row_mask:0xf bank_mask:0xf
	v_mov_b32_dpp v234, v67 row_shr:1 row_mask:0xf bank_mask:0xf
	v_mov_b32_dpp v235, v67 row_shr:2 row_mask:0xf bank_mask:0xf
	v_fma_f32 v240, v229, v140, v224
	v_fma_f32 v241, v231, v141, v225
	v_fma_f32 v242, v233, v142, v226
	v_fma_f32 v243, v235, v143, v227
	v_fmac_f32_e32 v240, v228, v156
	v_fmac_f32_e32 v241, v230, v157
	v_fmac_f32_e32 v242, v232, v158
	v_fmac_f32_e32 v243, v234, v159
	v_fmac_f32_e32 v240, v64, v204
	v_fmac_f32_e32 v241, v65, v205
	v_fmac_f32_e32 v242, v66, v206
	v_fmac_f32_e32 v243, v67, v207
	v_mul_f32_e32 v244, 0x3d372713, v236
	v_mul_f32_e32 v245, 0x3d372713, v237
	v_mul_f32_e32 v246, 0x3d372713, v238
	v_mul_f32_e32 v247, 0x3d372713, v239
	v_mul_f32_e32 v244, v236, v244
	v_mul_f32_e32 v245, v237, v245
	v_mul_f32_e32 v246, v238, v246
	v_mul_f32_e32 v247, v239, v247
	v_fma_f32 v244, v236, v244, v236
	v_fma_f32 v245, v237, v245, v237
	v_fma_f32 v246, v238, v246, v238
	v_fma_f32 v247, v239, v247, v239
	v_mul_f32_e32 v244, 0x3f4c422a, v244
	v_mul_f32_e32 v245, 0x3f4c422a, v245
	v_mul_f32_e32 v246, 0x3f4c422a, v246
	v_mul_f32_e32 v247, 0x3f4c422a, v247
	v_mul_f32_e32 v244, 0xc038aa3b, v244
	v_mul_f32_e32 v245, 0xc038aa3b, v245
	v_mul_f32_e32 v246, 0xc038aa3b, v246
	v_mul_f32_e32 v247, 0xc038aa3b, v247
	v_exp_f32_e32 v244, v244
	v_exp_f32_e32 v245, v245
	v_exp_f32_e32 v246, v246
	v_exp_f32_e32 v247, v247
	v_add_f32_e32 v244, 1.0, v244
	v_add_f32_e32 v245, 1.0, v245
	v_add_f32_e32 v246, 1.0, v246
	v_add_f32_e32 v247, 1.0, v247
	v_rcp_f32_e32 v244, v244
	v_rcp_f32_e32 v245, v245
	v_rcp_f32_e32 v246, v246
	v_rcp_f32_e32 v247, v247
	v_mul_f32_e32 v244, v236, v244
	v_mul_f32_e32 v245, v237, v245
	v_mul_f32_e32 v246, v238, v246
	v_mul_f32_e32 v247, v239, v247
	v_mul_f32_e32 v174, v240, v244
	v_mul_f32_e32 v175, v241, v245
	v_mul_f32_e32 v176, v242, v246
	v_mul_f32_e32 v177, v243, v247
	v_cvt_pk_bf16_f32 v180, v248, v249
	v_cvt_pk_bf16_f32 v181, v250, v251
	v_cvt_pk_bf16_f32 v182, v174, v175
	v_cvt_pk_bf16_f32 v183, v176, v177
.Lffn1e_store3:
	v_add_u32_e32 v252, 48, v218
	v_mad_i64_i32 v[216:217], vcc, v252, s79, v[190:191]
	v_cmp_gt_i32_e32 vcc, s58, v252
	s_nop 1
	s_and_saveexec_b64 s[10:11], vcc
	global_store_dwordx4 v[216:217], v[180:183], off sc1
	s_mov_b64 exec, s[10:11]
	s_add_i32 s6, s0, 2143
	s_mul_hi_u32 s7, s6, s59
	s_lshr_b32 s7, s7, 7
	s_mulk_i32 s7, 0x810
	s_sub_i32 s6, s6, s7
	s_cmp_lt_u32 s6, 17
	s_cbranch_scc1 .Lffn1e_slow4
	v_mov_b32_dpp v228, v76 row_ror:1 row_mask:0xf bank_mask:0xf
	v_mov_b32_dpp v229, v76 row_ror:2 row_mask:0xf bank_mask:0xf
	v_mov_b32_dpp v230, v77 row_ror:1 row_mask:0xf bank_mask:0xf
	v_mov_b32_dpp v231, v77 row_ror:2 row_mask:0xf bank_mask:0xf
	v_mov_b32_dpp v232, v78 row_ror:1 row_mask:0xf bank_mask:0xf
	v_mov_b32_dpp v233, v78 row_ror:2 row_mask:0xf bank_mask:0xf
	v_mov_b32_dpp v234, v79 row_ror:1 row_mask:0xf bank_mask:0xf
	v_mov_b32_dpp v235, v79 row_ror:2 row_mask:0xf bank_mask:0xf
	v_mov_b32_dpp v228, v60 row_shr:1 row_mask:0xf bank_mask:0xf
	v_mov_b32_dpp v229, v60 row_shr:2 row_mask:0xf bank_mask:0xf
	v_mov_b32_dpp v230, v61 row_shr:1 row_mask:0xf bank_mask:0xf
	v_mov_b32_dpp v231, v61 row_shr:2 row_mask:0xf bank_mask:0xf
	v_mov_b32_dpp v232, v62 row_shr:1 row_mask:0xf bank_mask:0xf
	v_mov_b32_dpp v233, v62 row_shr:2 row_mask:0xf bank_mask:0xf
	v_mov_b32_dpp v234, v63 row_shr:1 row_mask:0xf bank_mask:0xf
	v_mov_b32_dpp v235, v63 row_shr:2 row_mask:0xf bank_mask:0xf
	v_fma_f32 v236, v229, v128, v208
	v_fma_f32 v237, v231, v129, v209
	v_fma_f32 v238, v233, v130, v210
	v_fma_f32 v239, v235, v131, v211
	v_fmac_f32_e32 v236, v228, v144
	v_fmac_f32_e32 v237, v230, v145
	v_fmac_f32_e32 v238, v232, v146
	v_fmac_f32_e32 v239, v234, v147
	v_fmac_f32_e32 v236, v60, v160
	v_fmac_f32_e32 v237, v61, v161
	v_fmac_f32_e32 v238, v62, v162
	v_fmac_f32_e32 v239, v63, v163
	v_mov_b32_dpp v228, v68 row_ror:1 row_mask:0xf bank_mask:0xf
	v_mov_b32_dpp v229, v68 row_ror:2 row_mask:0xf bank_mask:0xf
	v_mov_b32_dpp v230, v69 row_ror:1 row_mask:0xf bank_mask:0xf
	v_mov_b32_dpp v231, v69 row_ror:2 row_mask:0xf bank_mask:0xf
	v_mov_b32_dpp v232, v70 row_ror:1 row_mask:0xf bank_mask:0xf
	v_mov_b32_dpp v233, v70 row_ror:2 row_mask:0xf bank_mask:0xf
	v_mov_b32_dpp v234, v71 row_ror:1 row_mask:0xf bank_mask:0xf
	v_mov_b32_dpp v235, v71 row_ror:2 row_mask:0xf bank_mask:0xf
	v_mov_b32_dpp v228, v52 row_shr:1 row_mask:0xf bank_mask:0xf
	v_mov_b32_dpp v229, v52 row_shr:2 row_mask:0xf bank_mask:0xf
	v_mov_b32_dpp v230, v53 row_shr:1 row_mask:0xf bank_mask:0xf
	v_mov_b32_dpp v231, v53 row_shr:2 row_mask:0xf bank_mask:0xf
	v_mov_b32_dpp v232, v54 row_shr:1 row_mask:0xf bank_mask:0xf
	v_mov_b32_dpp v233, v54 row_shr:2 row_mask:0xf bank_mask:0xf
	v_mov_b32_dpp v234, v55 row_shr:1 row_mask:0xf bank_mask:0xf
	v_mov_b32_dpp v235, v55 row_shr:2 row_mask:0xf bank_mask:0xf
	v_fma_f32 v240, v229, v132, v212
	v_fma_f32 v241, v231, v133, v213
	v_fma_f32 v242, v233, v134, v214
	v_fma_f32 v243, v235, v135, v215
	v_fmac_f32_e32 v240, v228, v148
	v_fmac_f32_e32 v241, v230, v149
	v_fmac_f32_e32 v242, v232, v150
	v_fmac_f32_e32 v243, v234, v151
	v_fmac_f32_e32 v240, v52, v164
	v_fmac_f32_e32 v241, v53, v165
	v_fmac_f32_e32 v242, v54, v166
	v_fmac_f32_e32 v243, v55, v167
	v_mul_f32_e32 v244, 0x3d372713, v236
	v_mul_f32_e32 v245, 0x3d372713, v237
	v_mul_f32_e32 v246, 0x3d372713, v238
	v_mul_f32_e32 v247, 0x3d372713, v239
	v_mul_f32_e32 v244, v236, v244
	v_mul_f32_e32 v245, v237, v245
	v_mul_f32_e32 v246, v238, v246
	v_mul_f32_e32 v247, v239, v247
	v_fma_f32 v244, v236, v244, v236
	v_fma_f32 v245, v237, v245, v237
	v_fma_f32 v246, v238, v246, v238
	v_fma_f32 v247, v239, v247, v239
	v_mul_f32_e32 v244, 0x3f4c422a, v244
	v_mul_f32_e32 v245, 0x3f4c422a, v245
	v_mul_f32_e32 v246, 0x3f4c422a, v246
	v_mul_f32_e32 v247, 0x3f4c422a, v247
	v_mul_f32_e32 v244, 0xc038aa3b, v244
	v_mul_f32_e32 v245, 0xc038aa3b, v245
	v_mul_f32_e32 v246, 0xc038aa3b, v246
	v_mul_f32_e32 v247, 0xc038aa3b, v247
	v_exp_f32_e32 v244, v244
	v_exp_f32_e32 v245, v245
	v_exp_f32_e32 v246, v246
	v_exp_f32_e32 v247, v247
	v_add_f32_e32 v244, 1.0, v244
	v_add_f32_e32 v245, 1.0, v245
	v_add_f32_e32 v246, 1.0, v246
	v_add_f32_e32 v247, 1.0, v247
	v_rcp_f32_e32 v244, v244
	v_rcp_f32_e32 v245, v245
	v_rcp_f32_e32 v246, v246
	v_rcp_f32_e32 v247, v247
	v_mul_f32_e32 v244, v236, v244
	v_mul_f32_e32 v245, v237, v245
	v_mul_f32_e32 v246, v238, v246
	v_mul_f32_e32 v247, v239, v247
	v_mul_f32_e32 v248, v240, v244
	v_mul_f32_e32 v249, v241, v245
	v_mul_f32_e32 v250, v242, v246
	v_mul_f32_e32 v251, v243, v247
	v_mov_b32_dpp v228, v72 row_ror:1 row_mask:0xf bank_mask:0xf
	v_mov_b32_dpp v229, v72 row_ror:2 row_mask:0xf bank_mask:0xf
	v_mov_b32_dpp v230, v73 row_ror:1 row_mask:0xf bank_mask:0xf
	v_mov_b32_dpp v231, v73 row_ror:2 row_mask:0xf bank_mask:0xf
	v_mov_b32_dpp v232, v74 row_ror:1 row_mask:0xf bank_mask:0xf
	v_mov_b32_dpp v233, v74 row_ror:2 row_mask:0xf bank_mask:0xf
	v_mov_b32_dpp v234, v75 row_ror:1 row_mask:0xf bank_mask:0xf
	v_mov_b32_dpp v235, v75 row_ror:2 row_mask:0xf bank_mask:0xf
	v_mov_b32_dpp v228, v56 row_shr:1 row_mask:0xf bank_mask:0xf
	v_mov_b32_dpp v229, v56 row_shr:2 row_mask:0xf bank_mask:0xf
	v_mov_b32_dpp v230, v57 row_shr:1 row_mask:0xf bank_mask:0xf
	v_mov_b32_dpp v231, v57 row_shr:2 row_mask:0xf bank_mask:0xf
	v_mov_b32_dpp v232, v58 row_shr:1 row_mask:0xf bank_mask:0xf
	v_mov_b32_dpp v233, v58 row_shr:2 row_mask:0xf bank_mask:0xf
	v_mov_b32_dpp v234, v59 row_shr:1 row_mask:0xf bank_mask:0xf
	v_mov_b32_dpp v235, v59 row_shr:2 row_mask:0xf bank_mask:0xf
	v_fma_f32 v236, v229, v136, v220
	v_fma_f32 v237, v231, v137, v221
	v_fma_f32 v238, v233, v138, v222
	v_fma_f32 v239, v235, v139, v223
	v_fmac_f32_e32 v236, v228, v152
	v_fmac_f32_e32 v237, v230, v153
	v_fmac_f32_e32 v238, v232, v154
	v_fmac_f32_e32 v239, v234, v155
	v_fmac_f32_e32 v236, v56, v168
	v_fmac_f32_e32 v237, v57, v169
	v_fmac_f32_e32 v238, v58, v170
	v_fmac_f32_e32 v239, v59, v171
	v_mov_b32_dpp v228, v64 row_ror:1 row_mask:0xf bank_mask:0xf
	v_mov_b32_dpp v229, v64 row_ror:2 row_mask:0xf bank_mask:0xf
	v_mov_b32_dpp v230, v65 row_ror:1 row_mask:0xf bank_mask:0xf
	v_mov_b32_dpp v231, v65 row_ror:2 row_mask:0xf bank_mask:0xf
	v_mov_b32_dpp v232, v66 row_ror:1 row_mask:0xf bank_mask:0xf
	v_mov_b32_dpp v233, v66 row_ror:2 row_mask:0xf bank_mask:0xf
	v_mov_b32_dpp v234, v67 row_ror:1 row_mask:0xf bank_mask:0xf
	v_mov_b32_dpp v235, v67 row_ror:2 row_mask:0xf bank_mask:0xf
	v_mov_b32_dpp v228, v48 row_shr:1 row_mask:0xf bank_mask:0xf
	v_mov_b32_dpp v229, v48 row_shr:2 row_mask:0xf bank_mask:0xf
	v_mov_b32_dpp v230, v49 row_shr:1 row_mask:0xf bank_mask:0xf
	v_mov_b32_dpp v231, v49 row_shr:2 row_mask:0xf bank_mask:0xf
	v_mov_b32_dpp v232, v50 row_shr:1 row_mask:0xf bank_mask:0xf
	v_mov_b32_dpp v233, v50 row_shr:2 row_mask:0xf bank_mask:0xf
	v_mov_b32_dpp v234, v51 row_shr:1 row_mask:0xf bank_mask:0xf
	v_mov_b32_dpp v235, v51 row_shr:2 row_mask:0xf bank_mask:0xf
	v_fma_f32 v240, v229, v140, v224
	v_fma_f32 v241, v231, v141, v225
	v_fma_f32 v242, v233, v142, v226
	v_fma_f32 v243, v235, v143, v227
	v_fmac_f32_e32 v240, v228, v156
	v_fmac_f32_e32 v241, v230, v157
	v_fmac_f32_e32 v242, v232, v158
	v_fmac_f32_e32 v243, v234, v159
	v_fmac_f32_e32 v240, v48, v204
	v_fmac_f32_e32 v241, v49, v205
	v_fmac_f32_e32 v242, v50, v206
	v_fmac_f32_e32 v243, v51, v207
	v_mul_f32_e32 v244, 0x3d372713, v236
	v_mul_f32_e32 v245, 0x3d372713, v237
	v_mul_f32_e32 v246, 0x3d372713, v238
	v_mul_f32_e32 v247, 0x3d372713, v239
	v_mul_f32_e32 v244, v236, v244
	v_mul_f32_e32 v245, v237, v245
	v_mul_f32_e32 v246, v238, v246
	v_mul_f32_e32 v247, v239, v247
	v_fma_f32 v244, v236, v244, v236
	v_fma_f32 v245, v237, v245, v237
	v_fma_f32 v246, v238, v246, v238
	v_fma_f32 v247, v239, v247, v239
	v_mul_f32_e32 v244, 0x3f4c422a, v244
	v_mul_f32_e32 v245, 0x3f4c422a, v245
	v_mul_f32_e32 v246, 0x3f4c422a, v246
	v_mul_f32_e32 v247, 0x3f4c422a, v247
	v_mul_f32_e32 v244, 0xc038aa3b, v244
	v_mul_f32_e32 v245, 0xc038aa3b, v245
	v_mul_f32_e32 v246, 0xc038aa3b, v246
	v_mul_f32_e32 v247, 0xc038aa3b, v247
	v_exp_f32_e32 v244, v244
	v_exp_f32_e32 v245, v245
	v_exp_f32_e32 v246, v246
	v_exp_f32_e32 v247, v247
	v_add_f32_e32 v244, 1.0, v244
	v_add_f32_e32 v245, 1.0, v245
	v_add_f32_e32 v246, 1.0, v246
	v_add_f32_e32 v247, 1.0, v247
	v_rcp_f32_e32 v244, v244
	v_rcp_f32_e32 v245, v245
	v_rcp_f32_e32 v246, v246
	v_rcp_f32_e32 v247, v247
	v_mul_f32_e32 v244, v236, v244
	v_mul_f32_e32 v245, v237, v245
	v_mul_f32_e32 v246, v238, v246
	v_mul_f32_e32 v247, v239, v247
	v_mul_f32_e32 v174, v240, v244
	v_mul_f32_e32 v175, v241, v245
	v_mul_f32_e32 v176, v242, v246
	v_mul_f32_e32 v177, v243, v247
	v_cvt_pk_bf16_f32 v180, v248, v249
	v_cvt_pk_bf16_f32 v181, v250, v251
	v_cvt_pk_bf16_f32 v182, v174, v175
	v_cvt_pk_bf16_f32 v183, v176, v177
.Lffn1e_store4:
	v_add_u32_e32 v252, 64, v218
	v_mad_i64_i32 v[216:217], vcc, v252, s79, v[190:191]
	v_cmp_gt_i32_e32 vcc, s58, v252
	s_nop 1
	s_and_saveexec_b64 s[10:11], vcc
	global_store_dwordx4 v[216:217], v[180:183], off sc1
	s_mov_b64 exec, s[10:11]
	s_add_i32 s6, s0, 2159
	s_mul_hi_u32 s7, s6, s59
	s_lshr_b32 s7, s7, 7
	s_mulk_i32 s7, 0x810
	s_sub_i32 s6, s6, s7
	s_cmp_lt_u32 s6, 17
	s_cbranch_scc1 .Lffn1e_slow5
	v_mov_b32_dpp v228, v60 row_ror:1 row_mask:0xf bank_mask:0xf
	v_mov_b32_dpp v229, v60 row_ror:2 row_mask:0xf bank_mask:0xf
	v_mov_b32_dpp v230, v61 row_ror:1 row_mask:0xf bank_mask:0xf
	v_mov_b32_dpp v231, v61 row_ror:2 row_mask:0xf bank_mask:0xf
	v_mov_b32_dpp v232, v62 row_ror:1 row_mask:0xf bank_mask:0xf
	v_mov_b32_dpp v233, v62 row_ror:2 row_mask:0xf bank_mask:0xf
	v_mov_b32_dpp v234, v63 row_ror:1 row_mask:0xf bank_mask:0xf
	v_mov_b32_dpp v235, v63 row_ror:2 row_mask:0xf bank_mask:0xf
	v_mov_b32_dpp v228, v44 row_shr:1 row_mask:0xf bank_mask:0xf
	v_mov_b32_dpp v229, v44 row_shr:2 row_mask:0xf bank_mask:0xf
	v_mov_b32_dpp v230, v45 row_shr:1 row_mask:0xf bank_mask:0xf
	v_mov_b32_dpp v231, v45 row_shr:2 row_mask:0xf bank_mask:0xf
	v_mov_b32_dpp v232, v46 row_shr:1 row_mask:0xf bank_mask:0xf
	v_mov_b32_dpp v233, v46 row_shr:2 row_mask:0xf bank_mask:0xf
	v_mov_b32_dpp v234, v47 row_shr:1 row_mask:0xf bank_mask:0xf
	v_mov_b32_dpp v235, v47 row_shr:2 row_mask:0xf bank_mask:0xf
	v_fma_f32 v236, v229, v128, v208
	v_fma_f32 v237, v231, v129, v209
	v_fma_f32 v238, v233, v130, v210
	v_fma_f32 v239, v235, v131, v211
	v_fmac_f32_e32 v236, v228, v144
	v_fmac_f32_e32 v237, v230, v145
	v_fmac_f32_e32 v238, v232, v146
	v_fmac_f32_e32 v239, v234, v147
	v_fmac_f32_e32 v236, v44, v160
	v_fmac_f32_e32 v237, v45, v161
	v_fmac_f32_e32 v238, v46, v162
	v_fmac_f32_e32 v239, v47, v163
	v_mov_b32_dpp v228, v52 row_ror:1 row_mask:0xf bank_mask:0xf
	v_mov_b32_dpp v229, v52 row_ror:2 row_mask:0xf bank_mask:0xf
	v_mov_b32_dpp v230, v53 row_ror:1 row_mask:0xf bank_mask:0xf
	v_mov_b32_dpp v231, v53 row_ror:2 row_mask:0xf bank_mask:0xf
	v_mov_b32_dpp v232, v54 row_ror:1 row_mask:0xf bank_mask:0xf
	v_mov_b32_dpp v233, v54 row_ror:2 row_mask:0xf bank_mask:0xf
	v_mov_b32_dpp v234, v55 row_ror:1 row_mask:0xf bank_mask:0xf
	v_mov_b32_dpp v235, v55 row_ror:2 row_mask:0xf bank_mask:0xf
	v_mov_b32_dpp v228, v36 row_shr:1 row_mask:0xf bank_mask:0xf
	v_mov_b32_dpp v229, v36 row_shr:2 row_mask:0xf bank_mask:0xf
	v_mov_b32_dpp v230, v37 row_shr:1 row_mask:0xf bank_mask:0xf
	v_mov_b32_dpp v231, v37 row_shr:2 row_mask:0xf bank_mask:0xf
	v_mov_b32_dpp v232, v38 row_shr:1 row_mask:0xf bank_mask:0xf
	v_mov_b32_dpp v233, v38 row_shr:2 row_mask:0xf bank_mask:0xf
	v_mov_b32_dpp v234, v39 row_shr:1 row_mask:0xf bank_mask:0xf
	v_mov_b32_dpp v235, v39 row_shr:2 row_mask:0xf bank_mask:0xf
	v_fma_f32 v240, v229, v132, v212
	v_fma_f32 v241, v231, v133, v213
	v_fma_f32 v242, v233, v134, v214
	v_fma_f32 v243, v235, v135, v215
	v_fmac_f32_e32 v240, v228, v148
	v_fmac_f32_e32 v241, v230, v149
	v_fmac_f32_e32 v242, v232, v150
	v_fmac_f32_e32 v243, v234, v151
	v_fmac_f32_e32 v240, v36, v164
	v_fmac_f32_e32 v241, v37, v165
	v_fmac_f32_e32 v242, v38, v166
	v_fmac_f32_e32 v243, v39, v167
	v_mul_f32_e32 v244, 0x3d372713, v236
	v_mul_f32_e32 v245, 0x3d372713, v237
	v_mul_f32_e32 v246, 0x3d372713, v238
	v_mul_f32_e32 v247, 0x3d372713, v239
	v_mul_f32_e32 v244, v236, v244
	v_mul_f32_e32 v245, v237, v245
	v_mul_f32_e32 v246, v238, v246
	v_mul_f32_e32 v247, v239, v247
	v_fma_f32 v244, v236, v244, v236
	v_fma_f32 v245, v237, v245, v237
	v_fma_f32 v246, v238, v246, v238
	v_fma_f32 v247, v239, v247, v239
	v_mul_f32_e32 v244, 0x3f4c422a, v244
	v_mul_f32_e32 v245, 0x3f4c422a, v245
	v_mul_f32_e32 v246, 0x3f4c422a, v246
	v_mul_f32_e32 v247, 0x3f4c422a, v247
	v_mul_f32_e32 v244, 0xc038aa3b, v244
	v_mul_f32_e32 v245, 0xc038aa3b, v245
	v_mul_f32_e32 v246, 0xc038aa3b, v246
	v_mul_f32_e32 v247, 0xc038aa3b, v247
	v_exp_f32_e32 v244, v244
	v_exp_f32_e32 v245, v245
	v_exp_f32_e32 v246, v246
	v_exp_f32_e32 v247, v247
	v_add_f32_e32 v244, 1.0, v244
	v_add_f32_e32 v245, 1.0, v245
	v_add_f32_e32 v246, 1.0, v246
	v_add_f32_e32 v247, 1.0, v247
	v_rcp_f32_e32 v244, v244
	v_rcp_f32_e32 v245, v245
	v_rcp_f32_e32 v246, v246
	v_rcp_f32_e32 v247, v247
	v_mul_f32_e32 v244, v236, v244
	v_mul_f32_e32 v245, v237, v245
	v_mul_f32_e32 v246, v238, v246
	v_mul_f32_e32 v247, v239, v247
	v_mul_f32_e32 v248, v240, v244
	v_mul_f32_e32 v249, v241, v245
	v_mul_f32_e32 v250, v242, v246
	v_mul_f32_e32 v251, v243, v247
	v_mov_b32_dpp v228, v56 row_ror:1 row_mask:0xf bank_mask:0xf
	v_mov_b32_dpp v229, v56 row_ror:2 row_mask:0xf bank_mask:0xf
	v_mov_b32_dpp v230, v57 row_ror:1 row_mask:0xf bank_mask:0xf
	v_mov_b32_dpp v231, v57 row_ror:2 row_mask:0xf bank_mask:0xf
	v_mov_b32_dpp v232, v58 row_ror:1 row_mask:0xf bank_mask:0xf
	v_mov_b32_dpp v233, v58 row_ror:2 row_mask:0xf bank_mask:0xf
	v_mov_b32_dpp v234, v59 row_ror:1 row_mask:0xf bank_mask:0xf
	v_mov_b32_dpp v235, v59 row_ror:2 row_mask:0xf bank_mask:0xf
	v_mov_b32_dpp v228, v40 row_shr:1 row_mask:0xf bank_mask:0xf
	v_mov_b32_dpp v229, v40 row_shr:2 row_mask:0xf bank_mask:0xf
	v_mov_b32_dpp v230, v41 row_shr:1 row_mask:0xf bank_mask:0xf
	v_mov_b32_dpp v231, v41 row_shr:2 row_mask:0xf bank_mask:0xf
	v_mov_b32_dpp v232, v42 row_shr:1 row_mask:0xf bank_mask:0xf
	v_mov_b32_dpp v233, v42 row_shr:2 row_mask:0xf bank_mask:0xf
	v_mov_b32_dpp v234, v43 row_shr:1 row_mask:0xf bank_mask:0xf
	v_mov_b32_dpp v235, v43 row_shr:2 row_mask:0xf bank_mask:0xf
	v_fma_f32 v236, v229, v136, v220
	v_fma_f32 v237, v231, v137, v221
	v_fma_f32 v238, v233, v138, v222
	v_fma_f32 v239, v235, v139, v223
	v_fmac_f32_e32 v236, v228, v152
	v_fmac_f32_e32 v237, v230, v153
	v_fmac_f32_e32 v238, v232, v154
	v_fmac_f32_e32 v239, v234, v155
	v_fmac_f32_e32 v236, v40, v168
	v_fmac_f32_e32 v237, v41, v169
	v_fmac_f32_e32 v238, v42, v170
	v_fmac_f32_e32 v239, v43, v171
	v_mov_b32_dpp v228, v48 row_ror:1 row_mask:0xf bank_mask:0xf
	v_mov_b32_dpp v229, v48 row_ror:2 row_mask:0xf bank_mask:0xf
	v_mov_b32_dpp v230, v49 row_ror:1 row_mask:0xf bank_mask:0xf
	v_mov_b32_dpp v231, v49 row_ror:2 row_mask:0xf bank_mask:0xf
	v_mov_b32_dpp v232, v50 row_ror:1 row_mask:0xf bank_mask:0xf
	v_mov_b32_dpp v233, v50 row_ror:2 row_mask:0xf bank_mask:0xf
	v_mov_b32_dpp v234, v51 row_ror:1 row_mask:0xf bank_mask:0xf
	v_mov_b32_dpp v235, v51 row_ror:2 row_mask:0xf bank_mask:0xf
	v_mov_b32_dpp v228, v32 row_shr:1 row_mask:0xf bank_mask:0xf
	v_mov_b32_dpp v229, v32 row_shr:2 row_mask:0xf bank_mask:0xf
	v_mov_b32_dpp v230, v33 row_shr:1 row_mask:0xf bank_mask:0xf
	v_mov_b32_dpp v231, v33 row_shr:2 row_mask:0xf bank_mask:0xf
	v_mov_b32_dpp v232, v34 row_shr:1 row_mask:0xf bank_mask:0xf
	v_mov_b32_dpp v233, v34 row_shr:2 row_mask:0xf bank_mask:0xf
	v_mov_b32_dpp v234, v35 row_shr:1 row_mask:0xf bank_mask:0xf
	v_mov_b32_dpp v235, v35 row_shr:2 row_mask:0xf bank_mask:0xf
	v_fma_f32 v240, v229, v140, v224
	v_fma_f32 v241, v231, v141, v225
	v_fma_f32 v242, v233, v142, v226
	v_fma_f32 v243, v235, v143, v227
	v_fmac_f32_e32 v240, v228, v156
	v_fmac_f32_e32 v241, v230, v157
	v_fmac_f32_e32 v242, v232, v158
	v_fmac_f32_e32 v243, v234, v159
	v_fmac_f32_e32 v240, v32, v204
	v_fmac_f32_e32 v241, v33, v205
	v_fmac_f32_e32 v242, v34, v206
	v_fmac_f32_e32 v243, v35, v207
	v_mul_f32_e32 v244, 0x3d372713, v236
	v_mul_f32_e32 v245, 0x3d372713, v237
	v_mul_f32_e32 v246, 0x3d372713, v238
	v_mul_f32_e32 v247, 0x3d372713, v239
	v_mul_f32_e32 v244, v236, v244
	v_mul_f32_e32 v245, v237, v245
	v_mul_f32_e32 v246, v238, v246
	v_mul_f32_e32 v247, v239, v247
	v_fma_f32 v244, v236, v244, v236
	v_fma_f32 v245, v237, v245, v237
	v_fma_f32 v246, v238, v246, v238
	v_fma_f32 v247, v239, v247, v239
	v_mul_f32_e32 v244, 0x3f4c422a, v244
	v_mul_f32_e32 v245, 0x3f4c422a, v245
	v_mul_f32_e32 v246, 0x3f4c422a, v246
	v_mul_f32_e32 v247, 0x3f4c422a, v247
	v_mul_f32_e32 v244, 0xc038aa3b, v244
	v_mul_f32_e32 v245, 0xc038aa3b, v245
	v_mul_f32_e32 v246, 0xc038aa3b, v246
	v_mul_f32_e32 v247, 0xc038aa3b, v247
	v_exp_f32_e32 v244, v244
	v_exp_f32_e32 v245, v245
	v_exp_f32_e32 v246, v246
	v_exp_f32_e32 v247, v247
	v_add_f32_e32 v244, 1.0, v244
	v_add_f32_e32 v245, 1.0, v245
	v_add_f32_e32 v246, 1.0, v246
	v_add_f32_e32 v247, 1.0, v247
	v_rcp_f32_e32 v244, v244
	v_rcp_f32_e32 v245, v245
	v_rcp_f32_e32 v246, v246
	v_rcp_f32_e32 v247, v247
	v_mul_f32_e32 v244, v236, v244
	v_mul_f32_e32 v245, v237, v245
	v_mul_f32_e32 v246, v238, v246
	v_mul_f32_e32 v247, v239, v247
	v_mul_f32_e32 v174, v240, v244
	v_mul_f32_e32 v175, v241, v245
	v_mul_f32_e32 v176, v242, v246
	v_mul_f32_e32 v177, v243, v247
	v_cvt_pk_bf16_f32 v180, v248, v249
	v_cvt_pk_bf16_f32 v181, v250, v251
	v_cvt_pk_bf16_f32 v182, v174, v175
	v_cvt_pk_bf16_f32 v183, v176, v177
.Lffn1e_store5:
	v_add_u32_e32 v252, 80, v218
	v_mad_i64_i32 v[216:217], vcc, v252, s79, v[190:191]
	v_cmp_gt_i32_e32 vcc, s58, v252
	s_nop 1
	s_and_saveexec_b64 s[10:11], vcc
	global_store_dwordx4 v[216:217], v[180:183], off sc1
	s_mov_b64 exec, s[10:11]
	s_add_i32 s6, s0, 2175
	s_mul_hi_u32 s7, s6, s59
	s_lshr_b32 s7, s7, 7
	s_mulk_i32 s7, 0x810
	s_sub_i32 s6, s6, s7
	s_cmp_lt_u32 s6, 17
	s_cbranch_scc1 .Lffn1e_slow6
	v_mov_b32_dpp v228, v44 row_ror:1 row_mask:0xf bank_mask:0xf
	v_mov_b32_dpp v229, v44 row_ror:2 row_mask:0xf bank_mask:0xf
	v_mov_b32_dpp v230, v45 row_ror:1 row_mask:0xf bank_mask:0xf
	v_mov_b32_dpp v231, v45 row_ror:2 row_mask:0xf bank_mask:0xf
	v_mov_b32_dpp v232, v46 row_ror:1 row_mask:0xf bank_mask:0xf
	v_mov_b32_dpp v233, v46 row_ror:2 row_mask:0xf bank_mask:0xf
	v_mov_b32_dpp v234, v47 row_ror:1 row_mask:0xf bank_mask:0xf
	v_mov_b32_dpp v235, v47 row_ror:2 row_mask:0xf bank_mask:0xf
	v_mov_b32_dpp v228, v28 row_shr:1 row_mask:0xf bank_mask:0xf
	v_mov_b32_dpp v229, v28 row_shr:2 row_mask:0xf bank_mask:0xf
	v_mov_b32_dpp v230, v29 row_shr:1 row_mask:0xf bank_mask:0xf
	v_mov_b32_dpp v231, v29 row_shr:2 row_mask:0xf bank_mask:0xf
	v_mov_b32_dpp v232, v30 row_shr:1 row_mask:0xf bank_mask:0xf
	v_mov_b32_dpp v233, v30 row_shr:2 row_mask:0xf bank_mask:0xf
	v_mov_b32_dpp v234, v31 row_shr:1 row_mask:0xf bank_mask:0xf
	v_mov_b32_dpp v235, v31 row_shr:2 row_mask:0xf bank_mask:0xf
	v_fma_f32 v236, v229, v128, v208
	v_fma_f32 v237, v231, v129, v209
	v_fma_f32 v238, v233, v130, v210
	v_fma_f32 v239, v235, v131, v211
	v_fmac_f32_e32 v236, v228, v144
	v_fmac_f32_e32 v237, v230, v145
	v_fmac_f32_e32 v238, v232, v146
	v_fmac_f32_e32 v239, v234, v147
	v_fmac_f32_e32 v236, v28, v160
	v_fmac_f32_e32 v237, v29, v161
	v_fmac_f32_e32 v238, v30, v162
	v_fmac_f32_e32 v239, v31, v163
	v_mov_b32_dpp v228, v36 row_ror:1 row_mask:0xf bank_mask:0xf
	v_mov_b32_dpp v229, v36 row_ror:2 row_mask:0xf bank_mask:0xf
	v_mov_b32_dpp v230, v37 row_ror:1 row_mask:0xf bank_mask:0xf
	v_mov_b32_dpp v231, v37 row_ror:2 row_mask:0xf bank_mask:0xf
	v_mov_b32_dpp v232, v38 row_ror:1 row_mask:0xf bank_mask:0xf
	v_mov_b32_dpp v233, v38 row_ror:2 row_mask:0xf bank_mask:0xf
	v_mov_b32_dpp v234, v39 row_ror:1 row_mask:0xf bank_mask:0xf
	v_mov_b32_dpp v235, v39 row_ror:2 row_mask:0xf bank_mask:0xf
	v_mov_b32_dpp v228, v20 row_shr:1 row_mask:0xf bank_mask:0xf
	v_mov_b32_dpp v229, v20 row_shr:2 row_mask:0xf bank_mask:0xf
	v_mov_b32_dpp v230, v21 row_shr:1 row_mask:0xf bank_mask:0xf
	v_mov_b32_dpp v231, v21 row_shr:2 row_mask:0xf bank_mask:0xf
	v_mov_b32_dpp v232, v22 row_shr:1 row_mask:0xf bank_mask:0xf
	v_mov_b32_dpp v233, v22 row_shr:2 row_mask:0xf bank_mask:0xf
	v_mov_b32_dpp v234, v23 row_shr:1 row_mask:0xf bank_mask:0xf
	v_mov_b32_dpp v235, v23 row_shr:2 row_mask:0xf bank_mask:0xf
	v_fma_f32 v240, v229, v132, v212
	v_fma_f32 v241, v231, v133, v213
	v_fma_f32 v242, v233, v134, v214
	v_fma_f32 v243, v235, v135, v215
	v_fmac_f32_e32 v240, v228, v148
	v_fmac_f32_e32 v241, v230, v149
	v_fmac_f32_e32 v242, v232, v150
	v_fmac_f32_e32 v243, v234, v151
	v_fmac_f32_e32 v240, v20, v164
	v_fmac_f32_e32 v241, v21, v165
	v_fmac_f32_e32 v242, v22, v166
	v_fmac_f32_e32 v243, v23, v167
	v_mul_f32_e32 v244, 0x3d372713, v236
	v_mul_f32_e32 v245, 0x3d372713, v237
	v_mul_f32_e32 v246, 0x3d372713, v238
	v_mul_f32_e32 v247, 0x3d372713, v239
	v_mul_f32_e32 v244, v236, v244
	v_mul_f32_e32 v245, v237, v245
	v_mul_f32_e32 v246, v238, v246
	v_mul_f32_e32 v247, v239, v247
	v_fma_f32 v244, v236, v244, v236
	v_fma_f32 v245, v237, v245, v237
	v_fma_f32 v246, v238, v246, v238
	v_fma_f32 v247, v239, v247, v239
	v_mul_f32_e32 v244, 0x3f4c422a, v244
	v_mul_f32_e32 v245, 0x3f4c422a, v245
	v_mul_f32_e32 v246, 0x3f4c422a, v246
	v_mul_f32_e32 v247, 0x3f4c422a, v247
	v_mul_f32_e32 v244, 0xc038aa3b, v244
	v_mul_f32_e32 v245, 0xc038aa3b, v245
	v_mul_f32_e32 v246, 0xc038aa3b, v246
	v_mul_f32_e32 v247, 0xc038aa3b, v247
	v_exp_f32_e32 v244, v244
	v_exp_f32_e32 v245, v245
	v_exp_f32_e32 v246, v246
	v_exp_f32_e32 v247, v247
	v_add_f32_e32 v244, 1.0, v244
	v_add_f32_e32 v245, 1.0, v245
	v_add_f32_e32 v246, 1.0, v246
	v_add_f32_e32 v247, 1.0, v247
	v_rcp_f32_e32 v244, v244
	v_rcp_f32_e32 v245, v245
	v_rcp_f32_e32 v246, v246
	v_rcp_f32_e32 v247, v247
	v_mul_f32_e32 v244, v236, v244
	v_mul_f32_e32 v245, v237, v245
	v_mul_f32_e32 v246, v238, v246
	v_mul_f32_e32 v247, v239, v247
	v_mul_f32_e32 v248, v240, v244
	v_mul_f32_e32 v249, v241, v245
	v_mul_f32_e32 v250, v242, v246
	v_mul_f32_e32 v251, v243, v247
	v_mov_b32_dpp v228, v40 row_ror:1 row_mask:0xf bank_mask:0xf
	v_mov_b32_dpp v229, v40 row_ror:2 row_mask:0xf bank_mask:0xf
	v_mov_b32_dpp v230, v41 row_ror:1 row_mask:0xf bank_mask:0xf
	v_mov_b32_dpp v231, v41 row_ror:2 row_mask:0xf bank_mask:0xf
	v_mov_b32_dpp v232, v42 row_ror:1 row_mask:0xf bank_mask:0xf
	v_mov_b32_dpp v233, v42 row_ror:2 row_mask:0xf bank_mask:0xf
	v_mov_b32_dpp v234, v43 row_ror:1 row_mask:0xf bank_mask:0xf
	v_mov_b32_dpp v235, v43 row_ror:2 row_mask:0xf bank_mask:0xf
	v_mov_b32_dpp v228, v24 row_shr:1 row_mask:0xf bank_mask:0xf
	v_mov_b32_dpp v229, v24 row_shr:2 row_mask:0xf bank_mask:0xf
	v_mov_b32_dpp v230, v25 row_shr:1 row_mask:0xf bank_mask:0xf
	v_mov_b32_dpp v231, v25 row_shr:2 row_mask:0xf bank_mask:0xf
	v_mov_b32_dpp v232, v26 row_shr:1 row_mask:0xf bank_mask:0xf
	v_mov_b32_dpp v233, v26 row_shr:2 row_mask:0xf bank_mask:0xf
	v_mov_b32_dpp v234, v27 row_shr:1 row_mask:0xf bank_mask:0xf
	v_mov_b32_dpp v235, v27 row_shr:2 row_mask:0xf bank_mask:0xf
	v_fma_f32 v236, v229, v136, v220
	v_fma_f32 v237, v231, v137, v221
	v_fma_f32 v238, v233, v138, v222
	v_fma_f32 v239, v235, v139, v223
	v_fmac_f32_e32 v236, v228, v152
	v_fmac_f32_e32 v237, v230, v153
	v_fmac_f32_e32 v238, v232, v154
	v_fmac_f32_e32 v239, v234, v155
	v_fmac_f32_e32 v236, v24, v168
	v_fmac_f32_e32 v237, v25, v169
	v_fmac_f32_e32 v238, v26, v170
	v_fmac_f32_e32 v239, v27, v171
	v_mov_b32_dpp v228, v32 row_ror:1 row_mask:0xf bank_mask:0xf
	v_mov_b32_dpp v229, v32 row_ror:2 row_mask:0xf bank_mask:0xf
	v_mov_b32_dpp v230, v33 row_ror:1 row_mask:0xf bank_mask:0xf
	v_mov_b32_dpp v231, v33 row_ror:2 row_mask:0xf bank_mask:0xf
	v_mov_b32_dpp v232, v34 row_ror:1 row_mask:0xf bank_mask:0xf
	v_mov_b32_dpp v233, v34 row_ror:2 row_mask:0xf bank_mask:0xf
	v_mov_b32_dpp v234, v35 row_ror:1 row_mask:0xf bank_mask:0xf
	v_mov_b32_dpp v235, v35 row_ror:2 row_mask:0xf bank_mask:0xf
	v_mov_b32_dpp v228, v16 row_shr:1 row_mask:0xf bank_mask:0xf
	v_mov_b32_dpp v229, v16 row_shr:2 row_mask:0xf bank_mask:0xf
	v_mov_b32_dpp v230, v17 row_shr:1 row_mask:0xf bank_mask:0xf
	v_mov_b32_dpp v231, v17 row_shr:2 row_mask:0xf bank_mask:0xf
	v_mov_b32_dpp v232, v18 row_shr:1 row_mask:0xf bank_mask:0xf
	v_mov_b32_dpp v233, v18 row_shr:2 row_mask:0xf bank_mask:0xf
	v_mov_b32_dpp v234, v19 row_shr:1 row_mask:0xf bank_mask:0xf
	v_mov_b32_dpp v235, v19 row_shr:2 row_mask:0xf bank_mask:0xf
	v_fma_f32 v240, v229, v140, v224
	v_fma_f32 v241, v231, v141, v225
	v_fma_f32 v242, v233, v142, v226
	v_fma_f32 v243, v235, v143, v227
	v_fmac_f32_e32 v240, v228, v156
	v_fmac_f32_e32 v241, v230, v157
	v_fmac_f32_e32 v242, v232, v158
	v_fmac_f32_e32 v243, v234, v159
	v_fmac_f32_e32 v240, v16, v204
	v_fmac_f32_e32 v241, v17, v205
	v_fmac_f32_e32 v242, v18, v206
	v_fmac_f32_e32 v243, v19, v207
	v_mul_f32_e32 v244, 0x3d372713, v236
	v_mul_f32_e32 v245, 0x3d372713, v237
	v_mul_f32_e32 v246, 0x3d372713, v238
	v_mul_f32_e32 v247, 0x3d372713, v239
	v_mul_f32_e32 v244, v236, v244
	v_mul_f32_e32 v245, v237, v245
	v_mul_f32_e32 v246, v238, v246
	v_mul_f32_e32 v247, v239, v247
	v_fma_f32 v244, v236, v244, v236
	v_fma_f32 v245, v237, v245, v237
	v_fma_f32 v246, v238, v246, v238
	v_fma_f32 v247, v239, v247, v239
	v_mul_f32_e32 v244, 0x3f4c422a, v244
	v_mul_f32_e32 v245, 0x3f4c422a, v245
	v_mul_f32_e32 v246, 0x3f4c422a, v246
	v_mul_f32_e32 v247, 0x3f4c422a, v247
	v_mul_f32_e32 v244, 0xc038aa3b, v244
	v_mul_f32_e32 v245, 0xc038aa3b, v245
	v_mul_f32_e32 v246, 0xc038aa3b, v246
	v_mul_f32_e32 v247, 0xc038aa3b, v247
	v_exp_f32_e32 v244, v244
	v_exp_f32_e32 v245, v245
	v_exp_f32_e32 v246, v246
	v_exp_f32_e32 v247, v247
	v_add_f32_e32 v244, 1.0, v244
	v_add_f32_e32 v245, 1.0, v245
	v_add_f32_e32 v246, 1.0, v246
	v_add_f32_e32 v247, 1.0, v247
	v_rcp_f32_e32 v244, v244
	v_rcp_f32_e32 v245, v245
	v_rcp_f32_e32 v246, v246
	v_rcp_f32_e32 v247, v247
	v_mul_f32_e32 v244, v236, v244
	v_mul_f32_e32 v245, v237, v245
	v_mul_f32_e32 v246, v238, v246
	v_mul_f32_e32 v247, v239, v247
	v_mul_f32_e32 v174, v240, v244
	v_mul_f32_e32 v175, v241, v245
	v_mul_f32_e32 v176, v242, v246
	v_mul_f32_e32 v177, v243, v247
	v_cvt_pk_bf16_f32 v180, v248, v249
	v_cvt_pk_bf16_f32 v181, v250, v251
	v_cvt_pk_bf16_f32 v182, v174, v175
	v_cvt_pk_bf16_f32 v183, v176, v177
.Lffn1e_store6:
	v_add_u32_e32 v252, 96, v218
	v_mad_i64_i32 v[216:217], vcc, v252, s79, v[190:191]
	v_cmp_gt_i32_e32 vcc, s58, v252
	s_nop 1
	s_and_saveexec_b64 s[10:11], vcc
	global_store_dwordx4 v[216:217], v[180:183], off sc1
	s_mov_b64 exec, s[10:11]
	s_add_i32 s6, s0, 2191
	s_mul_hi_u32 s7, s6, s59
	s_lshr_b32 s7, s7, 7
	s_mulk_i32 s7, 0x810
	s_sub_i32 s6, s6, s7
	s_cmp_lt_u32 s6, 17
	s_cbranch_scc1 .Lffn1e_slow7
	v_mov_b32_dpp v228, v28 row_ror:1 row_mask:0xf bank_mask:0xf
	v_mov_b32_dpp v229, v28 row_ror:2 row_mask:0xf bank_mask:0xf
	v_mov_b32_dpp v230, v29 row_ror:1 row_mask:0xf bank_mask:0xf
	v_mov_b32_dpp v231, v29 row_ror:2 row_mask:0xf bank_mask:0xf
	v_mov_b32_dpp v232, v30 row_ror:1 row_mask:0xf bank_mask:0xf
	v_mov_b32_dpp v233, v30 row_ror:2 row_mask:0xf bank_mask:0xf
	v_mov_b32_dpp v234, v31 row_ror:1 row_mask:0xf bank_mask:0xf
	v_mov_b32_dpp v235, v31 row_ror:2 row_mask:0xf bank_mask:0xf
	v_mov_b32_dpp v228, v4 row_shr:1 row_mask:0xf bank_mask:0xf
	v_mov_b32_dpp v229, v4 row_shr:2 row_mask:0xf bank_mask:0xf
	v_mov_b32_dpp v230, v5 row_shr:1 row_mask:0xf bank_mask:0xf
	v_mov_b32_dpp v231, v5 row_shr:2 row_mask:0xf bank_mask:0xf
	v_mov_b32_dpp v232, v6 row_shr:1 row_mask:0xf bank_mask:0xf
	v_mov_b32_dpp v233, v6 row_shr:2 row_mask:0xf bank_mask:0xf
	v_mov_b32_dpp v234, v7 row_shr:1 row_mask:0xf bank_mask:0xf
	v_mov_b32_dpp v235, v7 row_shr:2 row_mask:0xf bank_mask:0xf
	v_fma_f32 v236, v229, v128, v208
	v_fma_f32 v237, v231, v129, v209
	v_fma_f32 v238, v233, v130, v210
	v_fma_f32 v239, v235, v131, v211
	v_fmac_f32_e32 v236, v228, v144
	v_fmac_f32_e32 v237, v230, v145
	v_fmac_f32_e32 v238, v232, v146
	v_fmac_f32_e32 v239, v234, v147
	v_fmac_f32_e32 v236, v4, v160
	v_fmac_f32_e32 v237, v5, v161
	v_fmac_f32_e32 v238, v6, v162
	v_fmac_f32_e32 v239, v7, v163
	v_mov_b32_dpp v228, v20 row_ror:1 row_mask:0xf bank_mask:0xf
	v_mov_b32_dpp v229, v20 row_ror:2 row_mask:0xf bank_mask:0xf
	v_mov_b32_dpp v230, v21 row_ror:1 row_mask:0xf bank_mask:0xf
	v_mov_b32_dpp v231, v21 row_ror:2 row_mask:0xf bank_mask:0xf
	v_mov_b32_dpp v232, v22 row_ror:1 row_mask:0xf bank_mask:0xf
	v_mov_b32_dpp v233, v22 row_ror:2 row_mask:0xf bank_mask:0xf
	v_mov_b32_dpp v234, v23 row_ror:1 row_mask:0xf bank_mask:0xf
	v_mov_b32_dpp v235, v23 row_ror:2 row_mask:0xf bank_mask:0xf
	v_mov_b32_dpp v228, v8 row_shr:1 row_mask:0xf bank_mask:0xf
	v_mov_b32_dpp v229, v8 row_shr:2 row_mask:0xf bank_mask:0xf
	v_mov_b32_dpp v230, v9 row_shr:1 row_mask:0xf bank_mask:0xf
	v_mov_b32_dpp v231, v9 row_shr:2 row_mask:0xf bank_mask:0xf
	v_mov_b32_dpp v232, v10 row_shr:1 row_mask:0xf bank_mask:0xf
	v_mov_b32_dpp v233, v10 row_shr:2 row_mask:0xf bank_mask:0xf
	v_mov_b32_dpp v234, v11 row_shr:1 row_mask:0xf bank_mask:0xf
	v_mov_b32_dpp v235, v11 row_shr:2 row_mask:0xf bank_mask:0xf
	v_fma_f32 v240, v229, v132, v212
	v_fma_f32 v241, v231, v133, v213
	v_fma_f32 v242, v233, v134, v214
	v_fma_f32 v243, v235, v135, v215
	v_fmac_f32_e32 v240, v228, v148
	v_fmac_f32_e32 v241, v230, v149
	v_fmac_f32_e32 v242, v232, v150
	v_fmac_f32_e32 v243, v234, v151
	v_fmac_f32_e32 v240, v8, v164
	v_fmac_f32_e32 v241, v9, v165
	v_fmac_f32_e32 v242, v10, v166
	v_fmac_f32_e32 v243, v11, v167
	v_mul_f32_e32 v244, 0x3d372713, v236
	v_mul_f32_e32 v245, 0x3d372713, v237
	v_mul_f32_e32 v246, 0x3d372713, v238
	v_mul_f32_e32 v247, 0x3d372713, v239
	v_mul_f32_e32 v244, v236, v244
	v_mul_f32_e32 v245, v237, v245
	v_mul_f32_e32 v246, v238, v246
	v_mul_f32_e32 v247, v239, v247
	v_fma_f32 v244, v236, v244, v236
	v_fma_f32 v245, v237, v245, v237
	v_fma_f32 v246, v238, v246, v238
	v_fma_f32 v247, v239, v247, v239
	v_mul_f32_e32 v244, 0x3f4c422a, v244
	v_mul_f32_e32 v245, 0x3f4c422a, v245
	v_mul_f32_e32 v246, 0x3f4c422a, v246
	v_mul_f32_e32 v247, 0x3f4c422a, v247
	v_mul_f32_e32 v244, 0xc038aa3b, v244
	v_mul_f32_e32 v245, 0xc038aa3b, v245
	v_mul_f32_e32 v246, 0xc038aa3b, v246
	v_mul_f32_e32 v247, 0xc038aa3b, v247
	v_exp_f32_e32 v244, v244
	v_exp_f32_e32 v245, v245
	v_exp_f32_e32 v246, v246
	v_exp_f32_e32 v247, v247
	v_add_f32_e32 v244, 1.0, v244
	v_add_f32_e32 v245, 1.0, v245
	v_add_f32_e32 v246, 1.0, v246
	v_add_f32_e32 v247, 1.0, v247
	v_rcp_f32_e32 v244, v244
	v_rcp_f32_e32 v245, v245
	v_rcp_f32_e32 v246, v246
	v_rcp_f32_e32 v247, v247
	v_mul_f32_e32 v244, v236, v244
	v_mul_f32_e32 v245, v237, v245
	v_mul_f32_e32 v246, v238, v246
	v_mul_f32_e32 v247, v239, v247
	v_mul_f32_e32 v248, v240, v244
	v_mul_f32_e32 v249, v241, v245
	v_mul_f32_e32 v250, v242, v246
	v_mul_f32_e32 v251, v243, v247
	v_mov_b32_dpp v228, v24 row_ror:1 row_mask:0xf bank_mask:0xf
	v_mov_b32_dpp v229, v24 row_ror:2 row_mask:0xf bank_mask:0xf
	v_mov_b32_dpp v230, v25 row_ror:1 row_mask:0xf bank_mask:0xf
	v_mov_b32_dpp v231, v25 row_ror:2 row_mask:0xf bank_mask:0xf
	v_mov_b32_dpp v232, v26 row_ror:1 row_mask:0xf bank_mask:0xf
	v_mov_b32_dpp v233, v26 row_ror:2 row_mask:0xf bank_mask:0xf
	v_mov_b32_dpp v234, v27 row_ror:1 row_mask:0xf bank_mask:0xf
	v_mov_b32_dpp v235, v27 row_ror:2 row_mask:0xf bank_mask:0xf
	v_mov_b32_dpp v228, v12 row_shr:1 row_mask:0xf bank_mask:0xf
	v_mov_b32_dpp v229, v12 row_shr:2 row_mask:0xf bank_mask:0xf
	v_mov_b32_dpp v230, v13 row_shr:1 row_mask:0xf bank_mask:0xf
	v_mov_b32_dpp v231, v13 row_shr:2 row_mask:0xf bank_mask:0xf
	v_mov_b32_dpp v232, v14 row_shr:1 row_mask:0xf bank_mask:0xf
	v_mov_b32_dpp v233, v14 row_shr:2 row_mask:0xf bank_mask:0xf
	v_mov_b32_dpp v234, v15 row_shr:1 row_mask:0xf bank_mask:0xf
	v_mov_b32_dpp v235, v15 row_shr:2 row_mask:0xf bank_mask:0xf
	v_fma_f32 v236, v229, v136, v220
	v_fma_f32 v237, v231, v137, v221
	v_fma_f32 v238, v233, v138, v222
	v_fma_f32 v239, v235, v139, v223
	v_fmac_f32_e32 v236, v228, v152
	v_fmac_f32_e32 v237, v230, v153
	v_fmac_f32_e32 v238, v232, v154
	v_fmac_f32_e32 v239, v234, v155
	v_fmac_f32_e32 v236, v12, v168
	v_fmac_f32_e32 v237, v13, v169
	v_fmac_f32_e32 v238, v14, v170
	v_fmac_f32_e32 v239, v15, v171
	v_mov_b32_dpp v228, v16 row_ror:1 row_mask:0xf bank_mask:0xf
	v_mov_b32_dpp v229, v16 row_ror:2 row_mask:0xf bank_mask:0xf
	v_mov_b32_dpp v230, v17 row_ror:1 row_mask:0xf bank_mask:0xf
	v_mov_b32_dpp v231, v17 row_ror:2 row_mask:0xf bank_mask:0xf
	v_mov_b32_dpp v232, v18 row_ror:1 row_mask:0xf bank_mask:0xf
	v_mov_b32_dpp v233, v18 row_ror:2 row_mask:0xf bank_mask:0xf
	v_mov_b32_dpp v234, v19 row_ror:1 row_mask:0xf bank_mask:0xf
	v_mov_b32_dpp v235, v19 row_ror:2 row_mask:0xf bank_mask:0xf
	v_mov_b32_dpp v228, v0 row_shr:1 row_mask:0xf bank_mask:0xf
	v_mov_b32_dpp v229, v0 row_shr:2 row_mask:0xf bank_mask:0xf
	v_mov_b32_dpp v230, v1 row_shr:1 row_mask:0xf bank_mask:0xf
	v_mov_b32_dpp v231, v1 row_shr:2 row_mask:0xf bank_mask:0xf
	v_mov_b32_dpp v232, v2 row_shr:1 row_mask:0xf bank_mask:0xf
	v_mov_b32_dpp v233, v2 row_shr:2 row_mask:0xf bank_mask:0xf
	v_mov_b32_dpp v234, v3 row_shr:1 row_mask:0xf bank_mask:0xf
	v_mov_b32_dpp v235, v3 row_shr:2 row_mask:0xf bank_mask:0xf
	v_fma_f32 v240, v229, v140, v224
	v_fma_f32 v241, v231, v141, v225
	v_fma_f32 v242, v233, v142, v226
	v_fma_f32 v243, v235, v143, v227
	v_fmac_f32_e32 v240, v228, v156
	v_fmac_f32_e32 v241, v230, v157
	v_fmac_f32_e32 v242, v232, v158
	v_fmac_f32_e32 v243, v234, v159
	v_fmac_f32_e32 v240, v0, v204
	v_fmac_f32_e32 v241, v1, v205
	v_fmac_f32_e32 v242, v2, v206
	v_fmac_f32_e32 v243, v3, v207
	v_mul_f32_e32 v244, 0x3d372713, v236
	v_mul_f32_e32 v245, 0x3d372713, v237
	v_mul_f32_e32 v246, 0x3d372713, v238
	v_mul_f32_e32 v247, 0x3d372713, v239
	v_mul_f32_e32 v244, v236, v244
	v_mul_f32_e32 v245, v237, v245
	v_mul_f32_e32 v246, v238, v246
	v_mul_f32_e32 v247, v239, v247
	v_fma_f32 v244, v236, v244, v236
	v_fma_f32 v245, v237, v245, v237
	v_fma_f32 v246, v238, v246, v238
	v_fma_f32 v247, v239, v247, v239
	v_mul_f32_e32 v244, 0x3f4c422a, v244
	v_mul_f32_e32 v245, 0x3f4c422a, v245
	v_mul_f32_e32 v246, 0x3f4c422a, v246
	v_mul_f32_e32 v247, 0x3f4c422a, v247
	v_mul_f32_e32 v244, 0xc038aa3b, v244
	v_mul_f32_e32 v245, 0xc038aa3b, v245
	v_mul_f32_e32 v246, 0xc038aa3b, v246
	v_mul_f32_e32 v247, 0xc038aa3b, v247
	v_exp_f32_e32 v244, v244
	v_exp_f32_e32 v245, v245
	v_exp_f32_e32 v246, v246
	v_exp_f32_e32 v247, v247
	v_add_f32_e32 v244, 1.0, v244
	v_add_f32_e32 v245, 1.0, v245
	v_add_f32_e32 v246, 1.0, v246
	v_add_f32_e32 v247, 1.0, v247
	v_rcp_f32_e32 v244, v244
	v_rcp_f32_e32 v245, v245
	v_rcp_f32_e32 v246, v246
	v_rcp_f32_e32 v247, v247
	v_mul_f32_e32 v244, v236, v244
	v_mul_f32_e32 v245, v237, v245
	v_mul_f32_e32 v246, v238, v246
	v_mul_f32_e32 v247, v239, v247
	v_mul_f32_e32 v174, v240, v244
	v_mul_f32_e32 v175, v241, v245
	v_mul_f32_e32 v176, v242, v246
	v_mul_f32_e32 v177, v243, v247
	v_cvt_pk_bf16_f32 v180, v248, v249
	v_cvt_pk_bf16_f32 v181, v250, v251
	v_cvt_pk_bf16_f32 v182, v174, v175
	v_cvt_pk_bf16_f32 v183, v176, v177
.Lffn1e_store7:
	v_add_u32_e32 v252, 112, v218
	v_mad_i64_i32 v[216:217], vcc, v252, s79, v[190:191]
	v_cmp_gt_i32_e32 vcc, s58, v252
	s_nop 1
	s_and_saveexec_b64 s[10:11], vcc
	global_store_dwordx4 v[216:217], v[180:183], off sc1
	s_mov_b64 exec, s[10:11]
	s_branch .Lffn1e_done
.Lffn1e_slow0:
	v_add_u32_e32 v189, 2064, v218
	v_mul_hi_u32 v203, v189, s59
	v_lshrrev_b32_e32 v203, 7, v203
	v_mul_u32_u24_e32 v203, 0x810, v203
	v_sub_u32_e32 v189, v189, v203
	v_cmp_lt_u32_e32 vcc, 0, v189
	v_cmp_lt_u32_e64 s[8:9], 1, v189
	s_nop 1
	v_mov_b32_dpp v228, v124 row_shr:1 row_mask:0xf bank_mask:0xf bound_ctrl:1
	v_mov_b32_dpp v229, v124 row_shr:2 row_mask:0xf bank_mask:0xf bound_ctrl:1
	v_mov_b32_dpp v230, v125 row_shr:1 row_mask:0xf bank_mask:0xf bound_ctrl:1
	v_mov_b32_dpp v231, v125 row_shr:2 row_mask:0xf bank_mask:0xf bound_ctrl:1
	v_mov_b32_dpp v232, v126 row_shr:1 row_mask:0xf bank_mask:0xf bound_ctrl:1
	v_mov_b32_dpp v233, v126 row_shr:2 row_mask:0xf bank_mask:0xf bound_ctrl:1
	v_mov_b32_dpp v234, v127 row_shr:1 row_mask:0xf bank_mask:0xf bound_ctrl:1
	v_mov_b32_dpp v235, v127 row_shr:2 row_mask:0xf bank_mask:0xf bound_ctrl:1
	v_cndmask_b32_e64 v228, 0, v228, vcc
	v_cndmask_b32_e64 v229, 0, v229, s[8:9]
	v_cndmask_b32_e64 v230, 0, v230, vcc
	v_cndmask_b32_e64 v231, 0, v231, s[8:9]
	v_cndmask_b32_e64 v232, 0, v232, vcc
	v_cndmask_b32_e64 v233, 0, v233, s[8:9]
	v_cndmask_b32_e64 v234, 0, v234, vcc
	v_cndmask_b32_e64 v235, 0, v235, s[8:9]
	v_fma_f32 v236, v229, v128, v208
	v_fma_f32 v237, v231, v129, v209
	v_fma_f32 v238, v233, v130, v210
	v_fma_f32 v239, v235, v131, v211
	v_fmac_f32_e32 v236, v228, v144
	v_fmac_f32_e32 v237, v230, v145
	v_fmac_f32_e32 v238, v232, v146
	v_fmac_f32_e32 v239, v234, v147
	v_fmac_f32_e32 v236, v124, v160
	v_fmac_f32_e32 v237, v125, v161
	v_fmac_f32_e32 v238, v126, v162
	v_fmac_f32_e32 v239, v127, v163
	v_mov_b32_dpp v228, v116 row_shr:1 row_mask:0xf bank_mask:0xf bound_ctrl:1
	v_mov_b32_dpp v229, v116 row_shr:2 row_mask:0xf bank_mask:0xf bound_ctrl:1
	v_mov_b32_dpp v230, v117 row_shr:1 row_mask:0xf bank_mask:0xf bound_ctrl:1
	v_mov_b32_dpp v231, v117 row_shr:2 row_mask:0xf bank_mask:0xf bound_ctrl:1
	v_mov_b32_dpp v232, v118 row_shr:1 row_mask:0xf bank_mask:0xf bound_ctrl:1
	v_mov_b32_dpp v233, v118 row_shr:2 row_mask:0xf bank_mask:0xf bound_ctrl:1
	v_mov_b32_dpp v234, v119 row_shr:1 row_mask:0xf bank_mask:0xf bound_ctrl:1
	v_mov_b32_dpp v235, v119 row_shr:2 row_mask:0xf bank_mask:0xf bound_ctrl:1
	v_cndmask_b32_e64 v228, 0, v228, vcc
	v_cndmask_b32_e64 v229, 0, v229, s[8:9]
	v_cndmask_b32_e64 v230, 0, v230, vcc
	v_cndmask_b32_e64 v231, 0, v231, s[8:9]
	v_cndmask_b32_e64 v232, 0, v232, vcc
	v_cndmask_b32_e64 v233, 0, v233, s[8:9]
	v_cndmask_b32_e64 v234, 0, v234, vcc
	v_cndmask_b32_e64 v235, 0, v235, s[8:9]
	v_fma_f32 v240, v229, v132, v212
	v_fma_f32 v241, v231, v133, v213
	v_fma_f32 v242, v233, v134, v214
	v_fma_f32 v243, v235, v135, v215
	v_fmac_f32_e32 v240, v228, v148
	v_fmac_f32_e32 v241, v230, v149
	v_fmac_f32_e32 v242, v232, v150
	v_fmac_f32_e32 v243, v234, v151
	v_fmac_f32_e32 v240, v116, v164
	v_fmac_f32_e32 v241, v117, v165
	v_fmac_f32_e32 v242, v118, v166
	v_fmac_f32_e32 v243, v119, v167
	v_mul_f32_e32 v244, 0x3d372713, v236
	v_mul_f32_e32 v245, 0x3d372713, v237
	v_mul_f32_e32 v246, 0x3d372713, v238
	v_mul_f32_e32 v247, 0x3d372713, v239
	v_mul_f32_e32 v244, v236, v244
	v_mul_f32_e32 v245, v237, v245
	v_mul_f32_e32 v246, v238, v246
	v_mul_f32_e32 v247, v239, v247
	v_fma_f32 v244, v236, v244, v236
	v_fma_f32 v245, v237, v245, v237
	v_fma_f32 v246, v238, v246, v238
	v_fma_f32 v247, v239, v247, v239
	v_mul_f32_e32 v244, 0x3f4c422a, v244
	v_mul_f32_e32 v245, 0x3f4c422a, v245
	v_mul_f32_e32 v246, 0x3f4c422a, v246
	v_mul_f32_e32 v247, 0x3f4c422a, v247
	v_mul_f32_e32 v244, 0xc038aa3b, v244
	v_mul_f32_e32 v245, 0xc038aa3b, v245
	v_mul_f32_e32 v246, 0xc038aa3b, v246
	v_mul_f32_e32 v247, 0xc038aa3b, v247
	v_exp_f32_e32 v244, v244
	v_exp_f32_e32 v245, v245
	v_exp_f32_e32 v246, v246
	v_exp_f32_e32 v247, v247
	v_add_f32_e32 v244, 1.0, v244
	v_add_f32_e32 v245, 1.0, v245
	v_add_f32_e32 v246, 1.0, v246
	v_add_f32_e32 v247, 1.0, v247
	v_rcp_f32_e32 v244, v244
	v_rcp_f32_e32 v245, v245
	v_rcp_f32_e32 v246, v246
	v_rcp_f32_e32 v247, v247
	v_mul_f32_e32 v244, v236, v244
	v_mul_f32_e32 v245, v237, v245
	v_mul_f32_e32 v246, v238, v246
	v_mul_f32_e32 v247, v239, v247
	v_mul_f32_e32 v248, v240, v244
	v_mul_f32_e32 v249, v241, v245
	v_mul_f32_e32 v250, v242, v246
	v_mul_f32_e32 v251, v243, v247
	v_mov_b32_dpp v228, v120 row_shr:1 row_mask:0xf bank_mask:0xf bound_ctrl:1
	v_mov_b32_dpp v229, v120 row_shr:2 row_mask:0xf bank_mask:0xf bound_ctrl:1
	v_mov_b32_dpp v230, v121 row_shr:1 row_mask:0xf bank_mask:0xf bound_ctrl:1
	v_mov_b32_dpp v231, v121 row_shr:2 row_mask:0xf bank_mask:0xf bound_ctrl:1
	v_mov_b32_dpp v232, v122 row_shr:1 row_mask:0xf bank_mask:0xf bound_ctrl:1
	v_mov_b32_dpp v233, v122 row_shr:2 row_mask:0xf bank_mask:0xf bound_ctrl:1
	v_mov_b32_dpp v234, v123 row_shr:1 row_mask:0xf bank_mask:0xf bound_ctrl:1
	v_mov_b32_dpp v235, v123 row_shr:2 row_mask:0xf bank_mask:0xf bound_ctrl:1
	v_cndmask_b32_e64 v228, 0, v228, vcc
	v_cndmask_b32_e64 v229, 0, v229, s[8:9]
	v_cndmask_b32_e64 v230, 0, v230, vcc
	v_cndmask_b32_e64 v231, 0, v231, s[8:9]
	v_cndmask_b32_e64 v232, 0, v232, vcc
	v_cndmask_b32_e64 v233, 0, v233, s[8:9]
	v_cndmask_b32_e64 v234, 0, v234, vcc
	v_cndmask_b32_e64 v235, 0, v235, s[8:9]
	v_fma_f32 v236, v229, v136, v220
	v_fma_f32 v237, v231, v137, v221
	v_fma_f32 v238, v233, v138, v222
	v_fma_f32 v239, v235, v139, v223
	v_fmac_f32_e32 v236, v228, v152
	v_fmac_f32_e32 v237, v230, v153
	v_fmac_f32_e32 v238, v232, v154
	v_fmac_f32_e32 v239, v234, v155
	v_fmac_f32_e32 v236, v120, v168
	v_fmac_f32_e32 v237, v121, v169
	v_fmac_f32_e32 v238, v122, v170
	v_fmac_f32_e32 v239, v123, v171
	v_mov_b32_dpp v228, v112 row_shr:1 row_mask:0xf bank_mask:0xf bound_ctrl:1
	v_mov_b32_dpp v229, v112 row_shr:2 row_mask:0xf bank_mask:0xf bound_ctrl:1
	v_mov_b32_dpp v230, v113 row_shr:1 row_mask:0xf bank_mask:0xf bound_ctrl:1
	v_mov_b32_dpp v231, v113 row_shr:2 row_mask:0xf bank_mask:0xf bound_ctrl:1
	v_mov_b32_dpp v232, v114 row_shr:1 row_mask:0xf bank_mask:0xf bound_ctrl:1
	v_mov_b32_dpp v233, v114 row_shr:2 row_mask:0xf bank_mask:0xf bound_ctrl:1
	v_mov_b32_dpp v234, v115 row_shr:1 row_mask:0xf bank_mask:0xf bound_ctrl:1
	v_mov_b32_dpp v235, v115 row_shr:2 row_mask:0xf bank_mask:0xf bound_ctrl:1
	v_cndmask_b32_e64 v228, 0, v228, vcc
	v_cndmask_b32_e64 v229, 0, v229, s[8:9]
	v_cndmask_b32_e64 v230, 0, v230, vcc
	v_cndmask_b32_e64 v231, 0, v231, s[8:9]
	v_cndmask_b32_e64 v232, 0, v232, vcc
	v_cndmask_b32_e64 v233, 0, v233, s[8:9]
	v_cndmask_b32_e64 v234, 0, v234, vcc
	v_cndmask_b32_e64 v235, 0, v235, s[8:9]
	v_fma_f32 v240, v229, v140, v224
	v_fma_f32 v241, v231, v141, v225
	v_fma_f32 v242, v233, v142, v226
	v_fma_f32 v243, v235, v143, v227
	v_fmac_f32_e32 v240, v228, v156
	v_fmac_f32_e32 v241, v230, v157
	v_fmac_f32_e32 v242, v232, v158
	v_fmac_f32_e32 v243, v234, v159
	v_fmac_f32_e32 v240, v112, v204
	v_fmac_f32_e32 v241, v113, v205
	v_fmac_f32_e32 v242, v114, v206
	v_fmac_f32_e32 v243, v115, v207
	v_mul_f32_e32 v244, 0x3d372713, v236
	v_mul_f32_e32 v245, 0x3d372713, v237
	v_mul_f32_e32 v246, 0x3d372713, v238
	v_mul_f32_e32 v247, 0x3d372713, v239
	v_mul_f32_e32 v244, v236, v244
	v_mul_f32_e32 v245, v237, v245
	v_mul_f32_e32 v246, v238, v246
	v_mul_f32_e32 v247, v239, v247
	v_fma_f32 v244, v236, v244, v236
	v_fma_f32 v245, v237, v245, v237
	v_fma_f32 v246, v238, v246, v238
	v_fma_f32 v247, v239, v247, v239
	v_mul_f32_e32 v244, 0x3f4c422a, v244
	v_mul_f32_e32 v245, 0x3f4c422a, v245
	v_mul_f32_e32 v246, 0x3f4c422a, v246
	v_mul_f32_e32 v247, 0x3f4c422a, v247
	v_mul_f32_e32 v244, 0xc038aa3b, v244
	v_mul_f32_e32 v245, 0xc038aa3b, v245
	v_mul_f32_e32 v246, 0xc038aa3b, v246
	v_mul_f32_e32 v247, 0xc038aa3b, v247
	v_exp_f32_e32 v244, v244
	v_exp_f32_e32 v245, v245
	v_exp_f32_e32 v246, v246
	v_exp_f32_e32 v247, v247
	v_add_f32_e32 v244, 1.0, v244
	v_add_f32_e32 v245, 1.0, v245
	v_add_f32_e32 v246, 1.0, v246
	v_add_f32_e32 v247, 1.0, v247
	v_rcp_f32_e32 v244, v244
	v_rcp_f32_e32 v245, v245
	v_rcp_f32_e32 v246, v246
	v_rcp_f32_e32 v247, v247
	v_mul_f32_e32 v244, v236, v244
	v_mul_f32_e32 v245, v237, v245
	v_mul_f32_e32 v246, v238, v246
	v_mul_f32_e32 v247, v239, v247
	v_mul_f32_e32 v174, v240, v244
	v_mul_f32_e32 v175, v241, v245
	v_mul_f32_e32 v176, v242, v246
	v_mul_f32_e32 v177, v243, v247
	v_cvt_pk_bf16_f32 v180, v248, v249
	v_cvt_pk_bf16_f32 v181, v250, v251
	v_cvt_pk_bf16_f32 v182, v174, v175
	v_cvt_pk_bf16_f32 v183, v176, v177
	s_branch .Lffn1e_store0
.Lffn1e_slow1:
	v_add_u32_e32 v189, 2080, v218
	v_mul_hi_u32 v203, v189, s59
	v_lshrrev_b32_e32 v203, 7, v203
	v_mul_u32_u24_e32 v203, 0x810, v203
	v_sub_u32_e32 v189, v189, v203
	v_cmp_lt_u32_e32 vcc, 0, v189
	v_cmp_lt_u32_e64 s[8:9], 1, v189
	s_nop 1
	v_mov_b32_dpp v228, v124 row_ror:1 row_mask:0xf bank_mask:0xf
	v_mov_b32_dpp v229, v124 row_ror:2 row_mask:0xf bank_mask:0xf
	v_mov_b32_dpp v230, v125 row_ror:1 row_mask:0xf bank_mask:0xf
	v_mov_b32_dpp v231, v125 row_ror:2 row_mask:0xf bank_mask:0xf
	v_mov_b32_dpp v232, v126 row_ror:1 row_mask:0xf bank_mask:0xf
	v_mov_b32_dpp v233, v126 row_ror:2 row_mask:0xf bank_mask:0xf
	v_mov_b32_dpp v234, v127 row_ror:1 row_mask:0xf bank_mask:0xf
	v_mov_b32_dpp v235, v127 row_ror:2 row_mask:0xf bank_mask:0xf
	v_mov_b32_dpp v228, v108 row_shr:1 row_mask:0xf bank_mask:0xf
	v_mov_b32_dpp v229, v108 row_shr:2 row_mask:0xf bank_mask:0xf
	v_mov_b32_dpp v230, v109 row_shr:1 row_mask:0xf bank_mask:0xf
	v_mov_b32_dpp v231, v109 row_shr:2 row_mask:0xf bank_mask:0xf
	v_mov_b32_dpp v232, v110 row_shr:1 row_mask:0xf bank_mask:0xf
	v_mov_b32_dpp v233, v110 row_shr:2 row_mask:0xf bank_mask:0xf
	v_mov_b32_dpp v234, v111 row_shr:1 row_mask:0xf bank_mask:0xf
	v_mov_b32_dpp v235, v111 row_shr:2 row_mask:0xf bank_mask:0xf
	v_cndmask_b32_e64 v228, 0, v228, vcc
	v_cndmask_b32_e64 v229, 0, v229, s[8:9]
	v_cndmask_b32_e64 v230, 0, v230, vcc
	v_cndmask_b32_e64 v231, 0, v231, s[8:9]
	v_cndmask_b32_e64 v232, 0, v232, vcc
	v_cndmask_b32_e64 v233, 0, v233, s[8:9]
	v_cndmask_b32_e64 v234, 0, v234, vcc
	v_cndmask_b32_e64 v235, 0, v235, s[8:9]
	v_fma_f32 v236, v229, v128, v208
	v_fma_f32 v237, v231, v129, v209
	v_fma_f32 v238, v233, v130, v210
	v_fma_f32 v239, v235, v131, v211
	v_fmac_f32_e32 v236, v228, v144
	v_fmac_f32_e32 v237, v230, v145
	v_fmac_f32_e32 v238, v232, v146
	v_fmac_f32_e32 v239, v234, v147
	v_fmac_f32_e32 v236, v108, v160
	v_fmac_f32_e32 v237, v109, v161
	v_fmac_f32_e32 v238, v110, v162
	v_fmac_f32_e32 v239, v111, v163
	v_mov_b32_dpp v228, v116 row_ror:1 row_mask:0xf bank_mask:0xf
	v_mov_b32_dpp v229, v116 row_ror:2 row_mask:0xf bank_mask:0xf
	v_mov_b32_dpp v230, v117 row_ror:1 row_mask:0xf bank_mask:0xf
	v_mov_b32_dpp v231, v117 row_ror:2 row_mask:0xf bank_mask:0xf
	v_mov_b32_dpp v232, v118 row_ror:1 row_mask:0xf bank_mask:0xf
	v_mov_b32_dpp v233, v118 row_ror:2 row_mask:0xf bank_mask:0xf
	v_mov_b32_dpp v234, v119 row_ror:1 row_mask:0xf bank_mask:0xf
	v_mov_b32_dpp v235, v119 row_ror:2 row_mask:0xf bank_mask:0xf
	v_mov_b32_dpp v228, v100 row_shr:1 row_mask:0xf bank_mask:0xf
	v_mov_b32_dpp v229, v100 row_shr:2 row_mask:0xf bank_mask:0xf
	v_mov_b32_dpp v230, v101 row_shr:1 row_mask:0xf bank_mask:0xf
	v_mov_b32_dpp v231, v101 row_shr:2 row_mask:0xf bank_mask:0xf
	v_mov_b32_dpp v232, v102 row_shr:1 row_mask:0xf bank_mask:0xf
	v_mov_b32_dpp v233, v102 row_shr:2 row_mask:0xf bank_mask:0xf
	v_mov_b32_dpp v234, v103 row_shr:1 row_mask:0xf bank_mask:0xf
	v_mov_b32_dpp v235, v103 row_shr:2 row_mask:0xf bank_mask:0xf
	v_cndmask_b32_e64 v228, 0, v228, vcc
	v_cndmask_b32_e64 v229, 0, v229, s[8:9]
	v_cndmask_b32_e64 v230, 0, v230, vcc
	v_cndmask_b32_e64 v231, 0, v231, s[8:9]
	v_cndmask_b32_e64 v232, 0, v232, vcc
	v_cndmask_b32_e64 v233, 0, v233, s[8:9]
	v_cndmask_b32_e64 v234, 0, v234, vcc
	v_cndmask_b32_e64 v235, 0, v235, s[8:9]
	v_fma_f32 v240, v229, v132, v212
	v_fma_f32 v241, v231, v133, v213
	v_fma_f32 v242, v233, v134, v214
	v_fma_f32 v243, v235, v135, v215
	v_fmac_f32_e32 v240, v228, v148
	v_fmac_f32_e32 v241, v230, v149
	v_fmac_f32_e32 v242, v232, v150
	v_fmac_f32_e32 v243, v234, v151
	v_fmac_f32_e32 v240, v100, v164
	v_fmac_f32_e32 v241, v101, v165
	v_fmac_f32_e32 v242, v102, v166
	v_fmac_f32_e32 v243, v103, v167
	v_mul_f32_e32 v244, 0x3d372713, v236
	v_mul_f32_e32 v245, 0x3d372713, v237
	v_mul_f32_e32 v246, 0x3d372713, v238
	v_mul_f32_e32 v247, 0x3d372713, v239
	v_mul_f32_e32 v244, v236, v244
	v_mul_f32_e32 v245, v237, v245
	v_mul_f32_e32 v246, v238, v246
	v_mul_f32_e32 v247, v239, v247
	v_fma_f32 v244, v236, v244, v236
	v_fma_f32 v245, v237, v245, v237
	v_fma_f32 v246, v238, v246, v238
	v_fma_f32 v247, v239, v247, v239
	v_mul_f32_e32 v244, 0x3f4c422a, v244
	v_mul_f32_e32 v245, 0x3f4c422a, v245
	v_mul_f32_e32 v246, 0x3f4c422a, v246
	v_mul_f32_e32 v247, 0x3f4c422a, v247
	v_mul_f32_e32 v244, 0xc038aa3b, v244
	v_mul_f32_e32 v245, 0xc038aa3b, v245
	v_mul_f32_e32 v246, 0xc038aa3b, v246
	v_mul_f32_e32 v247, 0xc038aa3b, v247
	v_exp_f32_e32 v244, v244
	v_exp_f32_e32 v245, v245
	v_exp_f32_e32 v246, v246
	v_exp_f32_e32 v247, v247
	v_add_f32_e32 v244, 1.0, v244
	v_add_f32_e32 v245, 1.0, v245
	v_add_f32_e32 v246, 1.0, v246
	v_add_f32_e32 v247, 1.0, v247
	v_rcp_f32_e32 v244, v244
	v_rcp_f32_e32 v245, v245
	v_rcp_f32_e32 v246, v246
	v_rcp_f32_e32 v247, v247
	v_mul_f32_e32 v244, v236, v244
	v_mul_f32_e32 v245, v237, v245
	v_mul_f32_e32 v246, v238, v246
	v_mul_f32_e32 v247, v239, v247
	v_mul_f32_e32 v248, v240, v244
	v_mul_f32_e32 v249, v241, v245
	v_mul_f32_e32 v250, v242, v246
	v_mul_f32_e32 v251, v243, v247
	v_mov_b32_dpp v228, v120 row_ror:1 row_mask:0xf bank_mask:0xf
	v_mov_b32_dpp v229, v120 row_ror:2 row_mask:0xf bank_mask:0xf
	v_mov_b32_dpp v230, v121 row_ror:1 row_mask:0xf bank_mask:0xf
	v_mov_b32_dpp v231, v121 row_ror:2 row_mask:0xf bank_mask:0xf
	v_mov_b32_dpp v232, v122 row_ror:1 row_mask:0xf bank_mask:0xf
	v_mov_b32_dpp v233, v122 row_ror:2 row_mask:0xf bank_mask:0xf
	v_mov_b32_dpp v234, v123 row_ror:1 row_mask:0xf bank_mask:0xf
	v_mov_b32_dpp v235, v123 row_ror:2 row_mask:0xf bank_mask:0xf
	v_mov_b32_dpp v228, v104 row_shr:1 row_mask:0xf bank_mask:0xf
	v_mov_b32_dpp v229, v104 row_shr:2 row_mask:0xf bank_mask:0xf
	v_mov_b32_dpp v230, v105 row_shr:1 row_mask:0xf bank_mask:0xf
	v_mov_b32_dpp v231, v105 row_shr:2 row_mask:0xf bank_mask:0xf
	v_mov_b32_dpp v232, v106 row_shr:1 row_mask:0xf bank_mask:0xf
	v_mov_b32_dpp v233, v106 row_shr:2 row_mask:0xf bank_mask:0xf
	v_mov_b32_dpp v234, v107 row_shr:1 row_mask:0xf bank_mask:0xf
	v_mov_b32_dpp v235, v107 row_shr:2 row_mask:0xf bank_mask:0xf
	v_cndmask_b32_e64 v228, 0, v228, vcc
	v_cndmask_b32_e64 v229, 0, v229, s[8:9]
	v_cndmask_b32_e64 v230, 0, v230, vcc
	v_cndmask_b32_e64 v231, 0, v231, s[8:9]
	v_cndmask_b32_e64 v232, 0, v232, vcc
	v_cndmask_b32_e64 v233, 0, v233, s[8:9]
	v_cndmask_b32_e64 v234, 0, v234, vcc
	v_cndmask_b32_e64 v235, 0, v235, s[8:9]
	v_fma_f32 v236, v229, v136, v220
	v_fma_f32 v237, v231, v137, v221
	v_fma_f32 v238, v233, v138, v222
	v_fma_f32 v239, v235, v139, v223
	v_fmac_f32_e32 v236, v228, v152
	v_fmac_f32_e32 v237, v230, v153
	v_fmac_f32_e32 v238, v232, v154
	v_fmac_f32_e32 v239, v234, v155
	v_fmac_f32_e32 v236, v104, v168
	v_fmac_f32_e32 v237, v105, v169
	v_fmac_f32_e32 v238, v106, v170
	v_fmac_f32_e32 v239, v107, v171
	v_mov_b32_dpp v228, v112 row_ror:1 row_mask:0xf bank_mask:0xf
	v_mov_b32_dpp v229, v112 row_ror:2 row_mask:0xf bank_mask:0xf
	v_mov_b32_dpp v230, v113 row_ror:1 row_mask:0xf bank_mask:0xf
	v_mov_b32_dpp v231, v113 row_ror:2 row_mask:0xf bank_mask:0xf
	v_mov_b32_dpp v232, v114 row_ror:1 row_mask:0xf bank_mask:0xf
	v_mov_b32_dpp v233, v114 row_ror:2 row_mask:0xf bank_mask:0xf
	v_mov_b32_dpp v234, v115 row_ror:1 row_mask:0xf bank_mask:0xf
	v_mov_b32_dpp v235, v115 row_ror:2 row_mask:0xf bank_mask:0xf
	v_mov_b32_dpp v228, v96 row_shr:1 row_mask:0xf bank_mask:0xf
	v_mov_b32_dpp v229, v96 row_shr:2 row_mask:0xf bank_mask:0xf
	v_mov_b32_dpp v230, v97 row_shr:1 row_mask:0xf bank_mask:0xf
	v_mov_b32_dpp v231, v97 row_shr:2 row_mask:0xf bank_mask:0xf
	v_mov_b32_dpp v232, v98 row_shr:1 row_mask:0xf bank_mask:0xf
	v_mov_b32_dpp v233, v98 row_shr:2 row_mask:0xf bank_mask:0xf
	v_mov_b32_dpp v234, v99 row_shr:1 row_mask:0xf bank_mask:0xf
	v_mov_b32_dpp v235, v99 row_shr:2 row_mask:0xf bank_mask:0xf
	v_cndmask_b32_e64 v228, 0, v228, vcc
	v_cndmask_b32_e64 v229, 0, v229, s[8:9]
	v_cndmask_b32_e64 v230, 0, v230, vcc
	v_cndmask_b32_e64 v231, 0, v231, s[8:9]
	v_cndmask_b32_e64 v232, 0, v232, vcc
	v_cndmask_b32_e64 v233, 0, v233, s[8:9]
	v_cndmask_b32_e64 v234, 0, v234, vcc
	v_cndmask_b32_e64 v235, 0, v235, s[8:9]
	v_fma_f32 v240, v229, v140, v224
	v_fma_f32 v241, v231, v141, v225
	v_fma_f32 v242, v233, v142, v226
	v_fma_f32 v243, v235, v143, v227
	v_fmac_f32_e32 v240, v228, v156
	v_fmac_f32_e32 v241, v230, v157
	v_fmac_f32_e32 v242, v232, v158
	v_fmac_f32_e32 v243, v234, v159
	v_fmac_f32_e32 v240, v96, v204
	v_fmac_f32_e32 v241, v97, v205
	v_fmac_f32_e32 v242, v98, v206
	v_fmac_f32_e32 v243, v99, v207
	v_mul_f32_e32 v244, 0x3d372713, v236
	v_mul_f32_e32 v245, 0x3d372713, v237
	v_mul_f32_e32 v246, 0x3d372713, v238
	v_mul_f32_e32 v247, 0x3d372713, v239
	v_mul_f32_e32 v244, v236, v244
	v_mul_f32_e32 v245, v237, v245
	v_mul_f32_e32 v246, v238, v246
	v_mul_f32_e32 v247, v239, v247
	v_fma_f32 v244, v236, v244, v236
	v_fma_f32 v245, v237, v245, v237
	v_fma_f32 v246, v238, v246, v238
	v_fma_f32 v247, v239, v247, v239
	v_mul_f32_e32 v244, 0x3f4c422a, v244
	v_mul_f32_e32 v245, 0x3f4c422a, v245
	v_mul_f32_e32 v246, 0x3f4c422a, v246
	v_mul_f32_e32 v247, 0x3f4c422a, v247
	v_mul_f32_e32 v244, 0xc038aa3b, v244
	v_mul_f32_e32 v245, 0xc038aa3b, v245
	v_mul_f32_e32 v246, 0xc038aa3b, v246
	v_mul_f32_e32 v247, 0xc038aa3b, v247
	v_exp_f32_e32 v244, v244
	v_exp_f32_e32 v245, v245
	v_exp_f32_e32 v246, v246
	v_exp_f32_e32 v247, v247
	v_add_f32_e32 v244, 1.0, v244
	v_add_f32_e32 v245, 1.0, v245
	v_add_f32_e32 v246, 1.0, v246
	v_add_f32_e32 v247, 1.0, v247
	v_rcp_f32_e32 v244, v244
	v_rcp_f32_e32 v245, v245
	v_rcp_f32_e32 v246, v246
	v_rcp_f32_e32 v247, v247
	v_mul_f32_e32 v244, v236, v244
	v_mul_f32_e32 v245, v237, v245
	v_mul_f32_e32 v246, v238, v246
	v_mul_f32_e32 v247, v239, v247
	v_mul_f32_e32 v174, v240, v244
	v_mul_f32_e32 v175, v241, v245
	v_mul_f32_e32 v176, v242, v246
	v_mul_f32_e32 v177, v243, v247
	v_cvt_pk_bf16_f32 v180, v248, v249
	v_cvt_pk_bf16_f32 v181, v250, v251
	v_cvt_pk_bf16_f32 v182, v174, v175
	v_cvt_pk_bf16_f32 v183, v176, v177
	s_branch .Lffn1e_store1
.Lffn1e_slow2:
	v_add_u32_e32 v189, 2096, v218
	v_mul_hi_u32 v203, v189, s59
	v_lshrrev_b32_e32 v203, 7, v203
	v_mul_u32_u24_e32 v203, 0x810, v203
	v_sub_u32_e32 v189, v189, v203
	v_cmp_lt_u32_e32 vcc, 0, v189
	v_cmp_lt_u32_e64 s[8:9], 1, v189
	s_nop 1
	v_mov_b32_dpp v228, v108 row_ror:1 row_mask:0xf bank_mask:0xf
	v_mov_b32_dpp v229, v108 row_ror:2 row_mask:0xf bank_mask:0xf
	v_mov_b32_dpp v230, v109 row_ror:1 row_mask:0xf bank_mask:0xf
	v_mov_b32_dpp v231, v109 row_ror:2 row_mask:0xf bank_mask:0xf
	v_mov_b32_dpp v232, v110 row_ror:1 row_mask:0xf bank_mask:0xf
	v_mov_b32_dpp v233, v110 row_ror:2 row_mask:0xf bank_mask:0xf
	v_mov_b32_dpp v234, v111 row_ror:1 row_mask:0xf bank_mask:0xf
	v_mov_b32_dpp v235, v111 row_ror:2 row_mask:0xf bank_mask:0xf
	v_mov_b32_dpp v228, v92 row_shr:1 row_mask:0xf bank_mask:0xf
	v_mov_b32_dpp v229, v92 row_shr:2 row_mask:0xf bank_mask:0xf
	v_mov_b32_dpp v230, v93 row_shr:1 row_mask:0xf bank_mask:0xf
	v_mov_b32_dpp v231, v93 row_shr:2 row_mask:0xf bank_mask:0xf
	v_mov_b32_dpp v232, v94 row_shr:1 row_mask:0xf bank_mask:0xf
	v_mov_b32_dpp v233, v94 row_shr:2 row_mask:0xf bank_mask:0xf
	v_mov_b32_dpp v234, v95 row_shr:1 row_mask:0xf bank_mask:0xf
	v_mov_b32_dpp v235, v95 row_shr:2 row_mask:0xf bank_mask:0xf
	v_cndmask_b32_e64 v228, 0, v228, vcc
	v_cndmask_b32_e64 v229, 0, v229, s[8:9]
	v_cndmask_b32_e64 v230, 0, v230, vcc
	v_cndmask_b32_e64 v231, 0, v231, s[8:9]
	v_cndmask_b32_e64 v232, 0, v232, vcc
	v_cndmask_b32_e64 v233, 0, v233, s[8:9]
	v_cndmask_b32_e64 v234, 0, v234, vcc
	v_cndmask_b32_e64 v235, 0, v235, s[8:9]
	v_fma_f32 v236, v229, v128, v208
	v_fma_f32 v237, v231, v129, v209
	v_fma_f32 v238, v233, v130, v210
	v_fma_f32 v239, v235, v131, v211
	v_fmac_f32_e32 v236, v228, v144
	v_fmac_f32_e32 v237, v230, v145
	v_fmac_f32_e32 v238, v232, v146
	v_fmac_f32_e32 v239, v234, v147
	v_fmac_f32_e32 v236, v92, v160
	v_fmac_f32_e32 v237, v93, v161
	v_fmac_f32_e32 v238, v94, v162
	v_fmac_f32_e32 v239, v95, v163
	v_mov_b32_dpp v228, v100 row_ror:1 row_mask:0xf bank_mask:0xf
	v_mov_b32_dpp v229, v100 row_ror:2 row_mask:0xf bank_mask:0xf
	v_mov_b32_dpp v230, v101 row_ror:1 row_mask:0xf bank_mask:0xf
	v_mov_b32_dpp v231, v101 row_ror:2 row_mask:0xf bank_mask:0xf
	v_mov_b32_dpp v232, v102 row_ror:1 row_mask:0xf bank_mask:0xf
	v_mov_b32_dpp v233, v102 row_ror:2 row_mask:0xf bank_mask:0xf
	v_mov_b32_dpp v234, v103 row_ror:1 row_mask:0xf bank_mask:0xf
	v_mov_b32_dpp v235, v103 row_ror:2 row_mask:0xf bank_mask:0xf
	v_mov_b32_dpp v228, v84 row_shr:1 row_mask:0xf bank_mask:0xf
	v_mov_b32_dpp v229, v84 row_shr:2 row_mask:0xf bank_mask:0xf
	v_mov_b32_dpp v230, v85 row_shr:1 row_mask:0xf bank_mask:0xf
	v_mov_b32_dpp v231, v85 row_shr:2 row_mask:0xf bank_mask:0xf
	v_mov_b32_dpp v232, v86 row_shr:1 row_mask:0xf bank_mask:0xf
	v_mov_b32_dpp v233, v86 row_shr:2 row_mask:0xf bank_mask:0xf
	v_mov_b32_dpp v234, v87 row_shr:1 row_mask:0xf bank_mask:0xf
	v_mov_b32_dpp v235, v87 row_shr:2 row_mask:0xf bank_mask:0xf
	v_cndmask_b32_e64 v228, 0, v228, vcc
	v_cndmask_b32_e64 v229, 0, v229, s[8:9]
	v_cndmask_b32_e64 v230, 0, v230, vcc
	v_cndmask_b32_e64 v231, 0, v231, s[8:9]
	v_cndmask_b32_e64 v232, 0, v232, vcc
	v_cndmask_b32_e64 v233, 0, v233, s[8:9]
	v_cndmask_b32_e64 v234, 0, v234, vcc
	v_cndmask_b32_e64 v235, 0, v235, s[8:9]
	v_fma_f32 v240, v229, v132, v212
	v_fma_f32 v241, v231, v133, v213
	v_fma_f32 v242, v233, v134, v214
	v_fma_f32 v243, v235, v135, v215
	v_fmac_f32_e32 v240, v228, v148
	v_fmac_f32_e32 v241, v230, v149
	v_fmac_f32_e32 v242, v232, v150
	v_fmac_f32_e32 v243, v234, v151
	v_fmac_f32_e32 v240, v84, v164
	v_fmac_f32_e32 v241, v85, v165
	v_fmac_f32_e32 v242, v86, v166
	v_fmac_f32_e32 v243, v87, v167
	v_mul_f32_e32 v244, 0x3d372713, v236
	v_mul_f32_e32 v245, 0x3d372713, v237
	v_mul_f32_e32 v246, 0x3d372713, v238
	v_mul_f32_e32 v247, 0x3d372713, v239
	v_mul_f32_e32 v244, v236, v244
	v_mul_f32_e32 v245, v237, v245
	v_mul_f32_e32 v246, v238, v246
	v_mul_f32_e32 v247, v239, v247
	v_fma_f32 v244, v236, v244, v236
	v_fma_f32 v245, v237, v245, v237
	v_fma_f32 v246, v238, v246, v238
	v_fma_f32 v247, v239, v247, v239
	v_mul_f32_e32 v244, 0x3f4c422a, v244
	v_mul_f32_e32 v245, 0x3f4c422a, v245
	v_mul_f32_e32 v246, 0x3f4c422a, v246
	v_mul_f32_e32 v247, 0x3f4c422a, v247
	v_mul_f32_e32 v244, 0xc038aa3b, v244
	v_mul_f32_e32 v245, 0xc038aa3b, v245
	v_mul_f32_e32 v246, 0xc038aa3b, v246
	v_mul_f32_e32 v247, 0xc038aa3b, v247
	v_exp_f32_e32 v244, v244
	v_exp_f32_e32 v245, v245
	v_exp_f32_e32 v246, v246
	v_exp_f32_e32 v247, v247
	v_add_f32_e32 v244, 1.0, v244
	v_add_f32_e32 v245, 1.0, v245
	v_add_f32_e32 v246, 1.0, v246
	v_add_f32_e32 v247, 1.0, v247
	v_rcp_f32_e32 v244, v244
	v_rcp_f32_e32 v245, v245
	v_rcp_f32_e32 v246, v246
	v_rcp_f32_e32 v247, v247
	v_mul_f32_e32 v244, v236, v244
	v_mul_f32_e32 v245, v237, v245
	v_mul_f32_e32 v246, v238, v246
	v_mul_f32_e32 v247, v239, v247
	v_mul_f32_e32 v248, v240, v244
	v_mul_f32_e32 v249, v241, v245
	v_mul_f32_e32 v250, v242, v246
	v_mul_f32_e32 v251, v243, v247
	v_mov_b32_dpp v228, v104 row_ror:1 row_mask:0xf bank_mask:0xf
	v_mov_b32_dpp v229, v104 row_ror:2 row_mask:0xf bank_mask:0xf
	v_mov_b32_dpp v230, v105 row_ror:1 row_mask:0xf bank_mask:0xf
	v_mov_b32_dpp v231, v105 row_ror:2 row_mask:0xf bank_mask:0xf
	v_mov_b32_dpp v232, v106 row_ror:1 row_mask:0xf bank_mask:0xf
	v_mov_b32_dpp v233, v106 row_ror:2 row_mask:0xf bank_mask:0xf
	v_mov_b32_dpp v234, v107 row_ror:1 row_mask:0xf bank_mask:0xf
	v_mov_b32_dpp v235, v107 row_ror:2 row_mask:0xf bank_mask:0xf
	v_mov_b32_dpp v228, v88 row_shr:1 row_mask:0xf bank_mask:0xf
	v_mov_b32_dpp v229, v88 row_shr:2 row_mask:0xf bank_mask:0xf
	v_mov_b32_dpp v230, v89 row_shr:1 row_mask:0xf bank_mask:0xf
	v_mov_b32_dpp v231, v89 row_shr:2 row_mask:0xf bank_mask:0xf
	v_mov_b32_dpp v232, v90 row_shr:1 row_mask:0xf bank_mask:0xf
	v_mov_b32_dpp v233, v90 row_shr:2 row_mask:0xf bank_mask:0xf
	v_mov_b32_dpp v234, v91 row_shr:1 row_mask:0xf bank_mask:0xf
	v_mov_b32_dpp v235, v91 row_shr:2 row_mask:0xf bank_mask:0xf
	v_cndmask_b32_e64 v228, 0, v228, vcc
	v_cndmask_b32_e64 v229, 0, v229, s[8:9]
	v_cndmask_b32_e64 v230, 0, v230, vcc
	v_cndmask_b32_e64 v231, 0, v231, s[8:9]
	v_cndmask_b32_e64 v232, 0, v232, vcc
	v_cndmask_b32_e64 v233, 0, v233, s[8:9]
	v_cndmask_b32_e64 v234, 0, v234, vcc
	v_cndmask_b32_e64 v235, 0, v235, s[8:9]
	v_fma_f32 v236, v229, v136, v220
	v_fma_f32 v237, v231, v137, v221
	v_fma_f32 v238, v233, v138, v222
	v_fma_f32 v239, v235, v139, v223
	v_fmac_f32_e32 v236, v228, v152
	v_fmac_f32_e32 v237, v230, v153
	v_fmac_f32_e32 v238, v232, v154
	v_fmac_f32_e32 v239, v234, v155
	v_fmac_f32_e32 v236, v88, v168
	v_fmac_f32_e32 v237, v89, v169
	v_fmac_f32_e32 v238, v90, v170
	v_fmac_f32_e32 v239, v91, v171
	v_mov_b32_dpp v228, v96 row_ror:1 row_mask:0xf bank_mask:0xf
	v_mov_b32_dpp v229, v96 row_ror:2 row_mask:0xf bank_mask:0xf
	v_mov_b32_dpp v230, v97 row_ror:1 row_mask:0xf bank_mask:0xf
	v_mov_b32_dpp v231, v97 row_ror:2 row_mask:0xf bank_mask:0xf
	v_mov_b32_dpp v232, v98 row_ror:1 row_mask:0xf bank_mask:0xf
	v_mov_b32_dpp v233, v98 row_ror:2 row_mask:0xf bank_mask:0xf
	v_mov_b32_dpp v234, v99 row_ror:1 row_mask:0xf bank_mask:0xf
	v_mov_b32_dpp v235, v99 row_ror:2 row_mask:0xf bank_mask:0xf
	v_mov_b32_dpp v228, v80 row_shr:1 row_mask:0xf bank_mask:0xf
	v_mov_b32_dpp v229, v80 row_shr:2 row_mask:0xf bank_mask:0xf
	v_mov_b32_dpp v230, v81 row_shr:1 row_mask:0xf bank_mask:0xf
	v_mov_b32_dpp v231, v81 row_shr:2 row_mask:0xf bank_mask:0xf
	v_mov_b32_dpp v232, v82 row_shr:1 row_mask:0xf bank_mask:0xf
	v_mov_b32_dpp v233, v82 row_shr:2 row_mask:0xf bank_mask:0xf
	v_mov_b32_dpp v234, v83 row_shr:1 row_mask:0xf bank_mask:0xf
	v_mov_b32_dpp v235, v83 row_shr:2 row_mask:0xf bank_mask:0xf
	v_cndmask_b32_e64 v228, 0, v228, vcc
	v_cndmask_b32_e64 v229, 0, v229, s[8:9]
	v_cndmask_b32_e64 v230, 0, v230, vcc
	v_cndmask_b32_e64 v231, 0, v231, s[8:9]
	v_cndmask_b32_e64 v232, 0, v232, vcc
	v_cndmask_b32_e64 v233, 0, v233, s[8:9]
	v_cndmask_b32_e64 v234, 0, v234, vcc
	v_cndmask_b32_e64 v235, 0, v235, s[8:9]
	v_fma_f32 v240, v229, v140, v224
	v_fma_f32 v241, v231, v141, v225
	v_fma_f32 v242, v233, v142, v226
	v_fma_f32 v243, v235, v143, v227
	v_fmac_f32_e32 v240, v228, v156
	v_fmac_f32_e32 v241, v230, v157
	v_fmac_f32_e32 v242, v232, v158
	v_fmac_f32_e32 v243, v234, v159
	v_fmac_f32_e32 v240, v80, v204
	v_fmac_f32_e32 v241, v81, v205
	v_fmac_f32_e32 v242, v82, v206
	v_fmac_f32_e32 v243, v83, v207
	v_mul_f32_e32 v244, 0x3d372713, v236
	v_mul_f32_e32 v245, 0x3d372713, v237
	v_mul_f32_e32 v246, 0x3d372713, v238
	v_mul_f32_e32 v247, 0x3d372713, v239
	v_mul_f32_e32 v244, v236, v244
	v_mul_f32_e32 v245, v237, v245
	v_mul_f32_e32 v246, v238, v246
	v_mul_f32_e32 v247, v239, v247
	v_fma_f32 v244, v236, v244, v236
	v_fma_f32 v245, v237, v245, v237
	v_fma_f32 v246, v238, v246, v238
	v_fma_f32 v247, v239, v247, v239
	v_mul_f32_e32 v244, 0x3f4c422a, v244
	v_mul_f32_e32 v245, 0x3f4c422a, v245
	v_mul_f32_e32 v246, 0x3f4c422a, v246
	v_mul_f32_e32 v247, 0x3f4c422a, v247
	v_mul_f32_e32 v244, 0xc038aa3b, v244
	v_mul_f32_e32 v245, 0xc038aa3b, v245
	v_mul_f32_e32 v246, 0xc038aa3b, v246
	v_mul_f32_e32 v247, 0xc038aa3b, v247
	v_exp_f32_e32 v244, v244
	v_exp_f32_e32 v245, v245
	v_exp_f32_e32 v246, v246
	v_exp_f32_e32 v247, v247
	v_add_f32_e32 v244, 1.0, v244
	v_add_f32_e32 v245, 1.0, v245
	v_add_f32_e32 v246, 1.0, v246
	v_add_f32_e32 v247, 1.0, v247
	v_rcp_f32_e32 v244, v244
	v_rcp_f32_e32 v245, v245
	v_rcp_f32_e32 v246, v246
	v_rcp_f32_e32 v247, v247
	v_mul_f32_e32 v244, v236, v244
	v_mul_f32_e32 v245, v237, v245
	v_mul_f32_e32 v246, v238, v246
	v_mul_f32_e32 v247, v239, v247
	v_mul_f32_e32 v174, v240, v244
	v_mul_f32_e32 v175, v241, v245
	v_mul_f32_e32 v176, v242, v246
	v_mul_f32_e32 v177, v243, v247
	v_cvt_pk_bf16_f32 v180, v248, v249
	v_cvt_pk_bf16_f32 v181, v250, v251
	v_cvt_pk_bf16_f32 v182, v174, v175
	v_cvt_pk_bf16_f32 v183, v176, v177
	s_branch .Lffn1e_store2
.Lffn1e_slow3:
	v_add_u32_e32 v189, 2112, v218
	v_mul_hi_u32 v203, v189, s59
	v_lshrrev_b32_e32 v203, 7, v203
	v_mul_u32_u24_e32 v203, 0x810, v203
	v_sub_u32_e32 v189, v189, v203
	v_cmp_lt_u32_e32 vcc, 0, v189
	v_cmp_lt_u32_e64 s[8:9], 1, v189
	s_nop 1
	v_mov_b32_dpp v228, v92 row_ror:1 row_mask:0xf bank_mask:0xf
	v_mov_b32_dpp v229, v92 row_ror:2 row_mask:0xf bank_mask:0xf
	v_mov_b32_dpp v230, v93 row_ror:1 row_mask:0xf bank_mask:0xf
	v_mov_b32_dpp v231, v93 row_ror:2 row_mask:0xf bank_mask:0xf
	v_mov_b32_dpp v232, v94 row_ror:1 row_mask:0xf bank_mask:0xf
	v_mov_b32_dpp v233, v94 row_ror:2 row_mask:0xf bank_mask:0xf
	v_mov_b32_dpp v234, v95 row_ror:1 row_mask:0xf bank_mask:0xf
	v_mov_b32_dpp v235, v95 row_ror:2 row_mask:0xf bank_mask:0xf
	v_mov_b32_dpp v228, v76 row_shr:1 row_mask:0xf bank_mask:0xf
	v_mov_b32_dpp v229, v76 row_shr:2 row_mask:0xf bank_mask:0xf
	v_mov_b32_dpp v230, v77 row_shr:1 row_mask:0xf bank_mask:0xf
	v_mov_b32_dpp v231, v77 row_shr:2 row_mask:0xf bank_mask:0xf
	v_mov_b32_dpp v232, v78 row_shr:1 row_mask:0xf bank_mask:0xf
	v_mov_b32_dpp v233, v78 row_shr:2 row_mask:0xf bank_mask:0xf
	v_mov_b32_dpp v234, v79 row_shr:1 row_mask:0xf bank_mask:0xf
	v_mov_b32_dpp v235, v79 row_shr:2 row_mask:0xf bank_mask:0xf
	v_cndmask_b32_e64 v228, 0, v228, vcc
	v_cndmask_b32_e64 v229, 0, v229, s[8:9]
	v_cndmask_b32_e64 v230, 0, v230, vcc
	v_cndmask_b32_e64 v231, 0, v231, s[8:9]
	v_cndmask_b32_e64 v232, 0, v232, vcc
	v_cndmask_b32_e64 v233, 0, v233, s[8:9]
	v_cndmask_b32_e64 v234, 0, v234, vcc
	v_cndmask_b32_e64 v235, 0, v235, s[8:9]
	v_fma_f32 v236, v229, v128, v208
	v_fma_f32 v237, v231, v129, v209
	v_fma_f32 v238, v233, v130, v210
	v_fma_f32 v239, v235, v131, v211
	v_fmac_f32_e32 v236, v228, v144
	v_fmac_f32_e32 v237, v230, v145
	v_fmac_f32_e32 v238, v232, v146
	v_fmac_f32_e32 v239, v234, v147
	v_fmac_f32_e32 v236, v76, v160
	v_fmac_f32_e32 v237, v77, v161
	v_fmac_f32_e32 v238, v78, v162
	v_fmac_f32_e32 v239, v79, v163
	v_mov_b32_dpp v228, v84 row_ror:1 row_mask:0xf bank_mask:0xf
	v_mov_b32_dpp v229, v84 row_ror:2 row_mask:0xf bank_mask:0xf
	v_mov_b32_dpp v230, v85 row_ror:1 row_mask:0xf bank_mask:0xf
	v_mov_b32_dpp v231, v85 row_ror:2 row_mask:0xf bank_mask:0xf
	v_mov_b32_dpp v232, v86 row_ror:1 row_mask:0xf bank_mask:0xf
	v_mov_b32_dpp v233, v86 row_ror:2 row_mask:0xf bank_mask:0xf
	v_mov_b32_dpp v234, v87 row_ror:1 row_mask:0xf bank_mask:0xf
	v_mov_b32_dpp v235, v87 row_ror:2 row_mask:0xf bank_mask:0xf
	v_mov_b32_dpp v228, v68 row_shr:1 row_mask:0xf bank_mask:0xf
	v_mov_b32_dpp v229, v68 row_shr:2 row_mask:0xf bank_mask:0xf
	v_mov_b32_dpp v230, v69 row_shr:1 row_mask:0xf bank_mask:0xf
	v_mov_b32_dpp v231, v69 row_shr:2 row_mask:0xf bank_mask:0xf
	v_mov_b32_dpp v232, v70 row_shr:1 row_mask:0xf bank_mask:0xf
	v_mov_b32_dpp v233, v70 row_shr:2 row_mask:0xf bank_mask:0xf
	v_mov_b32_dpp v234, v71 row_shr:1 row_mask:0xf bank_mask:0xf
	v_mov_b32_dpp v235, v71 row_shr:2 row_mask:0xf bank_mask:0xf
	v_cndmask_b32_e64 v228, 0, v228, vcc
	v_cndmask_b32_e64 v229, 0, v229, s[8:9]
	v_cndmask_b32_e64 v230, 0, v230, vcc
	v_cndmask_b32_e64 v231, 0, v231, s[8:9]
	v_cndmask_b32_e64 v232, 0, v232, vcc
	v_cndmask_b32_e64 v233, 0, v233, s[8:9]
	v_cndmask_b32_e64 v234, 0, v234, vcc
	v_cndmask_b32_e64 v235, 0, v235, s[8:9]
	v_fma_f32 v240, v229, v132, v212
	v_fma_f32 v241, v231, v133, v213
	v_fma_f32 v242, v233, v134, v214
	v_fma_f32 v243, v235, v135, v215
	v_fmac_f32_e32 v240, v228, v148
	v_fmac_f32_e32 v241, v230, v149
	v_fmac_f32_e32 v242, v232, v150
	v_fmac_f32_e32 v243, v234, v151
	v_fmac_f32_e32 v240, v68, v164
	v_fmac_f32_e32 v241, v69, v165
	v_fmac_f32_e32 v242, v70, v166
	v_fmac_f32_e32 v243, v71, v167
	v_mul_f32_e32 v244, 0x3d372713, v236
	v_mul_f32_e32 v245, 0x3d372713, v237
	v_mul_f32_e32 v246, 0x3d372713, v238
	v_mul_f32_e32 v247, 0x3d372713, v239
	v_mul_f32_e32 v244, v236, v244
	v_mul_f32_e32 v245, v237, v245
	v_mul_f32_e32 v246, v238, v246
	v_mul_f32_e32 v247, v239, v247
	v_fma_f32 v244, v236, v244, v236
	v_fma_f32 v245, v237, v245, v237
	v_fma_f32 v246, v238, v246, v238
	v_fma_f32 v247, v239, v247, v239
	v_mul_f32_e32 v244, 0x3f4c422a, v244
	v_mul_f32_e32 v245, 0x3f4c422a, v245
	v_mul_f32_e32 v246, 0x3f4c422a, v246
	v_mul_f32_e32 v247, 0x3f4c422a, v247
	v_mul_f32_e32 v244, 0xc038aa3b, v244
	v_mul_f32_e32 v245, 0xc038aa3b, v245
	v_mul_f32_e32 v246, 0xc038aa3b, v246
	v_mul_f32_e32 v247, 0xc038aa3b, v247
	v_exp_f32_e32 v244, v244
	v_exp_f32_e32 v245, v245
	v_exp_f32_e32 v246, v246
	v_exp_f32_e32 v247, v247
	v_add_f32_e32 v244, 1.0, v244
	v_add_f32_e32 v245, 1.0, v245
	v_add_f32_e32 v246, 1.0, v246
	v_add_f32_e32 v247, 1.0, v247
	v_rcp_f32_e32 v244, v244
	v_rcp_f32_e32 v245, v245
	v_rcp_f32_e32 v246, v246
	v_rcp_f32_e32 v247, v247
	v_mul_f32_e32 v244, v236, v244
	v_mul_f32_e32 v245, v237, v245
	v_mul_f32_e32 v246, v238, v246
	v_mul_f32_e32 v247, v239, v247
	v_mul_f32_e32 v248, v240, v244
	v_mul_f32_e32 v249, v241, v245
	v_mul_f32_e32 v250, v242, v246
	v_mul_f32_e32 v251, v243, v247
	v_mov_b32_dpp v228, v88 row_ror:1 row_mask:0xf bank_mask:0xf
	v_mov_b32_dpp v229, v88 row_ror:2 row_mask:0xf bank_mask:0xf
	v_mov_b32_dpp v230, v89 row_ror:1 row_mask:0xf bank_mask:0xf
	v_mov_b32_dpp v231, v89 row_ror:2 row_mask:0xf bank_mask:0xf
	v_mov_b32_dpp v232, v90 row_ror:1 row_mask:0xf bank_mask:0xf
	v_mov_b32_dpp v233, v90 row_ror:2 row_mask:0xf bank_mask:0xf
	v_mov_b32_dpp v234, v91 row_ror:1 row_mask:0xf bank_mask:0xf
	v_mov_b32_dpp v235, v91 row_ror:2 row_mask:0xf bank_mask:0xf
	v_mov_b32_dpp v228, v72 row_shr:1 row_mask:0xf bank_mask:0xf
	v_mov_b32_dpp v229, v72 row_shr:2 row_mask:0xf bank_mask:0xf
	v_mov_b32_dpp v230, v73 row_shr:1 row_mask:0xf bank_mask:0xf
	v_mov_b32_dpp v231, v73 row_shr:2 row_mask:0xf bank_mask:0xf
	v_mov_b32_dpp v232, v74 row_shr:1 row_mask:0xf bank_mask:0xf
	v_mov_b32_dpp v233, v74 row_shr:2 row_mask:0xf bank_mask:0xf
	v_mov_b32_dpp v234, v75 row_shr:1 row_mask:0xf bank_mask:0xf
	v_mov_b32_dpp v235, v75 row_shr:2 row_mask:0xf bank_mask:0xf
	v_cndmask_b32_e64 v228, 0, v228, vcc
	v_cndmask_b32_e64 v229, 0, v229, s[8:9]
	v_cndmask_b32_e64 v230, 0, v230, vcc
	v_cndmask_b32_e64 v231, 0, v231, s[8:9]
	v_cndmask_b32_e64 v232, 0, v232, vcc
	v_cndmask_b32_e64 v233, 0, v233, s[8:9]
	v_cndmask_b32_e64 v234, 0, v234, vcc
	v_cndmask_b32_e64 v235, 0, v235, s[8:9]
	v_fma_f32 v236, v229, v136, v220
	v_fma_f32 v237, v231, v137, v221
	v_fma_f32 v238, v233, v138, v222
	v_fma_f32 v239, v235, v139, v223
	v_fmac_f32_e32 v236, v228, v152
	v_fmac_f32_e32 v237, v230, v153
	v_fmac_f32_e32 v238, v232, v154
	v_fmac_f32_e32 v239, v234, v155
	v_fmac_f32_e32 v236, v72, v168
	v_fmac_f32_e32 v237, v73, v169
	v_fmac_f32_e32 v238, v74, v170
	v_fmac_f32_e32 v239, v75, v171
	v_mov_b32_dpp v228, v80 row_ror:1 row_mask:0xf bank_mask:0xf
	v_mov_b32_dpp v229, v80 row_ror:2 row_mask:0xf bank_mask:0xf
	v_mov_b32_dpp v230, v81 row_ror:1 row_mask:0xf bank_mask:0xf
	v_mov_b32_dpp v231, v81 row_ror:2 row_mask:0xf bank_mask:0xf
	v_mov_b32_dpp v232, v82 row_ror:1 row_mask:0xf bank_mask:0xf
	v_mov_b32_dpp v233, v82 row_ror:2 row_mask:0xf bank_mask:0xf
	v_mov_b32_dpp v234, v83 row_ror:1 row_mask:0xf bank_mask:0xf
	v_mov_b32_dpp v235, v83 row_ror:2 row_mask:0xf bank_mask:0xf
	v_mov_b32_dpp v228, v64 row_shr:1 row_mask:0xf bank_mask:0xf
	v_mov_b32_dpp v229, v64 row_shr:2 row_mask:0xf bank_mask:0xf
	v_mov_b32_dpp v230, v65 row_shr:1 row_mask:0xf bank_mask:0xf
	v_mov_b32_dpp v231, v65 row_shr:2 row_mask:0xf bank_mask:0xf
	v_mov_b32_dpp v232, v66 row_shr:1 row_mask:0xf bank_mask:0xf
	v_mov_b32_dpp v233, v66 row_shr:2 row_mask:0xf bank_mask:0xf
	v_mov_b32_dpp v234, v67 row_shr:1 row_mask:0xf bank_mask:0xf
	v_mov_b32_dpp v235, v67 row_shr:2 row_mask:0xf bank_mask:0xf
	v_cndmask_b32_e64 v228, 0, v228, vcc
	v_cndmask_b32_e64 v229, 0, v229, s[8:9]
	v_cndmask_b32_e64 v230, 0, v230, vcc
	v_cndmask_b32_e64 v231, 0, v231, s[8:9]
	v_cndmask_b32_e64 v232, 0, v232, vcc
	v_cndmask_b32_e64 v233, 0, v233, s[8:9]
	v_cndmask_b32_e64 v234, 0, v234, vcc
	v_cndmask_b32_e64 v235, 0, v235, s[8:9]
	v_fma_f32 v240, v229, v140, v224
	v_fma_f32 v241, v231, v141, v225
	v_fma_f32 v242, v233, v142, v226
	v_fma_f32 v243, v235, v143, v227
	v_fmac_f32_e32 v240, v228, v156
	v_fmac_f32_e32 v241, v230, v157
	v_fmac_f32_e32 v242, v232, v158
	v_fmac_f32_e32 v243, v234, v159
	v_fmac_f32_e32 v240, v64, v204
	v_fmac_f32_e32 v241, v65, v205
	v_fmac_f32_e32 v242, v66, v206
	v_fmac_f32_e32 v243, v67, v207
	v_mul_f32_e32 v244, 0x3d372713, v236
	v_mul_f32_e32 v245, 0x3d372713, v237
	v_mul_f32_e32 v246, 0x3d372713, v238
	v_mul_f32_e32 v247, 0x3d372713, v239
	v_mul_f32_e32 v244, v236, v244
	v_mul_f32_e32 v245, v237, v245
	v_mul_f32_e32 v246, v238, v246
	v_mul_f32_e32 v247, v239, v247
	v_fma_f32 v244, v236, v244, v236
	v_fma_f32 v245, v237, v245, v237
	v_fma_f32 v246, v238, v246, v238
	v_fma_f32 v247, v239, v247, v239
	v_mul_f32_e32 v244, 0x3f4c422a, v244
	v_mul_f32_e32 v245, 0x3f4c422a, v245
	v_mul_f32_e32 v246, 0x3f4c422a, v246
	v_mul_f32_e32 v247, 0x3f4c422a, v247
	v_mul_f32_e32 v244, 0xc038aa3b, v244
	v_mul_f32_e32 v245, 0xc038aa3b, v245
	v_mul_f32_e32 v246, 0xc038aa3b, v246
	v_mul_f32_e32 v247, 0xc038aa3b, v247
	v_exp_f32_e32 v244, v244
	v_exp_f32_e32 v245, v245
	v_exp_f32_e32 v246, v246
	v_exp_f32_e32 v247, v247
	v_add_f32_e32 v244, 1.0, v244
	v_add_f32_e32 v245, 1.0, v245
	v_add_f32_e32 v246, 1.0, v246
	v_add_f32_e32 v247, 1.0, v247
	v_rcp_f32_e32 v244, v244
	v_rcp_f32_e32 v245, v245
	v_rcp_f32_e32 v246, v246
	v_rcp_f32_e32 v247, v247
	v_mul_f32_e32 v244, v236, v244
	v_mul_f32_e32 v245, v237, v245
	v_mul_f32_e32 v246, v238, v246
	v_mul_f32_e32 v247, v239, v247
	v_mul_f32_e32 v174, v240, v244
	v_mul_f32_e32 v175, v241, v245
	v_mul_f32_e32 v176, v242, v246
	v_mul_f32_e32 v177, v243, v247
	v_cvt_pk_bf16_f32 v180, v248, v249
	v_cvt_pk_bf16_f32 v181, v250, v251
	v_cvt_pk_bf16_f32 v182, v174, v175
	v_cvt_pk_bf16_f32 v183, v176, v177
	s_branch .Lffn1e_store3
.Lffn1e_slow4:
	v_add_u32_e32 v189, 2128, v218
	v_mul_hi_u32 v203, v189, s59
	v_lshrrev_b32_e32 v203, 7, v203
	v_mul_u32_u24_e32 v203, 0x810, v203
	v_sub_u32_e32 v189, v189, v203
	v_cmp_lt_u32_e32 vcc, 0, v189
	v_cmp_lt_u32_e64 s[8:9], 1, v189
	s_nop 1
	v_mov_b32_dpp v228, v76 row_ror:1 row_mask:0xf bank_mask:0xf
	v_mov_b32_dpp v229, v76 row_ror:2 row_mask:0xf bank_mask:0xf
	v_mov_b32_dpp v230, v77 row_ror:1 row_mask:0xf bank_mask:0xf
	v_mov_b32_dpp v231, v77 row_ror:2 row_mask:0xf bank_mask:0xf
	v_mov_b32_dpp v232, v78 row_ror:1 row_mask:0xf bank_mask:0xf
	v_mov_b32_dpp v233, v78 row_ror:2 row_mask:0xf bank_mask:0xf
	v_mov_b32_dpp v234, v79 row_ror:1 row_mask:0xf bank_mask:0xf
	v_mov_b32_dpp v235, v79 row_ror:2 row_mask:0xf bank_mask:0xf
	v_mov_b32_dpp v228, v60 row_shr:1 row_mask:0xf bank_mask:0xf
	v_mov_b32_dpp v229, v60 row_shr:2 row_mask:0xf bank_mask:0xf
	v_mov_b32_dpp v230, v61 row_shr:1 row_mask:0xf bank_mask:0xf
	v_mov_b32_dpp v231, v61 row_shr:2 row_mask:0xf bank_mask:0xf
	v_mov_b32_dpp v232, v62 row_shr:1 row_mask:0xf bank_mask:0xf
	v_mov_b32_dpp v233, v62 row_shr:2 row_mask:0xf bank_mask:0xf
	v_mov_b32_dpp v234, v63 row_shr:1 row_mask:0xf bank_mask:0xf
	v_mov_b32_dpp v235, v63 row_shr:2 row_mask:0xf bank_mask:0xf
	v_cndmask_b32_e64 v228, 0, v228, vcc
	v_cndmask_b32_e64 v229, 0, v229, s[8:9]
	v_cndmask_b32_e64 v230, 0, v230, vcc
	v_cndmask_b32_e64 v231, 0, v231, s[8:9]
	v_cndmask_b32_e64 v232, 0, v232, vcc
	v_cndmask_b32_e64 v233, 0, v233, s[8:9]
	v_cndmask_b32_e64 v234, 0, v234, vcc
	v_cndmask_b32_e64 v235, 0, v235, s[8:9]
	v_fma_f32 v236, v229, v128, v208
	v_fma_f32 v237, v231, v129, v209
	v_fma_f32 v238, v233, v130, v210
	v_fma_f32 v239, v235, v131, v211
	v_fmac_f32_e32 v236, v228, v144
	v_fmac_f32_e32 v237, v230, v145
	v_fmac_f32_e32 v238, v232, v146
	v_fmac_f32_e32 v239, v234, v147
	v_fmac_f32_e32 v236, v60, v160
	v_fmac_f32_e32 v237, v61, v161
	v_fmac_f32_e32 v238, v62, v162
	v_fmac_f32_e32 v239, v63, v163
	v_mov_b32_dpp v228, v68 row_ror:1 row_mask:0xf bank_mask:0xf
	v_mov_b32_dpp v229, v68 row_ror:2 row_mask:0xf bank_mask:0xf
	v_mov_b32_dpp v230, v69 row_ror:1 row_mask:0xf bank_mask:0xf
	v_mov_b32_dpp v231, v69 row_ror:2 row_mask:0xf bank_mask:0xf
	v_mov_b32_dpp v232, v70 row_ror:1 row_mask:0xf bank_mask:0xf
	v_mov_b32_dpp v233, v70 row_ror:2 row_mask:0xf bank_mask:0xf
	v_mov_b32_dpp v234, v71 row_ror:1 row_mask:0xf bank_mask:0xf
	v_mov_b32_dpp v235, v71 row_ror:2 row_mask:0xf bank_mask:0xf
	v_mov_b32_dpp v228, v52 row_shr:1 row_mask:0xf bank_mask:0xf
	v_mov_b32_dpp v229, v52 row_shr:2 row_mask:0xf bank_mask:0xf
	v_mov_b32_dpp v230, v53 row_shr:1 row_mask:0xf bank_mask:0xf
	v_mov_b32_dpp v231, v53 row_shr:2 row_mask:0xf bank_mask:0xf
	v_mov_b32_dpp v232, v54 row_shr:1 row_mask:0xf bank_mask:0xf
	v_mov_b32_dpp v233, v54 row_shr:2 row_mask:0xf bank_mask:0xf
	v_mov_b32_dpp v234, v55 row_shr:1 row_mask:0xf bank_mask:0xf
	v_mov_b32_dpp v235, v55 row_shr:2 row_mask:0xf bank_mask:0xf
	v_cndmask_b32_e64 v228, 0, v228, vcc
	v_cndmask_b32_e64 v229, 0, v229, s[8:9]
	v_cndmask_b32_e64 v230, 0, v230, vcc
	v_cndmask_b32_e64 v231, 0, v231, s[8:9]
	v_cndmask_b32_e64 v232, 0, v232, vcc
	v_cndmask_b32_e64 v233, 0, v233, s[8:9]
	v_cndmask_b32_e64 v234, 0, v234, vcc
	v_cndmask_b32_e64 v235, 0, v235, s[8:9]
	v_fma_f32 v240, v229, v132, v212
	v_fma_f32 v241, v231, v133, v213
	v_fma_f32 v242, v233, v134, v214
	v_fma_f32 v243, v235, v135, v215
	v_fmac_f32_e32 v240, v228, v148
	v_fmac_f32_e32 v241, v230, v149
	v_fmac_f32_e32 v242, v232, v150
	v_fmac_f32_e32 v243, v234, v151
	v_fmac_f32_e32 v240, v52, v164
	v_fmac_f32_e32 v241, v53, v165
	v_fmac_f32_e32 v242, v54, v166
	v_fmac_f32_e32 v243, v55, v167
	v_mul_f32_e32 v244, 0x3d372713, v236
	v_mul_f32_e32 v245, 0x3d372713, v237
	v_mul_f32_e32 v246, 0x3d372713, v238
	v_mul_f32_e32 v247, 0x3d372713, v239
	v_mul_f32_e32 v244, v236, v244
	v_mul_f32_e32 v245, v237, v245
	v_mul_f32_e32 v246, v238, v246
	v_mul_f32_e32 v247, v239, v247
	v_fma_f32 v244, v236, v244, v236
	v_fma_f32 v245, v237, v245, v237
	v_fma_f32 v246, v238, v246, v238
	v_fma_f32 v247, v239, v247, v239
	v_mul_f32_e32 v244, 0x3f4c422a, v244
	v_mul_f32_e32 v245, 0x3f4c422a, v245
	v_mul_f32_e32 v246, 0x3f4c422a, v246
	v_mul_f32_e32 v247, 0x3f4c422a, v247
	v_mul_f32_e32 v244, 0xc038aa3b, v244
	v_mul_f32_e32 v245, 0xc038aa3b, v245
	v_mul_f32_e32 v246, 0xc038aa3b, v246
	v_mul_f32_e32 v247, 0xc038aa3b, v247
	v_exp_f32_e32 v244, v244
	v_exp_f32_e32 v245, v245
	v_exp_f32_e32 v246, v246
	v_exp_f32_e32 v247, v247
	v_add_f32_e32 v244, 1.0, v244
	v_add_f32_e32 v245, 1.0, v245
	v_add_f32_e32 v246, 1.0, v246
	v_add_f32_e32 v247, 1.0, v247
	v_rcp_f32_e32 v244, v244
	v_rcp_f32_e32 v245, v245
	v_rcp_f32_e32 v246, v246
	v_rcp_f32_e32 v247, v247
	v_mul_f32_e32 v244, v236, v244
	v_mul_f32_e32 v245, v237, v245
	v_mul_f32_e32 v246, v238, v246
	v_mul_f32_e32 v247, v239, v247
	v_mul_f32_e32 v248, v240, v244
	v_mul_f32_e32 v249, v241, v245
	v_mul_f32_e32 v250, v242, v246
	v_mul_f32_e32 v251, v243, v247
	v_mov_b32_dpp v228, v72 row_ror:1 row_mask:0xf bank_mask:0xf
	v_mov_b32_dpp v229, v72 row_ror:2 row_mask:0xf bank_mask:0xf
	v_mov_b32_dpp v230, v73 row_ror:1 row_mask:0xf bank_mask:0xf
	v_mov_b32_dpp v231, v73 row_ror:2 row_mask:0xf bank_mask:0xf
	v_mov_b32_dpp v232, v74 row_ror:1 row_mask:0xf bank_mask:0xf
	v_mov_b32_dpp v233, v74 row_ror:2 row_mask:0xf bank_mask:0xf
	v_mov_b32_dpp v234, v75 row_ror:1 row_mask:0xf bank_mask:0xf
	v_mov_b32_dpp v235, v75 row_ror:2 row_mask:0xf bank_mask:0xf
	v_mov_b32_dpp v228, v56 row_shr:1 row_mask:0xf bank_mask:0xf
	v_mov_b32_dpp v229, v56 row_shr:2 row_mask:0xf bank_mask:0xf
	v_mov_b32_dpp v230, v57 row_shr:1 row_mask:0xf bank_mask:0xf
	v_mov_b32_dpp v231, v57 row_shr:2 row_mask:0xf bank_mask:0xf
	v_mov_b32_dpp v232, v58 row_shr:1 row_mask:0xf bank_mask:0xf
	v_mov_b32_dpp v233, v58 row_shr:2 row_mask:0xf bank_mask:0xf
	v_mov_b32_dpp v234, v59 row_shr:1 row_mask:0xf bank_mask:0xf
	v_mov_b32_dpp v235, v59 row_shr:2 row_mask:0xf bank_mask:0xf
	v_cndmask_b32_e64 v228, 0, v228, vcc
	v_cndmask_b32_e64 v229, 0, v229, s[8:9]
	v_cndmask_b32_e64 v230, 0, v230, vcc
	v_cndmask_b32_e64 v231, 0, v231, s[8:9]
	v_cndmask_b32_e64 v232, 0, v232, vcc
	v_cndmask_b32_e64 v233, 0, v233, s[8:9]
	v_cndmask_b32_e64 v234, 0, v234, vcc
	v_cndmask_b32_e64 v235, 0, v235, s[8:9]
	v_fma_f32 v236, v229, v136, v220
	v_fma_f32 v237, v231, v137, v221
	v_fma_f32 v238, v233, v138, v222
	v_fma_f32 v239, v235, v139, v223
	v_fmac_f32_e32 v236, v228, v152
	v_fmac_f32_e32 v237, v230, v153
	v_fmac_f32_e32 v238, v232, v154
	v_fmac_f32_e32 v239, v234, v155
	v_fmac_f32_e32 v236, v56, v168
	v_fmac_f32_e32 v237, v57, v169
	v_fmac_f32_e32 v238, v58, v170
	v_fmac_f32_e32 v239, v59, v171
	v_mov_b32_dpp v228, v64 row_ror:1 row_mask:0xf bank_mask:0xf
	v_mov_b32_dpp v229, v64 row_ror:2 row_mask:0xf bank_mask:0xf
	v_mov_b32_dpp v230, v65 row_ror:1 row_mask:0xf bank_mask:0xf
	v_mov_b32_dpp v231, v65 row_ror:2 row_mask:0xf bank_mask:0xf
	v_mov_b32_dpp v232, v66 row_ror:1 row_mask:0xf bank_mask:0xf
	v_mov_b32_dpp v233, v66 row_ror:2 row_mask:0xf bank_mask:0xf
	v_mov_b32_dpp v234, v67 row_ror:1 row_mask:0xf bank_mask:0xf
	v_mov_b32_dpp v235, v67 row_ror:2 row_mask:0xf bank_mask:0xf
	v_mov_b32_dpp v228, v48 row_shr:1 row_mask:0xf bank_mask:0xf
	v_mov_b32_dpp v229, v48 row_shr:2 row_mask:0xf bank_mask:0xf
	v_mov_b32_dpp v230, v49 row_shr:1 row_mask:0xf bank_mask:0xf
	v_mov_b32_dpp v231, v49 row_shr:2 row_mask:0xf bank_mask:0xf
	v_mov_b32_dpp v232, v50 row_shr:1 row_mask:0xf bank_mask:0xf
	v_mov_b32_dpp v233, v50 row_shr:2 row_mask:0xf bank_mask:0xf
	v_mov_b32_dpp v234, v51 row_shr:1 row_mask:0xf bank_mask:0xf
	v_mov_b32_dpp v235, v51 row_shr:2 row_mask:0xf bank_mask:0xf
	v_cndmask_b32_e64 v228, 0, v228, vcc
	v_cndmask_b32_e64 v229, 0, v229, s[8:9]
	v_cndmask_b32_e64 v230, 0, v230, vcc
	v_cndmask_b32_e64 v231, 0, v231, s[8:9]
	v_cndmask_b32_e64 v232, 0, v232, vcc
	v_cndmask_b32_e64 v233, 0, v233, s[8:9]
	v_cndmask_b32_e64 v234, 0, v234, vcc
	v_cndmask_b32_e64 v235, 0, v235, s[8:9]
	v_fma_f32 v240, v229, v140, v224
	v_fma_f32 v241, v231, v141, v225
	v_fma_f32 v242, v233, v142, v226
	v_fma_f32 v243, v235, v143, v227
	v_fmac_f32_e32 v240, v228, v156
	v_fmac_f32_e32 v241, v230, v157
	v_fmac_f32_e32 v242, v232, v158
	v_fmac_f32_e32 v243, v234, v159
	v_fmac_f32_e32 v240, v48, v204
	v_fmac_f32_e32 v241, v49, v205
	v_fmac_f32_e32 v242, v50, v206
	v_fmac_f32_e32 v243, v51, v207
	v_mul_f32_e32 v244, 0x3d372713, v236
	v_mul_f32_e32 v245, 0x3d372713, v237
	v_mul_f32_e32 v246, 0x3d372713, v238
	v_mul_f32_e32 v247, 0x3d372713, v239
	v_mul_f32_e32 v244, v236, v244
	v_mul_f32_e32 v245, v237, v245
	v_mul_f32_e32 v246, v238, v246
	v_mul_f32_e32 v247, v239, v247
	v_fma_f32 v244, v236, v244, v236
	v_fma_f32 v245, v237, v245, v237
	v_fma_f32 v246, v238, v246, v238
	v_fma_f32 v247, v239, v247, v239
	v_mul_f32_e32 v244, 0x3f4c422a, v244
	v_mul_f32_e32 v245, 0x3f4c422a, v245
	v_mul_f32_e32 v246, 0x3f4c422a, v246
	v_mul_f32_e32 v247, 0x3f4c422a, v247
	v_mul_f32_e32 v244, 0xc038aa3b, v244
	v_mul_f32_e32 v245, 0xc038aa3b, v245
	v_mul_f32_e32 v246, 0xc038aa3b, v246
	v_mul_f32_e32 v247, 0xc038aa3b, v247
	v_exp_f32_e32 v244, v244
	v_exp_f32_e32 v245, v245
	v_exp_f32_e32 v246, v246
	v_exp_f32_e32 v247, v247
	v_add_f32_e32 v244, 1.0, v244
	v_add_f32_e32 v245, 1.0, v245
	v_add_f32_e32 v246, 1.0, v246
	v_add_f32_e32 v247, 1.0, v247
	v_rcp_f32_e32 v244, v244
	v_rcp_f32_e32 v245, v245
	v_rcp_f32_e32 v246, v246
	v_rcp_f32_e32 v247, v247
	v_mul_f32_e32 v244, v236, v244
	v_mul_f32_e32 v245, v237, v245
	v_mul_f32_e32 v246, v238, v246
	v_mul_f32_e32 v247, v239, v247
	v_mul_f32_e32 v174, v240, v244
	v_mul_f32_e32 v175, v241, v245
	v_mul_f32_e32 v176, v242, v246
	v_mul_f32_e32 v177, v243, v247
	v_cvt_pk_bf16_f32 v180, v248, v249
	v_cvt_pk_bf16_f32 v181, v250, v251
	v_cvt_pk_bf16_f32 v182, v174, v175
	v_cvt_pk_bf16_f32 v183, v176, v177
	s_branch .Lffn1e_store4
.Lffn1e_slow5:
	v_add_u32_e32 v189, 2144, v218
	v_mul_hi_u32 v203, v189, s59
	v_lshrrev_b32_e32 v203, 7, v203
	v_mul_u32_u24_e32 v203, 0x810, v203
	v_sub_u32_e32 v189, v189, v203
	v_cmp_lt_u32_e32 vcc, 0, v189
	v_cmp_lt_u32_e64 s[8:9], 1, v189
	s_nop 1
	v_mov_b32_dpp v228, v60 row_ror:1 row_mask:0xf bank_mask:0xf
	v_mov_b32_dpp v229, v60 row_ror:2 row_mask:0xf bank_mask:0xf
	v_mov_b32_dpp v230, v61 row_ror:1 row_mask:0xf bank_mask:0xf
	v_mov_b32_dpp v231, v61 row_ror:2 row_mask:0xf bank_mask:0xf
	v_mov_b32_dpp v232, v62 row_ror:1 row_mask:0xf bank_mask:0xf
	v_mov_b32_dpp v233, v62 row_ror:2 row_mask:0xf bank_mask:0xf
	v_mov_b32_dpp v234, v63 row_ror:1 row_mask:0xf bank_mask:0xf
	v_mov_b32_dpp v235, v63 row_ror:2 row_mask:0xf bank_mask:0xf
	v_mov_b32_dpp v228, v44 row_shr:1 row_mask:0xf bank_mask:0xf
	v_mov_b32_dpp v229, v44 row_shr:2 row_mask:0xf bank_mask:0xf
	v_mov_b32_dpp v230, v45 row_shr:1 row_mask:0xf bank_mask:0xf
	v_mov_b32_dpp v231, v45 row_shr:2 row_mask:0xf bank_mask:0xf
	v_mov_b32_dpp v232, v46 row_shr:1 row_mask:0xf bank_mask:0xf
	v_mov_b32_dpp v233, v46 row_shr:2 row_mask:0xf bank_mask:0xf
	v_mov_b32_dpp v234, v47 row_shr:1 row_mask:0xf bank_mask:0xf
	v_mov_b32_dpp v235, v47 row_shr:2 row_mask:0xf bank_mask:0xf
	v_cndmask_b32_e64 v228, 0, v228, vcc
	v_cndmask_b32_e64 v229, 0, v229, s[8:9]
	v_cndmask_b32_e64 v230, 0, v230, vcc
	v_cndmask_b32_e64 v231, 0, v231, s[8:9]
	v_cndmask_b32_e64 v232, 0, v232, vcc
	v_cndmask_b32_e64 v233, 0, v233, s[8:9]
	v_cndmask_b32_e64 v234, 0, v234, vcc
	v_cndmask_b32_e64 v235, 0, v235, s[8:9]
	v_fma_f32 v236, v229, v128, v208
	v_fma_f32 v237, v231, v129, v209
	v_fma_f32 v238, v233, v130, v210
	v_fma_f32 v239, v235, v131, v211
	v_fmac_f32_e32 v236, v228, v144
	v_fmac_f32_e32 v237, v230, v145
	v_fmac_f32_e32 v238, v232, v146
	v_fmac_f32_e32 v239, v234, v147
	v_fmac_f32_e32 v236, v44, v160
	v_fmac_f32_e32 v237, v45, v161
	v_fmac_f32_e32 v238, v46, v162
	v_fmac_f32_e32 v239, v47, v163
	v_mov_b32_dpp v228, v52 row_ror:1 row_mask:0xf bank_mask:0xf
	v_mov_b32_dpp v229, v52 row_ror:2 row_mask:0xf bank_mask:0xf
	v_mov_b32_dpp v230, v53 row_ror:1 row_mask:0xf bank_mask:0xf
	v_mov_b32_dpp v231, v53 row_ror:2 row_mask:0xf bank_mask:0xf
	v_mov_b32_dpp v232, v54 row_ror:1 row_mask:0xf bank_mask:0xf
	v_mov_b32_dpp v233, v54 row_ror:2 row_mask:0xf bank_mask:0xf
	v_mov_b32_dpp v234, v55 row_ror:1 row_mask:0xf bank_mask:0xf
	v_mov_b32_dpp v235, v55 row_ror:2 row_mask:0xf bank_mask:0xf
	v_mov_b32_dpp v228, v36 row_shr:1 row_mask:0xf bank_mask:0xf
	v_mov_b32_dpp v229, v36 row_shr:2 row_mask:0xf bank_mask:0xf
	v_mov_b32_dpp v230, v37 row_shr:1 row_mask:0xf bank_mask:0xf
	v_mov_b32_dpp v231, v37 row_shr:2 row_mask:0xf bank_mask:0xf
	v_mov_b32_dpp v232, v38 row_shr:1 row_mask:0xf bank_mask:0xf
	v_mov_b32_dpp v233, v38 row_shr:2 row_mask:0xf bank_mask:0xf
	v_mov_b32_dpp v234, v39 row_shr:1 row_mask:0xf bank_mask:0xf
	v_mov_b32_dpp v235, v39 row_shr:2 row_mask:0xf bank_mask:0xf
	v_cndmask_b32_e64 v228, 0, v228, vcc
	v_cndmask_b32_e64 v229, 0, v229, s[8:9]
	v_cndmask_b32_e64 v230, 0, v230, vcc
	v_cndmask_b32_e64 v231, 0, v231, s[8:9]
	v_cndmask_b32_e64 v232, 0, v232, vcc
	v_cndmask_b32_e64 v233, 0, v233, s[8:9]
	v_cndmask_b32_e64 v234, 0, v234, vcc
	v_cndmask_b32_e64 v235, 0, v235, s[8:9]
	v_fma_f32 v240, v229, v132, v212
	v_fma_f32 v241, v231, v133, v213
	v_fma_f32 v242, v233, v134, v214
	v_fma_f32 v243, v235, v135, v215
	v_fmac_f32_e32 v240, v228, v148
	v_fmac_f32_e32 v241, v230, v149
	v_fmac_f32_e32 v242, v232, v150
	v_fmac_f32_e32 v243, v234, v151
	v_fmac_f32_e32 v240, v36, v164
	v_fmac_f32_e32 v241, v37, v165
	v_fmac_f32_e32 v242, v38, v166
	v_fmac_f32_e32 v243, v39, v167
	v_mul_f32_e32 v244, 0x3d372713, v236
	v_mul_f32_e32 v245, 0x3d372713, v237
	v_mul_f32_e32 v246, 0x3d372713, v238
	v_mul_f32_e32 v247, 0x3d372713, v239
	v_mul_f32_e32 v244, v236, v244
	v_mul_f32_e32 v245, v237, v245
	v_mul_f32_e32 v246, v238, v246
	v_mul_f32_e32 v247, v239, v247
	v_fma_f32 v244, v236, v244, v236
	v_fma_f32 v245, v237, v245, v237
	v_fma_f32 v246, v238, v246, v238
	v_fma_f32 v247, v239, v247, v239
	v_mul_f32_e32 v244, 0x3f4c422a, v244
	v_mul_f32_e32 v245, 0x3f4c422a, v245
	v_mul_f32_e32 v246, 0x3f4c422a, v246
	v_mul_f32_e32 v247, 0x3f4c422a, v247
	v_mul_f32_e32 v244, 0xc038aa3b, v244
	v_mul_f32_e32 v245, 0xc038aa3b, v245
	v_mul_f32_e32 v246, 0xc038aa3b, v246
	v_mul_f32_e32 v247, 0xc038aa3b, v247
	v_exp_f32_e32 v244, v244
	v_exp_f32_e32 v245, v245
	v_exp_f32_e32 v246, v246
	v_exp_f32_e32 v247, v247
	v_add_f32_e32 v244, 1.0, v244
	v_add_f32_e32 v245, 1.0, v245
	v_add_f32_e32 v246, 1.0, v246
	v_add_f32_e32 v247, 1.0, v247
	v_rcp_f32_e32 v244, v244
	v_rcp_f32_e32 v245, v245
	v_rcp_f32_e32 v246, v246
	v_rcp_f32_e32 v247, v247
	v_mul_f32_e32 v244, v236, v244
	v_mul_f32_e32 v245, v237, v245
	v_mul_f32_e32 v246, v238, v246
	v_mul_f32_e32 v247, v239, v247
	v_mul_f32_e32 v248, v240, v244
	v_mul_f32_e32 v249, v241, v245
	v_mul_f32_e32 v250, v242, v246
	v_mul_f32_e32 v251, v243, v247
	v_mov_b32_dpp v228, v56 row_ror:1 row_mask:0xf bank_mask:0xf
	v_mov_b32_dpp v229, v56 row_ror:2 row_mask:0xf bank_mask:0xf
	v_mov_b32_dpp v230, v57 row_ror:1 row_mask:0xf bank_mask:0xf
	v_mov_b32_dpp v231, v57 row_ror:2 row_mask:0xf bank_mask:0xf
	v_mov_b32_dpp v232, v58 row_ror:1 row_mask:0xf bank_mask:0xf
	v_mov_b32_dpp v233, v58 row_ror:2 row_mask:0xf bank_mask:0xf
	v_mov_b32_dpp v234, v59 row_ror:1 row_mask:0xf bank_mask:0xf
	v_mov_b32_dpp v235, v59 row_ror:2 row_mask:0xf bank_mask:0xf
	v_mov_b32_dpp v228, v40 row_shr:1 row_mask:0xf bank_mask:0xf
	v_mov_b32_dpp v229, v40 row_shr:2 row_mask:0xf bank_mask:0xf
	v_mov_b32_dpp v230, v41 row_shr:1 row_mask:0xf bank_mask:0xf
	v_mov_b32_dpp v231, v41 row_shr:2 row_mask:0xf bank_mask:0xf
	v_mov_b32_dpp v232, v42 row_shr:1 row_mask:0xf bank_mask:0xf
	v_mov_b32_dpp v233, v42 row_shr:2 row_mask:0xf bank_mask:0xf
	v_mov_b32_dpp v234, v43 row_shr:1 row_mask:0xf bank_mask:0xf
	v_mov_b32_dpp v235, v43 row_shr:2 row_mask:0xf bank_mask:0xf
	v_cndmask_b32_e64 v228, 0, v228, vcc
	v_cndmask_b32_e64 v229, 0, v229, s[8:9]
	v_cndmask_b32_e64 v230, 0, v230, vcc
	v_cndmask_b32_e64 v231, 0, v231, s[8:9]
	v_cndmask_b32_e64 v232, 0, v232, vcc
	v_cndmask_b32_e64 v233, 0, v233, s[8:9]
	v_cndmask_b32_e64 v234, 0, v234, vcc
	v_cndmask_b32_e64 v235, 0, v235, s[8:9]
	v_fma_f32 v236, v229, v136, v220
	v_fma_f32 v237, v231, v137, v221
	v_fma_f32 v238, v233, v138, v222
	v_fma_f32 v239, v235, v139, v223
	v_fmac_f32_e32 v236, v228, v152
	v_fmac_f32_e32 v237, v230, v153
	v_fmac_f32_e32 v238, v232, v154
	v_fmac_f32_e32 v239, v234, v155
	v_fmac_f32_e32 v236, v40, v168
	v_fmac_f32_e32 v237, v41, v169
	v_fmac_f32_e32 v238, v42, v170
	v_fmac_f32_e32 v239, v43, v171
	v_mov_b32_dpp v228, v48 row_ror:1 row_mask:0xf bank_mask:0xf
	v_mov_b32_dpp v229, v48 row_ror:2 row_mask:0xf bank_mask:0xf
	v_mov_b32_dpp v230, v49 row_ror:1 row_mask:0xf bank_mask:0xf
	v_mov_b32_dpp v231, v49 row_ror:2 row_mask:0xf bank_mask:0xf
	v_mov_b32_dpp v232, v50 row_ror:1 row_mask:0xf bank_mask:0xf
	v_mov_b32_dpp v233, v50 row_ror:2 row_mask:0xf bank_mask:0xf
	v_mov_b32_dpp v234, v51 row_ror:1 row_mask:0xf bank_mask:0xf
	v_mov_b32_dpp v235, v51 row_ror:2 row_mask:0xf bank_mask:0xf
	v_mov_b32_dpp v228, v32 row_shr:1 row_mask:0xf bank_mask:0xf
	v_mov_b32_dpp v229, v32 row_shr:2 row_mask:0xf bank_mask:0xf
	v_mov_b32_dpp v230, v33 row_shr:1 row_mask:0xf bank_mask:0xf
	v_mov_b32_dpp v231, v33 row_shr:2 row_mask:0xf bank_mask:0xf
	v_mov_b32_dpp v232, v34 row_shr:1 row_mask:0xf bank_mask:0xf
	v_mov_b32_dpp v233, v34 row_shr:2 row_mask:0xf bank_mask:0xf
	v_mov_b32_dpp v234, v35 row_shr:1 row_mask:0xf bank_mask:0xf
	v_mov_b32_dpp v235, v35 row_shr:2 row_mask:0xf bank_mask:0xf
	v_cndmask_b32_e64 v228, 0, v228, vcc
	v_cndmask_b32_e64 v229, 0, v229, s[8:9]
	v_cndmask_b32_e64 v230, 0, v230, vcc
	v_cndmask_b32_e64 v231, 0, v231, s[8:9]
	v_cndmask_b32_e64 v232, 0, v232, vcc
	v_cndmask_b32_e64 v233, 0, v233, s[8:9]
	v_cndmask_b32_e64 v234, 0, v234, vcc
	v_cndmask_b32_e64 v235, 0, v235, s[8:9]
	v_fma_f32 v240, v229, v140, v224
	v_fma_f32 v241, v231, v141, v225
	v_fma_f32 v242, v233, v142, v226
	v_fma_f32 v243, v235, v143, v227
	v_fmac_f32_e32 v240, v228, v156
	v_fmac_f32_e32 v241, v230, v157
	v_fmac_f32_e32 v242, v232, v158
	v_fmac_f32_e32 v243, v234, v159
	v_fmac_f32_e32 v240, v32, v204
	v_fmac_f32_e32 v241, v33, v205
	v_fmac_f32_e32 v242, v34, v206
	v_fmac_f32_e32 v243, v35, v207
	v_mul_f32_e32 v244, 0x3d372713, v236
	v_mul_f32_e32 v245, 0x3d372713, v237
	v_mul_f32_e32 v246, 0x3d372713, v238
	v_mul_f32_e32 v247, 0x3d372713, v239
	v_mul_f32_e32 v244, v236, v244
	v_mul_f32_e32 v245, v237, v245
	v_mul_f32_e32 v246, v238, v246
	v_mul_f32_e32 v247, v239, v247
	v_fma_f32 v244, v236, v244, v236
	v_fma_f32 v245, v237, v245, v237
	v_fma_f32 v246, v238, v246, v238
	v_fma_f32 v247, v239, v247, v239
	v_mul_f32_e32 v244, 0x3f4c422a, v244
	v_mul_f32_e32 v245, 0x3f4c422a, v245
	v_mul_f32_e32 v246, 0x3f4c422a, v246
	v_mul_f32_e32 v247, 0x3f4c422a, v247
	v_mul_f32_e32 v244, 0xc038aa3b, v244
	v_mul_f32_e32 v245, 0xc038aa3b, v245
	v_mul_f32_e32 v246, 0xc038aa3b, v246
	v_mul_f32_e32 v247, 0xc038aa3b, v247
	v_exp_f32_e32 v244, v244
	v_exp_f32_e32 v245, v245
	v_exp_f32_e32 v246, v246
	v_exp_f32_e32 v247, v247
	v_add_f32_e32 v244, 1.0, v244
	v_add_f32_e32 v245, 1.0, v245
	v_add_f32_e32 v246, 1.0, v246
	v_add_f32_e32 v247, 1.0, v247
	v_rcp_f32_e32 v244, v244
	v_rcp_f32_e32 v245, v245
	v_rcp_f32_e32 v246, v246
	v_rcp_f32_e32 v247, v247
	v_mul_f32_e32 v244, v236, v244
	v_mul_f32_e32 v245, v237, v245
	v_mul_f32_e32 v246, v238, v246
	v_mul_f32_e32 v247, v239, v247
	v_mul_f32_e32 v174, v240, v244
	v_mul_f32_e32 v175, v241, v245
	v_mul_f32_e32 v176, v242, v246
	v_mul_f32_e32 v177, v243, v247
	v_cvt_pk_bf16_f32 v180, v248, v249
	v_cvt_pk_bf16_f32 v181, v250, v251
	v_cvt_pk_bf16_f32 v182, v174, v175
	v_cvt_pk_bf16_f32 v183, v176, v177
	s_branch .Lffn1e_store5
.Lffn1e_slow6:
	v_add_u32_e32 v189, 2160, v218
	v_mul_hi_u32 v203, v189, s59
	v_lshrrev_b32_e32 v203, 7, v203
	v_mul_u32_u24_e32 v203, 0x810, v203
	v_sub_u32_e32 v189, v189, v203
	v_cmp_lt_u32_e32 vcc, 0, v189
	v_cmp_lt_u32_e64 s[8:9], 1, v189
	s_nop 1
	v_mov_b32_dpp v228, v44 row_ror:1 row_mask:0xf bank_mask:0xf
	v_mov_b32_dpp v229, v44 row_ror:2 row_mask:0xf bank_mask:0xf
	v_mov_b32_dpp v230, v45 row_ror:1 row_mask:0xf bank_mask:0xf
	v_mov_b32_dpp v231, v45 row_ror:2 row_mask:0xf bank_mask:0xf
	v_mov_b32_dpp v232, v46 row_ror:1 row_mask:0xf bank_mask:0xf
	v_mov_b32_dpp v233, v46 row_ror:2 row_mask:0xf bank_mask:0xf
	v_mov_b32_dpp v234, v47 row_ror:1 row_mask:0xf bank_mask:0xf
	v_mov_b32_dpp v235, v47 row_ror:2 row_mask:0xf bank_mask:0xf
	v_mov_b32_dpp v228, v28 row_shr:1 row_mask:0xf bank_mask:0xf
	v_mov_b32_dpp v229, v28 row_shr:2 row_mask:0xf bank_mask:0xf
	v_mov_b32_dpp v230, v29 row_shr:1 row_mask:0xf bank_mask:0xf
	v_mov_b32_dpp v231, v29 row_shr:2 row_mask:0xf bank_mask:0xf
	v_mov_b32_dpp v232, v30 row_shr:1 row_mask:0xf bank_mask:0xf
	v_mov_b32_dpp v233, v30 row_shr:2 row_mask:0xf bank_mask:0xf
	v_mov_b32_dpp v234, v31 row_shr:1 row_mask:0xf bank_mask:0xf
	v_mov_b32_dpp v235, v31 row_shr:2 row_mask:0xf bank_mask:0xf
	v_cndmask_b32_e64 v228, 0, v228, vcc
	v_cndmask_b32_e64 v229, 0, v229, s[8:9]
	v_cndmask_b32_e64 v230, 0, v230, vcc
	v_cndmask_b32_e64 v231, 0, v231, s[8:9]
	v_cndmask_b32_e64 v232, 0, v232, vcc
	v_cndmask_b32_e64 v233, 0, v233, s[8:9]
	v_cndmask_b32_e64 v234, 0, v234, vcc
	v_cndmask_b32_e64 v235, 0, v235, s[8:9]
	v_fma_f32 v236, v229, v128, v208
	v_fma_f32 v237, v231, v129, v209
	v_fma_f32 v238, v233, v130, v210
	v_fma_f32 v239, v235, v131, v211
	v_fmac_f32_e32 v236, v228, v144
	v_fmac_f32_e32 v237, v230, v145
	v_fmac_f32_e32 v238, v232, v146
	v_fmac_f32_e32 v239, v234, v147
	v_fmac_f32_e32 v236, v28, v160
	v_fmac_f32_e32 v237, v29, v161
	v_fmac_f32_e32 v238, v30, v162
	v_fmac_f32_e32 v239, v31, v163
	v_mov_b32_dpp v228, v36 row_ror:1 row_mask:0xf bank_mask:0xf
	v_mov_b32_dpp v229, v36 row_ror:2 row_mask:0xf bank_mask:0xf
	v_mov_b32_dpp v230, v37 row_ror:1 row_mask:0xf bank_mask:0xf
	v_mov_b32_dpp v231, v37 row_ror:2 row_mask:0xf bank_mask:0xf
	v_mov_b32_dpp v232, v38 row_ror:1 row_mask:0xf bank_mask:0xf
	v_mov_b32_dpp v233, v38 row_ror:2 row_mask:0xf bank_mask:0xf
	v_mov_b32_dpp v234, v39 row_ror:1 row_mask:0xf bank_mask:0xf
	v_mov_b32_dpp v235, v39 row_ror:2 row_mask:0xf bank_mask:0xf
	v_mov_b32_dpp v228, v20 row_shr:1 row_mask:0xf bank_mask:0xf
	v_mov_b32_dpp v229, v20 row_shr:2 row_mask:0xf bank_mask:0xf
	v_mov_b32_dpp v230, v21 row_shr:1 row_mask:0xf bank_mask:0xf
	v_mov_b32_dpp v231, v21 row_shr:2 row_mask:0xf bank_mask:0xf
	v_mov_b32_dpp v232, v22 row_shr:1 row_mask:0xf bank_mask:0xf
	v_mov_b32_dpp v233, v22 row_shr:2 row_mask:0xf bank_mask:0xf
	v_mov_b32_dpp v234, v23 row_shr:1 row_mask:0xf bank_mask:0xf
	v_mov_b32_dpp v235, v23 row_shr:2 row_mask:0xf bank_mask:0xf
	v_cndmask_b32_e64 v228, 0, v228, vcc
	v_cndmask_b32_e64 v229, 0, v229, s[8:9]
	v_cndmask_b32_e64 v230, 0, v230, vcc
	v_cndmask_b32_e64 v231, 0, v231, s[8:9]
	v_cndmask_b32_e64 v232, 0, v232, vcc
	v_cndmask_b32_e64 v233, 0, v233, s[8:9]
	v_cndmask_b32_e64 v234, 0, v234, vcc
	v_cndmask_b32_e64 v235, 0, v235, s[8:9]
	v_fma_f32 v240, v229, v132, v212
	v_fma_f32 v241, v231, v133, v213
	v_fma_f32 v242, v233, v134, v214
	v_fma_f32 v243, v235, v135, v215
	v_fmac_f32_e32 v240, v228, v148
	v_fmac_f32_e32 v241, v230, v149
	v_fmac_f32_e32 v242, v232, v150
	v_fmac_f32_e32 v243, v234, v151
	v_fmac_f32_e32 v240, v20, v164
	v_fmac_f32_e32 v241, v21, v165
	v_fmac_f32_e32 v242, v22, v166
	v_fmac_f32_e32 v243, v23, v167
	v_mul_f32_e32 v244, 0x3d372713, v236
	v_mul_f32_e32 v245, 0x3d372713, v237
	v_mul_f32_e32 v246, 0x3d372713, v238
	v_mul_f32_e32 v247, 0x3d372713, v239
	v_mul_f32_e32 v244, v236, v244
	v_mul_f32_e32 v245, v237, v245
	v_mul_f32_e32 v246, v238, v246
	v_mul_f32_e32 v247, v239, v247
	v_fma_f32 v244, v236, v244, v236
	v_fma_f32 v245, v237, v245, v237
	v_fma_f32 v246, v238, v246, v238
	v_fma_f32 v247, v239, v247, v239
	v_mul_f32_e32 v244, 0x3f4c422a, v244
	v_mul_f32_e32 v245, 0x3f4c422a, v245
	v_mul_f32_e32 v246, 0x3f4c422a, v246
	v_mul_f32_e32 v247, 0x3f4c422a, v247
	v_mul_f32_e32 v244, 0xc038aa3b, v244
	v_mul_f32_e32 v245, 0xc038aa3b, v245
	v_mul_f32_e32 v246, 0xc038aa3b, v246
	v_mul_f32_e32 v247, 0xc038aa3b, v247
	v_exp_f32_e32 v244, v244
	v_exp_f32_e32 v245, v245
	v_exp_f32_e32 v246, v246
	v_exp_f32_e32 v247, v247
	v_add_f32_e32 v244, 1.0, v244
	v_add_f32_e32 v245, 1.0, v245
	v_add_f32_e32 v246, 1.0, v246
	v_add_f32_e32 v247, 1.0, v247
	v_rcp_f32_e32 v244, v244
	v_rcp_f32_e32 v245, v245
	v_rcp_f32_e32 v246, v246
	v_rcp_f32_e32 v247, v247
	v_mul_f32_e32 v244, v236, v244
	v_mul_f32_e32 v245, v237, v245
	v_mul_f32_e32 v246, v238, v246
	v_mul_f32_e32 v247, v239, v247
	v_mul_f32_e32 v248, v240, v244
	v_mul_f32_e32 v249, v241, v245
	v_mul_f32_e32 v250, v242, v246
	v_mul_f32_e32 v251, v243, v247
	v_mov_b32_dpp v228, v40 row_ror:1 row_mask:0xf bank_mask:0xf
	v_mov_b32_dpp v229, v40 row_ror:2 row_mask:0xf bank_mask:0xf
	v_mov_b32_dpp v230, v41 row_ror:1 row_mask:0xf bank_mask:0xf
	v_mov_b32_dpp v231, v41 row_ror:2 row_mask:0xf bank_mask:0xf
	v_mov_b32_dpp v232, v42 row_ror:1 row_mask:0xf bank_mask:0xf
	v_mov_b32_dpp v233, v42 row_ror:2 row_mask:0xf bank_mask:0xf
	v_mov_b32_dpp v234, v43 row_ror:1 row_mask:0xf bank_mask:0xf
	v_mov_b32_dpp v235, v43 row_ror:2 row_mask:0xf bank_mask:0xf
	v_mov_b32_dpp v228, v24 row_shr:1 row_mask:0xf bank_mask:0xf
	v_mov_b32_dpp v229, v24 row_shr:2 row_mask:0xf bank_mask:0xf
	v_mov_b32_dpp v230, v25 row_shr:1 row_mask:0xf bank_mask:0xf
	v_mov_b32_dpp v231, v25 row_shr:2 row_mask:0xf bank_mask:0xf
	v_mov_b32_dpp v232, v26 row_shr:1 row_mask:0xf bank_mask:0xf
	v_mov_b32_dpp v233, v26 row_shr:2 row_mask:0xf bank_mask:0xf
	v_mov_b32_dpp v234, v27 row_shr:1 row_mask:0xf bank_mask:0xf
	v_mov_b32_dpp v235, v27 row_shr:2 row_mask:0xf bank_mask:0xf
	v_cndmask_b32_e64 v228, 0, v228, vcc
	v_cndmask_b32_e64 v229, 0, v229, s[8:9]
	v_cndmask_b32_e64 v230, 0, v230, vcc
	v_cndmask_b32_e64 v231, 0, v231, s[8:9]
	v_cndmask_b32_e64 v232, 0, v232, vcc
	v_cndmask_b32_e64 v233, 0, v233, s[8:9]
	v_cndmask_b32_e64 v234, 0, v234, vcc
	v_cndmask_b32_e64 v235, 0, v235, s[8:9]
	v_fma_f32 v236, v229, v136, v220
	v_fma_f32 v237, v231, v137, v221
	v_fma_f32 v238, v233, v138, v222
	v_fma_f32 v239, v235, v139, v223
	v_fmac_f32_e32 v236, v228, v152
	v_fmac_f32_e32 v237, v230, v153
	v_fmac_f32_e32 v238, v232, v154
	v_fmac_f32_e32 v239, v234, v155
	v_fmac_f32_e32 v236, v24, v168
	v_fmac_f32_e32 v237, v25, v169
	v_fmac_f32_e32 v238, v26, v170
	v_fmac_f32_e32 v239, v27, v171
	v_mov_b32_dpp v228, v32 row_ror:1 row_mask:0xf bank_mask:0xf
	v_mov_b32_dpp v229, v32 row_ror:2 row_mask:0xf bank_mask:0xf
	v_mov_b32_dpp v230, v33 row_ror:1 row_mask:0xf bank_mask:0xf
	v_mov_b32_dpp v231, v33 row_ror:2 row_mask:0xf bank_mask:0xf
	v_mov_b32_dpp v232, v34 row_ror:1 row_mask:0xf bank_mask:0xf
	v_mov_b32_dpp v233, v34 row_ror:2 row_mask:0xf bank_mask:0xf
	v_mov_b32_dpp v234, v35 row_ror:1 row_mask:0xf bank_mask:0xf
	v_mov_b32_dpp v235, v35 row_ror:2 row_mask:0xf bank_mask:0xf
	v_mov_b32_dpp v228, v16 row_shr:1 row_mask:0xf bank_mask:0xf
	v_mov_b32_dpp v229, v16 row_shr:2 row_mask:0xf bank_mask:0xf
	v_mov_b32_dpp v230, v17 row_shr:1 row_mask:0xf bank_mask:0xf
	v_mov_b32_dpp v231, v17 row_shr:2 row_mask:0xf bank_mask:0xf
	v_mov_b32_dpp v232, v18 row_shr:1 row_mask:0xf bank_mask:0xf
	v_mov_b32_dpp v233, v18 row_shr:2 row_mask:0xf bank_mask:0xf
	v_mov_b32_dpp v234, v19 row_shr:1 row_mask:0xf bank_mask:0xf
	v_mov_b32_dpp v235, v19 row_shr:2 row_mask:0xf bank_mask:0xf
	v_cndmask_b32_e64 v228, 0, v228, vcc
	v_cndmask_b32_e64 v229, 0, v229, s[8:9]
	v_cndmask_b32_e64 v230, 0, v230, vcc
	v_cndmask_b32_e64 v231, 0, v231, s[8:9]
	v_cndmask_b32_e64 v232, 0, v232, vcc
	v_cndmask_b32_e64 v233, 0, v233, s[8:9]
	v_cndmask_b32_e64 v234, 0, v234, vcc
	v_cndmask_b32_e64 v235, 0, v235, s[8:9]
	v_fma_f32 v240, v229, v140, v224
	v_fma_f32 v241, v231, v141, v225
	v_fma_f32 v242, v233, v142, v226
	v_fma_f32 v243, v235, v143, v227
	v_fmac_f32_e32 v240, v228, v156
	v_fmac_f32_e32 v241, v230, v157
	v_fmac_f32_e32 v242, v232, v158
	v_fmac_f32_e32 v243, v234, v159
	v_fmac_f32_e32 v240, v16, v204
	v_fmac_f32_e32 v241, v17, v205
	v_fmac_f32_e32 v242, v18, v206
	v_fmac_f32_e32 v243, v19, v207
	v_mul_f32_e32 v244, 0x3d372713, v236
	v_mul_f32_e32 v245, 0x3d372713, v237
	v_mul_f32_e32 v246, 0x3d372713, v238
	v_mul_f32_e32 v247, 0x3d372713, v239
	v_mul_f32_e32 v244, v236, v244
	v_mul_f32_e32 v245, v237, v245
	v_mul_f32_e32 v246, v238, v246
	v_mul_f32_e32 v247, v239, v247
	v_fma_f32 v244, v236, v244, v236
	v_fma_f32 v245, v237, v245, v237
	v_fma_f32 v246, v238, v246, v238
	v_fma_f32 v247, v239, v247, v239
	v_mul_f32_e32 v244, 0x3f4c422a, v244
	v_mul_f32_e32 v245, 0x3f4c422a, v245
	v_mul_f32_e32 v246, 0x3f4c422a, v246
	v_mul_f32_e32 v247, 0x3f4c422a, v247
	v_mul_f32_e32 v244, 0xc038aa3b, v244
	v_mul_f32_e32 v245, 0xc038aa3b, v245
	v_mul_f32_e32 v246, 0xc038aa3b, v246
	v_mul_f32_e32 v247, 0xc038aa3b, v247
	v_exp_f32_e32 v244, v244
	v_exp_f32_e32 v245, v245
	v_exp_f32_e32 v246, v246
	v_exp_f32_e32 v247, v247
	v_add_f32_e32 v244, 1.0, v244
	v_add_f32_e32 v245, 1.0, v245
	v_add_f32_e32 v246, 1.0, v246
	v_add_f32_e32 v247, 1.0, v247
	v_rcp_f32_e32 v244, v244
	v_rcp_f32_e32 v245, v245
	v_rcp_f32_e32 v246, v246
	v_rcp_f32_e32 v247, v247
	v_mul_f32_e32 v244, v236, v244
	v_mul_f32_e32 v245, v237, v245
	v_mul_f32_e32 v246, v238, v246
	v_mul_f32_e32 v247, v239, v247
	v_mul_f32_e32 v174, v240, v244
	v_mul_f32_e32 v175, v241, v245
	v_mul_f32_e32 v176, v242, v246
	v_mul_f32_e32 v177, v243, v247
	v_cvt_pk_bf16_f32 v180, v248, v249
	v_cvt_pk_bf16_f32 v181, v250, v251
	v_cvt_pk_bf16_f32 v182, v174, v175
	v_cvt_pk_bf16_f32 v183, v176, v177
	s_branch .Lffn1e_store6
.Lffn1e_slow7:
	v_add_u32_e32 v189, 2176, v218
	v_mul_hi_u32 v203, v189, s59
	v_lshrrev_b32_e32 v203, 7, v203
	v_mul_u32_u24_e32 v203, 0x810, v203
	v_sub_u32_e32 v189, v189, v203
	v_cmp_lt_u32_e32 vcc, 0, v189
	v_cmp_lt_u32_e64 s[8:9], 1, v189
	s_nop 1
	v_mov_b32_dpp v228, v28 row_ror:1 row_mask:0xf bank_mask:0xf
	v_mov_b32_dpp v229, v28 row_ror:2 row_mask:0xf bank_mask:0xf
	v_mov_b32_dpp v230, v29 row_ror:1 row_mask:0xf bank_mask:0xf
	v_mov_b32_dpp v231, v29 row_ror:2 row_mask:0xf bank_mask:0xf
	v_mov_b32_dpp v232, v30 row_ror:1 row_mask:0xf bank_mask:0xf
	v_mov_b32_dpp v233, v30 row_ror:2 row_mask:0xf bank_mask:0xf
	v_mov_b32_dpp v234, v31 row_ror:1 row_mask:0xf bank_mask:0xf
	v_mov_b32_dpp v235, v31 row_ror:2 row_mask:0xf bank_mask:0xf
	v_mov_b32_dpp v228, v4 row_shr:1 row_mask:0xf bank_mask:0xf
	v_mov_b32_dpp v229, v4 row_shr:2 row_mask:0xf bank_mask:0xf
	v_mov_b32_dpp v230, v5 row_shr:1 row_mask:0xf bank_mask:0xf
	v_mov_b32_dpp v231, v5 row_shr:2 row_mask:0xf bank_mask:0xf
	v_mov_b32_dpp v232, v6 row_shr:1 row_mask:0xf bank_mask:0xf
	v_mov_b32_dpp v233, v6 row_shr:2 row_mask:0xf bank_mask:0xf
	v_mov_b32_dpp v234, v7 row_shr:1 row_mask:0xf bank_mask:0xf
	v_mov_b32_dpp v235, v7 row_shr:2 row_mask:0xf bank_mask:0xf
	v_cndmask_b32_e64 v228, 0, v228, vcc
	v_cndmask_b32_e64 v229, 0, v229, s[8:9]
	v_cndmask_b32_e64 v230, 0, v230, vcc
	v_cndmask_b32_e64 v231, 0, v231, s[8:9]
	v_cndmask_b32_e64 v232, 0, v232, vcc
	v_cndmask_b32_e64 v233, 0, v233, s[8:9]
	v_cndmask_b32_e64 v234, 0, v234, vcc
	v_cndmask_b32_e64 v235, 0, v235, s[8:9]
	v_fma_f32 v236, v229, v128, v208
	v_fma_f32 v237, v231, v129, v209
	v_fma_f32 v238, v233, v130, v210
	v_fma_f32 v239, v235, v131, v211
	v_fmac_f32_e32 v236, v228, v144
	v_fmac_f32_e32 v237, v230, v145
	v_fmac_f32_e32 v238, v232, v146
	v_fmac_f32_e32 v239, v234, v147
	v_fmac_f32_e32 v236, v4, v160
	v_fmac_f32_e32 v237, v5, v161
	v_fmac_f32_e32 v238, v6, v162
	v_fmac_f32_e32 v239, v7, v163
	v_mov_b32_dpp v228, v20 row_ror:1 row_mask:0xf bank_mask:0xf
	v_mov_b32_dpp v229, v20 row_ror:2 row_mask:0xf bank_mask:0xf
	v_mov_b32_dpp v230, v21 row_ror:1 row_mask:0xf bank_mask:0xf
	v_mov_b32_dpp v231, v21 row_ror:2 row_mask:0xf bank_mask:0xf
	v_mov_b32_dpp v232, v22 row_ror:1 row_mask:0xf bank_mask:0xf
	v_mov_b32_dpp v233, v22 row_ror:2 row_mask:0xf bank_mask:0xf
	v_mov_b32_dpp v234, v23 row_ror:1 row_mask:0xf bank_mask:0xf
	v_mov_b32_dpp v235, v23 row_ror:2 row_mask:0xf bank_mask:0xf
	v_mov_b32_dpp v228, v8 row_shr:1 row_mask:0xf bank_mask:0xf
	v_mov_b32_dpp v229, v8 row_shr:2 row_mask:0xf bank_mask:0xf
	v_mov_b32_dpp v230, v9 row_shr:1 row_mask:0xf bank_mask:0xf
	v_mov_b32_dpp v231, v9 row_shr:2 row_mask:0xf bank_mask:0xf
	v_mov_b32_dpp v232, v10 row_shr:1 row_mask:0xf bank_mask:0xf
	v_mov_b32_dpp v233, v10 row_shr:2 row_mask:0xf bank_mask:0xf
	v_mov_b32_dpp v234, v11 row_shr:1 row_mask:0xf bank_mask:0xf
	v_mov_b32_dpp v235, v11 row_shr:2 row_mask:0xf bank_mask:0xf
	v_cndmask_b32_e64 v228, 0, v228, vcc
	v_cndmask_b32_e64 v229, 0, v229, s[8:9]
	v_cndmask_b32_e64 v230, 0, v230, vcc
	v_cndmask_b32_e64 v231, 0, v231, s[8:9]
	v_cndmask_b32_e64 v232, 0, v232, vcc
	v_cndmask_b32_e64 v233, 0, v233, s[8:9]
	v_cndmask_b32_e64 v234, 0, v234, vcc
	v_cndmask_b32_e64 v235, 0, v235, s[8:9]
	v_fma_f32 v240, v229, v132, v212
	v_fma_f32 v241, v231, v133, v213
	v_fma_f32 v242, v233, v134, v214
	v_fma_f32 v243, v235, v135, v215
	v_fmac_f32_e32 v240, v228, v148
	v_fmac_f32_e32 v241, v230, v149
	v_fmac_f32_e32 v242, v232, v150
	v_fmac_f32_e32 v243, v234, v151
	v_fmac_f32_e32 v240, v8, v164
	v_fmac_f32_e32 v241, v9, v165
	v_fmac_f32_e32 v242, v10, v166
	v_fmac_f32_e32 v243, v11, v167
	v_mul_f32_e32 v244, 0x3d372713, v236
	v_mul_f32_e32 v245, 0x3d372713, v237
	v_mul_f32_e32 v246, 0x3d372713, v238
	v_mul_f32_e32 v247, 0x3d372713, v239
	v_mul_f32_e32 v244, v236, v244
	v_mul_f32_e32 v245, v237, v245
	v_mul_f32_e32 v246, v238, v246
	v_mul_f32_e32 v247, v239, v247
	v_fma_f32 v244, v236, v244, v236
	v_fma_f32 v245, v237, v245, v237
	v_fma_f32 v246, v238, v246, v238
	v_fma_f32 v247, v239, v247, v239
	v_mul_f32_e32 v244, 0x3f4c422a, v244
	v_mul_f32_e32 v245, 0x3f4c422a, v245
	v_mul_f32_e32 v246, 0x3f4c422a, v246
	v_mul_f32_e32 v247, 0x3f4c422a, v247
	v_mul_f32_e32 v244, 0xc038aa3b, v244
	v_mul_f32_e32 v245, 0xc038aa3b, v245
	v_mul_f32_e32 v246, 0xc038aa3b, v246
	v_mul_f32_e32 v247, 0xc038aa3b, v247
	v_exp_f32_e32 v244, v244
	v_exp_f32_e32 v245, v245
	v_exp_f32_e32 v246, v246
	v_exp_f32_e32 v247, v247
	v_add_f32_e32 v244, 1.0, v244
	v_add_f32_e32 v245, 1.0, v245
	v_add_f32_e32 v246, 1.0, v246
	v_add_f32_e32 v247, 1.0, v247
	v_rcp_f32_e32 v244, v244
	v_rcp_f32_e32 v245, v245
	v_rcp_f32_e32 v246, v246
	v_rcp_f32_e32 v247, v247
	v_mul_f32_e32 v244, v236, v244
	v_mul_f32_e32 v245, v237, v245
	v_mul_f32_e32 v246, v238, v246
	v_mul_f32_e32 v247, v239, v247
	v_mul_f32_e32 v248, v240, v244
	v_mul_f32_e32 v249, v241, v245
	v_mul_f32_e32 v250, v242, v246
	v_mul_f32_e32 v251, v243, v247
	v_mov_b32_dpp v228, v24 row_ror:1 row_mask:0xf bank_mask:0xf
	v_mov_b32_dpp v229, v24 row_ror:2 row_mask:0xf bank_mask:0xf
	v_mov_b32_dpp v230, v25 row_ror:1 row_mask:0xf bank_mask:0xf
	v_mov_b32_dpp v231, v25 row_ror:2 row_mask:0xf bank_mask:0xf
	v_mov_b32_dpp v232, v26 row_ror:1 row_mask:0xf bank_mask:0xf
	v_mov_b32_dpp v233, v26 row_ror:2 row_mask:0xf bank_mask:0xf
	v_mov_b32_dpp v234, v27 row_ror:1 row_mask:0xf bank_mask:0xf
	v_mov_b32_dpp v235, v27 row_ror:2 row_mask:0xf bank_mask:0xf
	v_mov_b32_dpp v228, v12 row_shr:1 row_mask:0xf bank_mask:0xf
	v_mov_b32_dpp v229, v12 row_shr:2 row_mask:0xf bank_mask:0xf
	v_mov_b32_dpp v230, v13 row_shr:1 row_mask:0xf bank_mask:0xf
	v_mov_b32_dpp v231, v13 row_shr:2 row_mask:0xf bank_mask:0xf
	v_mov_b32_dpp v232, v14 row_shr:1 row_mask:0xf bank_mask:0xf
	v_mov_b32_dpp v233, v14 row_shr:2 row_mask:0xf bank_mask:0xf
	v_mov_b32_dpp v234, v15 row_shr:1 row_mask:0xf bank_mask:0xf
	v_mov_b32_dpp v235, v15 row_shr:2 row_mask:0xf bank_mask:0xf
	v_cndmask_b32_e64 v228, 0, v228, vcc
	v_cndmask_b32_e64 v229, 0, v229, s[8:9]
	v_cndmask_b32_e64 v230, 0, v230, vcc
	v_cndmask_b32_e64 v231, 0, v231, s[8:9]
	v_cndmask_b32_e64 v232, 0, v232, vcc
	v_cndmask_b32_e64 v233, 0, v233, s[8:9]
	v_cndmask_b32_e64 v234, 0, v234, vcc
	v_cndmask_b32_e64 v235, 0, v235, s[8:9]
	v_fma_f32 v236, v229, v136, v220
	v_fma_f32 v237, v231, v137, v221
	v_fma_f32 v238, v233, v138, v222
	v_fma_f32 v239, v235, v139, v223
	v_fmac_f32_e32 v236, v228, v152
	v_fmac_f32_e32 v237, v230, v153
	v_fmac_f32_e32 v238, v232, v154
	v_fmac_f32_e32 v239, v234, v155
	v_fmac_f32_e32 v236, v12, v168
	v_fmac_f32_e32 v237, v13, v169
	v_fmac_f32_e32 v238, v14, v170
	v_fmac_f32_e32 v239, v15, v171
	v_mov_b32_dpp v228, v16 row_ror:1 row_mask:0xf bank_mask:0xf
	v_mov_b32_dpp v229, v16 row_ror:2 row_mask:0xf bank_mask:0xf
	v_mov_b32_dpp v230, v17 row_ror:1 row_mask:0xf bank_mask:0xf
	v_mov_b32_dpp v231, v17 row_ror:2 row_mask:0xf bank_mask:0xf
	v_mov_b32_dpp v232, v18 row_ror:1 row_mask:0xf bank_mask:0xf
	v_mov_b32_dpp v233, v18 row_ror:2 row_mask:0xf bank_mask:0xf
	v_mov_b32_dpp v234, v19 row_ror:1 row_mask:0xf bank_mask:0xf
	v_mov_b32_dpp v235, v19 row_ror:2 row_mask:0xf bank_mask:0xf
	v_mov_b32_dpp v228, v0 row_shr:1 row_mask:0xf bank_mask:0xf
	v_mov_b32_dpp v229, v0 row_shr:2 row_mask:0xf bank_mask:0xf
	v_mov_b32_dpp v230, v1 row_shr:1 row_mask:0xf bank_mask:0xf
	v_mov_b32_dpp v231, v1 row_shr:2 row_mask:0xf bank_mask:0xf
	v_mov_b32_dpp v232, v2 row_shr:1 row_mask:0xf bank_mask:0xf
	v_mov_b32_dpp v233, v2 row_shr:2 row_mask:0xf bank_mask:0xf
	v_mov_b32_dpp v234, v3 row_shr:1 row_mask:0xf bank_mask:0xf
	v_mov_b32_dpp v235, v3 row_shr:2 row_mask:0xf bank_mask:0xf
	v_cndmask_b32_e64 v228, 0, v228, vcc
	v_cndmask_b32_e64 v229, 0, v229, s[8:9]
	v_cndmask_b32_e64 v230, 0, v230, vcc
	v_cndmask_b32_e64 v231, 0, v231, s[8:9]
	v_cndmask_b32_e64 v232, 0, v232, vcc
	v_cndmask_b32_e64 v233, 0, v233, s[8:9]
	v_cndmask_b32_e64 v234, 0, v234, vcc
	v_cndmask_b32_e64 v235, 0, v235, s[8:9]
	v_fma_f32 v240, v229, v140, v224
	v_fma_f32 v241, v231, v141, v225
	v_fma_f32 v242, v233, v142, v226
	v_fma_f32 v243, v235, v143, v227
	v_fmac_f32_e32 v240, v228, v156
	v_fmac_f32_e32 v241, v230, v157
	v_fmac_f32_e32 v242, v232, v158
	v_fmac_f32_e32 v243, v234, v159
	v_fmac_f32_e32 v240, v0, v204
	v_fmac_f32_e32 v241, v1, v205
	v_fmac_f32_e32 v242, v2, v206
	v_fmac_f32_e32 v243, v3, v207
	v_mul_f32_e32 v244, 0x3d372713, v236
	v_mul_f32_e32 v245, 0x3d372713, v237
	v_mul_f32_e32 v246, 0x3d372713, v238
	v_mul_f32_e32 v247, 0x3d372713, v239
	v_mul_f32_e32 v244, v236, v244
	v_mul_f32_e32 v245, v237, v245
	v_mul_f32_e32 v246, v238, v246
	v_mul_f32_e32 v247, v239, v247
	v_fma_f32 v244, v236, v244, v236
	v_fma_f32 v245, v237, v245, v237
	v_fma_f32 v246, v238, v246, v238
	v_fma_f32 v247, v239, v247, v239
	v_mul_f32_e32 v244, 0x3f4c422a, v244
	v_mul_f32_e32 v245, 0x3f4c422a, v245
	v_mul_f32_e32 v246, 0x3f4c422a, v246
	v_mul_f32_e32 v247, 0x3f4c422a, v247
	v_mul_f32_e32 v244, 0xc038aa3b, v244
	v_mul_f32_e32 v245, 0xc038aa3b, v245
	v_mul_f32_e32 v246, 0xc038aa3b, v246
	v_mul_f32_e32 v247, 0xc038aa3b, v247
	v_exp_f32_e32 v244, v244
	v_exp_f32_e32 v245, v245
	v_exp_f32_e32 v246, v246
	v_exp_f32_e32 v247, v247
	v_add_f32_e32 v244, 1.0, v244
	v_add_f32_e32 v245, 1.0, v245
	v_add_f32_e32 v246, 1.0, v246
	v_add_f32_e32 v247, 1.0, v247
	v_rcp_f32_e32 v244, v244
	v_rcp_f32_e32 v245, v245
	v_rcp_f32_e32 v246, v246
	v_rcp_f32_e32 v247, v247
	v_mul_f32_e32 v244, v236, v244
	v_mul_f32_e32 v245, v237, v245
	v_mul_f32_e32 v246, v238, v246
	v_mul_f32_e32 v247, v239, v247
	v_mul_f32_e32 v174, v240, v244
	v_mul_f32_e32 v175, v241, v245
	v_mul_f32_e32 v176, v242, v246
	v_mul_f32_e32 v177, v243, v247
	v_cvt_pk_bf16_f32 v180, v248, v249
	v_cvt_pk_bf16_f32 v181, v250, v251
	v_cvt_pk_bf16_f32 v182, v174, v175
	v_cvt_pk_bf16_f32 v183, v176, v177
	s_branch .Lffn1e_store7
.Lffn1e_done:
.LBB0_1009:
	s_or_b64 exec, exec, s[30:31]
	s_andn2_b64 vcc, exec, s[4:5]
	s_mov_b64 s[4:5], -1
	s_cbranch_vccnz .LBB0_982
	v_mov_b32_e32 v0, v192
	s_andn2_b64 vcc, exec, s[12:13]
	s_cbranch_vccnz .LBB0_981
	s_barrier
	s_branch .LBB0_981

.LBB0_1241:
	s_or_b64 exec, exec, s[30:31]
	v_readlane_b32 s4, v254, 4
	s_add_i32 s87, s61, 4
	v_readlane_b32 s5, v254, 5
	s_cmp_ge_i32 s87, s5
	s_cselect_b32 s100, 1, 0
	s_cmp_eq_u32 s78, 3
	s_cselect_b32 s100, 1, s100
	s_cmp_lg_u32 s100, 0
	s_mov_b32 s20, s78
	s_cbranch_scc0 .LBB0_1242
	s_getpc_b64 s[98:99]

	.amdhsa_kernel _Z4mega6Params
		.amdhsa_group_segment_fixed_size 0
		.amdhsa_private_segment_fixed_size 0
		.amdhsa_kernarg_size 464
		.amdhsa_user_sgpr_count 2
		.amdhsa_user_sgpr_dispatch_ptr 0
		.amdhsa_user_sgpr_queue_ptr 0
		.amdhsa_user_sgpr_kernarg_segment_ptr 1
		.amdhsa_user_sgpr_dispatch_id 0
		.amdhsa_user_sgpr_kernarg_preload_length 0
		.amdhsa_user_sgpr_kernarg_preload_offset 0
		.amdhsa_user_sgpr_private_segment_size 0
		.amdhsa_uses_dynamic_stack 0
		.amdhsa_enable_private_segment 0
		.amdhsa_system_sgpr_workgroup_id_x 1
		.amdhsa_system_sgpr_workgroup_id_y 0
		.amdhsa_system_sgpr_workgroup_id_z 0
		.amdhsa_system_sgpr_workgroup_info 0
		.amdhsa_system_vgpr_workitem_id 2
		.amdhsa_next_free_vgpr 255
		.amdhsa_next_free_sgpr 102
		.amdhsa_accum_offset 256
		.amdhsa_reserve_vcc 1
		.amdhsa_float_round_mode_32 0
		.amdhsa_float_round_mode_16_64 0
		.amdhsa_float_denorm_mode_32 3
		.amdhsa_float_denorm_mode_16_64 3
		.amdhsa_dx10_clamp 1
		.amdhsa_ieee_mode 1
		.amdhsa_fp16_overflow 0
		.amdhsa_tg_split 0
		.amdhsa_exception_fp_ieee_invalid_op 0
		.amdhsa_exception_fp_denorm_src 0
		.amdhsa_exception_fp_ieee_div_zero 0
		.amdhsa_exception_fp_ieee_overflow 0
		.amdhsa_exception_fp_ieee_underflow 0
		.amdhsa_exception_fp_ieee_inexact 0
		.amdhsa_exception_int_div_zero 0
	.end_amdhsa_kernel

amdhsa.kernels:
  - .agpr_count:     0
    .args:
      - .offset:         0
        .size:           208
        .value_kind:     by_value
      - .offset:         208
        .size:           4
        .value_kind:     hidden_block_count_x
      - .offset:         212
        .size:           4
        .value_kind:     hidden_block_count_y
      - .offset:         216
        .size:           4
        .value_kind:     hidden_block_count_z
      - .offset:         220
        .size:           2
        .value_kind:     hidden_group_size_x
      - .offset:         222
        .size:           2
        .value_kind:     hidden_group_size_y
      - .offset:         224
        .size:           2
        .value_kind:     hidden_group_size_z
      - .offset:         226
        .size:           2
        .value_kind:     hidden_remainder_x
      - .offset:         228
        .size:           2
        .value_kind:     hidden_remainder_y
      - .offset:         230
        .size:           2
        .value_kind:     hidden_remainder_z
      - .offset:         248
        .size:           8
        .value_kind:     hidden_global_offset_x
      - .offset:         256
        .size:           8
        .value_kind:     hidden_global_offset_y
      - .offset:         264
        .size:           8
        .value_kind:     hidden_global_offset_z
      - .offset:         272
        .size:           2
        .value_kind:     hidden_grid_dims
      - .offset:         296
        .size:           8
        .value_kind:     hidden_multigrid_sync_arg
      - .offset:         328
        .size:           4
        .value_kind:     hidden_dynamic_lds_size
    .group_segment_fixed_size: 0
    .kernarg_segment_align: 8
    .kernarg_segment_size: 464
    .language:       OpenCL C
    .language_version:
      - 2
      - 0
    .max_flat_workgroup_size: 512
    .name:           _Z4mega6Params
    .private_segment_fixed_size: 0
    .sgpr_count:     108
    .sgpr_spill_count: 126
    .symbol:         _Z4mega6Params.kd
    .uniform_work_group_size: 1
    .uses_dynamic_stack: false
    .vgpr_count:     255
    .vgpr_spill_count: 0
    .wavefront_size: 64
